# side_kv: the two K-chunk jobs of a wave merged into one accumulator set, four 64-row units software pipelined through even/odd register banks
# baseline (speedup 1.0000x reference)
.LBB0_830:
	s_lshl_b32 s0, s3, 2
	s_and_b32 s5, s0, 0x1f00
	s_ashr_i32 s0, s2, 2
	s_lshr_b32 s4, s2, 2
	s_and_b32 s0, s0, 0xffffff80
	s_and_b32 s4, s4, 0x78
	s_ashr_i32 s1, s0, 31
	s_lshl_b32 s6, s4, 12
	v_readlane_b32 s7, v251, 30
	s_add_u32 s8, s7, s6
	v_readlane_b32 s6, v251, 31
	s_addc_u32 s9, s6, 0
	s_lshl_b64 s[6:7], s[0:1], 2
	s_add_u32 s6, s8, s6
	s_addc_u32 s7, s9, s7
	v_lshl_add_u64 v[4:5], s[6:7], 0, v[0:1]
	s_movk_i32 s1, 0x2000
	v_add_co_u32_e32 v6, vcc, s1, v4
	s_movk_i32 s1, 0x4000
	s_nop 0
	v_addc_co_u32_e32 v7, vcc, 0, v5, vcc
	global_load_dword v3, v0, s[6:7]
	global_load_dword v19, v[6:7], off offset:-4096
	global_load_dword v20, v[6:7], off
	v_add_co_u32_e32 v6, vcc, s1, v4
	s_movk_i32 s1, 0x5000
	s_nop 0
	v_addc_co_u32_e32 v7, vcc, 0, v5, vcc
	global_load_dword v21, v[6:7], off offset:-4096
	global_load_dword v22, v[6:7], off
	v_add_co_u32_e32 v6, vcc, s1, v4
	s_mul_hi_i32 s1, s0, 0xe0c0
	s_nop 0
	v_addc_co_u32_e32 v7, vcc, 0, v5, vcc
	global_load_dword v23, v[6:7], off
	v_add_co_u32_e32 v6, vcc, 0x6000, v4
	v_readlane_b32 s6, v254, 30
	s_nop 0
	v_addc_co_u32_e32 v7, vcc, 0, v5, vcc
	global_load_dword v24, v[6:7], off
	v_add_co_u32_e32 v6, vcc, 0x7000, v4
	v_readlane_b32 s7, v254, 31
	s_nop 0
	v_addc_co_u32_e32 v7, vcc, 0, v5, vcc
	global_load_dword v25, v[6:7], off
	v_lshl_or_b32 v6, v2, 2, s5
	s_mul_i32 s5, s0, 0xe0c0
	v_or_b32_e32 v6, s5, v6
	v_mov_b32_e32 v7, s1
	v_mov_b32_e32 v16, 0
	s_mov_b32 s0, 0
	v_lshl_add_u64 v[8:9], s[6:7], 0, v[6:7]
	v_mov_b32_e32 v17, v16
	v_mov_b32_e32 v14, v16
	v_mov_b32_e32 v15, v16
	v_mov_b32_e32 v12, v16
	v_mov_b32_e32 v13, v16
	v_mov_b32_e32 v10, v16
	v_mov_b32_e32 v11, v16
	s_mov_b32 s5, 0x2a000
	s_mov_b32 s14, 0x38000
	s_mov_b32 s15, 0x46000
	s_mov_b32 s16, 0x54000
	s_mov_b32 s17, 0x62000
	s_mov_b32 s18, 0xfff9e000
	s_mov_b32 s22, 0xfffac000
	s_mov_b32 s23, 0xfffba000
	s_mov_b32 s24, 0xfffc8000
	s_mov_b32 s25, 0xfffd6000
	s_mov_b32 s26, 0xfffe4000
	s_mov_b32 s27, 0xffff2000
	s_mov_b64 s[30:31], 0xe0c00
	s_mov_b32 s34, 0x1c000
	s_mov_b32 s35, 0xe000
	s_mov_b32 s16, 0x1000
	s_mov_b32 s17, 0
	v_mov_b32_e32 v34, v4
	v_mov_b32_e32 v35, v5
	global_load_dword v26, v[34:35], off offset:256
	global_load_dword v172, v[34:35], off offset:2048
	global_load_dword v180, v[34:35], off offset:2304
	v_lshl_add_u64 v[34:35], v[34:35], 0, s[16:17]
	global_load_dword v27, v[34:35], off offset:256
	global_load_dword v173, v[34:35], off offset:2048
	global_load_dword v181, v[34:35], off offset:2304
	v_lshl_add_u64 v[34:35], v[34:35], 0, s[16:17]
	global_load_dword v28, v[34:35], off offset:256
	global_load_dword v174, v[34:35], off offset:2048
	global_load_dword v182, v[34:35], off offset:2304
	v_lshl_add_u64 v[34:35], v[34:35], 0, s[16:17]
	global_load_dword v29, v[34:35], off offset:256
	global_load_dword v175, v[34:35], off offset:2048
	global_load_dword v183, v[34:35], off offset:2304
	v_lshl_add_u64 v[34:35], v[34:35], 0, s[16:17]
	global_load_dword v30, v[34:35], off offset:256
	global_load_dword v176, v[34:35], off offset:2048
	global_load_dword v184, v[34:35], off offset:2304
	v_lshl_add_u64 v[34:35], v[34:35], 0, s[16:17]
	global_load_dword v31, v[34:35], off offset:256
	global_load_dword v177, v[34:35], off offset:2048
	global_load_dword v185, v[34:35], off offset:2304
	v_lshl_add_u64 v[34:35], v[34:35], 0, s[16:17]
	global_load_dword v32, v[34:35], off offset:256
	global_load_dword v178, v[34:35], off offset:2048
	global_load_dword v186, v[34:35], off offset:2304
	v_lshl_add_u64 v[34:35], v[34:35], 0, s[16:17]
	global_load_dword v33, v[34:35], off offset:256
	global_load_dword v179, v[34:35], off offset:2048
	global_load_dword v187, v[34:35], off offset:2304
	s_mov_b32 s14, 0xfff8fa00
	s_mov_b32 s15, -1
	v_lshl_add_u64 v[8:9], v[8:9], 0, s[14:15]
	s_mov_b32 s14, 0xe0c0
	s_mov_b32 s15, 0
	s_mov_b32 s16, 0x15200c0
	s_mov_b32 s17, 0
	global_load_dword v40, v[8:9], off
	v_lshl_add_u64 v[8:9], v[8:9], 0, s[14:15]
	global_load_dword v42, v[8:9], off
	v_lshl_add_u64 v[8:9], v[8:9], 0, s[14:15]
	global_load_dword v44, v[8:9], off
	v_lshl_add_u64 v[8:9], v[8:9], 0, s[14:15]
	global_load_dword v46, v[8:9], off
	v_lshl_add_u64 v[8:9], v[8:9], 0, s[14:15]
	global_load_dword v48, v[8:9], off
	v_lshl_add_u64 v[8:9], v[8:9], 0, s[14:15]
	global_load_dword v50, v[8:9], off
	v_lshl_add_u64 v[8:9], v[8:9], 0, s[14:15]
	global_load_dword v52, v[8:9], off
	v_lshl_add_u64 v[8:9], v[8:9], 0, s[14:15]
	global_load_dword v54, v[8:9], off
	v_lshl_add_u64 v[8:9], v[8:9], 0, s[14:15]
	global_load_dword v56, v[8:9], off
	v_lshl_add_u64 v[8:9], v[8:9], 0, s[14:15]
	global_load_dword v58, v[8:9], off
	v_lshl_add_u64 v[8:9], v[8:9], 0, s[14:15]
	global_load_dword v60, v[8:9], off
	v_lshl_add_u64 v[8:9], v[8:9], 0, s[14:15]
	global_load_dword v62, v[8:9], off
	v_lshl_add_u64 v[8:9], v[8:9], 0, s[14:15]
	global_load_dword v64, v[8:9], off
	v_lshl_add_u64 v[8:9], v[8:9], 0, s[14:15]
	global_load_dword v66, v[8:9], off
	v_lshl_add_u64 v[8:9], v[8:9], 0, s[14:15]
	global_load_dword v68, v[8:9], off
	v_lshl_add_u64 v[8:9], v[8:9], 0, s[14:15]
	global_load_dword v70, v[8:9], off
	v_lshl_add_u64 v[8:9], v[8:9], 0, s[14:15]
	global_load_dword v72, v[8:9], off
	v_lshl_add_u64 v[8:9], v[8:9], 0, s[14:15]
	global_load_dword v74, v[8:9], off
	v_lshl_add_u64 v[8:9], v[8:9], 0, s[14:15]
	global_load_dword v76, v[8:9], off
	v_lshl_add_u64 v[8:9], v[8:9], 0, s[14:15]
	global_load_dword v78, v[8:9], off
	v_lshl_add_u64 v[8:9], v[8:9], 0, s[14:15]
	global_load_dword v80, v[8:9], off
	v_lshl_add_u64 v[8:9], v[8:9], 0, s[14:15]
	global_load_dword v82, v[8:9], off
	v_lshl_add_u64 v[8:9], v[8:9], 0, s[14:15]
	global_load_dword v84, v[8:9], off
	v_lshl_add_u64 v[8:9], v[8:9], 0, s[14:15]
	global_load_dword v86, v[8:9], off
	v_lshl_add_u64 v[8:9], v[8:9], 0, s[14:15]
	global_load_dword v88, v[8:9], off
	v_lshl_add_u64 v[8:9], v[8:9], 0, s[14:15]
	global_load_dword v90, v[8:9], off
	v_lshl_add_u64 v[8:9], v[8:9], 0, s[14:15]
	global_load_dword v92, v[8:9], off
	v_lshl_add_u64 v[8:9], v[8:9], 0, s[14:15]
	global_load_dword v94, v[8:9], off
	v_lshl_add_u64 v[8:9], v[8:9], 0, s[14:15]
	global_load_dword v96, v[8:9], off
	v_lshl_add_u64 v[8:9], v[8:9], 0, s[14:15]
	global_load_dword v98, v[8:9], off
	v_lshl_add_u64 v[8:9], v[8:9], 0, s[14:15]
	global_load_dword v100, v[8:9], off
	v_lshl_add_u64 v[8:9], v[8:9], 0, s[14:15]
	global_load_dword v102, v[8:9], off
	v_lshl_add_u64 v[8:9], v[8:9], 0, s[14:15]
	global_load_dword v104, v[8:9], off
	v_lshl_add_u64 v[8:9], v[8:9], 0, s[14:15]
	global_load_dword v106, v[8:9], off
	v_lshl_add_u64 v[8:9], v[8:9], 0, s[14:15]
	global_load_dword v108, v[8:9], off
	v_lshl_add_u64 v[8:9], v[8:9], 0, s[14:15]
	global_load_dword v110, v[8:9], off
	v_lshl_add_u64 v[8:9], v[8:9], 0, s[14:15]
	global_load_dword v112, v[8:9], off
	v_lshl_add_u64 v[8:9], v[8:9], 0, s[14:15]
	global_load_dword v114, v[8:9], off
	v_lshl_add_u64 v[8:9], v[8:9], 0, s[14:15]
	global_load_dword v116, v[8:9], off
	v_lshl_add_u64 v[8:9], v[8:9], 0, s[14:15]
	global_load_dword v118, v[8:9], off
	v_lshl_add_u64 v[8:9], v[8:9], 0, s[14:15]
	global_load_dword v120, v[8:9], off
	v_lshl_add_u64 v[8:9], v[8:9], 0, s[14:15]
	global_load_dword v122, v[8:9], off
	v_lshl_add_u64 v[8:9], v[8:9], 0, s[14:15]
	global_load_dword v124, v[8:9], off
	v_lshl_add_u64 v[8:9], v[8:9], 0, s[14:15]
	global_load_dword v126, v[8:9], off
	v_lshl_add_u64 v[8:9], v[8:9], 0, s[14:15]
	global_load_dword v128, v[8:9], off
	v_lshl_add_u64 v[8:9], v[8:9], 0, s[14:15]
	global_load_dword v130, v[8:9], off
	v_lshl_add_u64 v[8:9], v[8:9], 0, s[14:15]
	global_load_dword v132, v[8:9], off
	v_lshl_add_u64 v[8:9], v[8:9], 0, s[14:15]
	global_load_dword v134, v[8:9], off
	v_lshl_add_u64 v[8:9], v[8:9], 0, s[14:15]
	global_load_dword v136, v[8:9], off
	v_lshl_add_u64 v[8:9], v[8:9], 0, s[14:15]
	global_load_dword v138, v[8:9], off
	v_lshl_add_u64 v[8:9], v[8:9], 0, s[14:15]
	global_load_dword v140, v[8:9], off
	v_lshl_add_u64 v[8:9], v[8:9], 0, s[14:15]
	global_load_dword v142, v[8:9], off
	v_lshl_add_u64 v[8:9], v[8:9], 0, s[14:15]
	global_load_dword v144, v[8:9], off
	v_lshl_add_u64 v[8:9], v[8:9], 0, s[14:15]
	global_load_dword v146, v[8:9], off
	v_lshl_add_u64 v[8:9], v[8:9], 0, s[14:15]
	global_load_dword v148, v[8:9], off
	v_lshl_add_u64 v[8:9], v[8:9], 0, s[14:15]
	global_load_dword v150, v[8:9], off
	v_lshl_add_u64 v[8:9], v[8:9], 0, s[14:15]
	global_load_dword v152, v[8:9], off
	v_lshl_add_u64 v[8:9], v[8:9], 0, s[14:15]
	global_load_dword v154, v[8:9], off
	v_lshl_add_u64 v[8:9], v[8:9], 0, s[14:15]
	global_load_dword v156, v[8:9], off
	v_lshl_add_u64 v[8:9], v[8:9], 0, s[14:15]
	global_load_dword v158, v[8:9], off
	v_lshl_add_u64 v[8:9], v[8:9], 0, s[14:15]
	global_load_dword v164, v[8:9], off
	v_lshl_add_u64 v[8:9], v[8:9], 0, s[14:15]
	global_load_dword v166, v[8:9], off
	v_lshl_add_u64 v[8:9], v[8:9], 0, s[14:15]
	global_load_dword v168, v[8:9], off
	v_lshl_add_u64 v[8:9], v[8:9], 0, s[14:15]
	global_load_dword v170, v[8:9], off
	v_lshl_add_u64 v[8:9], v[8:9], 0, s[14:15]
	global_load_dword v41, v[8:9], off
	v_lshl_add_u64 v[8:9], v[8:9], 0, s[14:15]
	global_load_dword v43, v[8:9], off
	v_lshl_add_u64 v[8:9], v[8:9], 0, s[14:15]
	global_load_dword v45, v[8:9], off
	v_lshl_add_u64 v[8:9], v[8:9], 0, s[14:15]
	global_load_dword v47, v[8:9], off
	v_lshl_add_u64 v[8:9], v[8:9], 0, s[14:15]
	global_load_dword v49, v[8:9], off
	v_lshl_add_u64 v[8:9], v[8:9], 0, s[14:15]
	global_load_dword v51, v[8:9], off
	v_lshl_add_u64 v[8:9], v[8:9], 0, s[14:15]
	global_load_dword v53, v[8:9], off
	v_lshl_add_u64 v[8:9], v[8:9], 0, s[14:15]
	global_load_dword v55, v[8:9], off
	v_lshl_add_u64 v[8:9], v[8:9], 0, s[14:15]
	global_load_dword v57, v[8:9], off
	v_lshl_add_u64 v[8:9], v[8:9], 0, s[14:15]
	global_load_dword v59, v[8:9], off
	v_lshl_add_u64 v[8:9], v[8:9], 0, s[14:15]
	global_load_dword v61, v[8:9], off
	v_lshl_add_u64 v[8:9], v[8:9], 0, s[14:15]
	global_load_dword v63, v[8:9], off
	v_lshl_add_u64 v[8:9], v[8:9], 0, s[14:15]
	global_load_dword v65, v[8:9], off
	v_lshl_add_u64 v[8:9], v[8:9], 0, s[14:15]
	global_load_dword v67, v[8:9], off
	v_lshl_add_u64 v[8:9], v[8:9], 0, s[14:15]
	global_load_dword v69, v[8:9], off
	v_lshl_add_u64 v[8:9], v[8:9], 0, s[14:15]
	global_load_dword v71, v[8:9], off
	v_lshl_add_u64 v[8:9], v[8:9], 0, s[14:15]
	global_load_dword v73, v[8:9], off
	v_lshl_add_u64 v[8:9], v[8:9], 0, s[14:15]
	global_load_dword v75, v[8:9], off
	v_lshl_add_u64 v[8:9], v[8:9], 0, s[14:15]
	global_load_dword v77, v[8:9], off
	v_lshl_add_u64 v[8:9], v[8:9], 0, s[14:15]
	global_load_dword v79, v[8:9], off
	v_lshl_add_u64 v[8:9], v[8:9], 0, s[14:15]
	global_load_dword v81, v[8:9], off
	v_lshl_add_u64 v[8:9], v[8:9], 0, s[14:15]
	global_load_dword v83, v[8:9], off
	v_lshl_add_u64 v[8:9], v[8:9], 0, s[14:15]
	global_load_dword v85, v[8:9], off
	v_lshl_add_u64 v[8:9], v[8:9], 0, s[14:15]
	global_load_dword v87, v[8:9], off
	v_lshl_add_u64 v[8:9], v[8:9], 0, s[14:15]
	global_load_dword v89, v[8:9], off
	v_lshl_add_u64 v[8:9], v[8:9], 0, s[14:15]
	global_load_dword v91, v[8:9], off
	v_lshl_add_u64 v[8:9], v[8:9], 0, s[14:15]
	global_load_dword v93, v[8:9], off
	v_lshl_add_u64 v[8:9], v[8:9], 0, s[14:15]
	global_load_dword v95, v[8:9], off
	v_lshl_add_u64 v[8:9], v[8:9], 0, s[14:15]
	global_load_dword v97, v[8:9], off
	v_lshl_add_u64 v[8:9], v[8:9], 0, s[14:15]
	global_load_dword v99, v[8:9], off
	v_lshl_add_u64 v[8:9], v[8:9], 0, s[14:15]
	global_load_dword v101, v[8:9], off
	v_lshl_add_u64 v[8:9], v[8:9], 0, s[14:15]
	global_load_dword v103, v[8:9], off
	v_lshl_add_u64 v[8:9], v[8:9], 0, s[14:15]
	global_load_dword v105, v[8:9], off
	v_lshl_add_u64 v[8:9], v[8:9], 0, s[14:15]
	global_load_dword v107, v[8:9], off
	v_lshl_add_u64 v[8:9], v[8:9], 0, s[14:15]
	global_load_dword v109, v[8:9], off
	v_lshl_add_u64 v[8:9], v[8:9], 0, s[14:15]
	global_load_dword v111, v[8:9], off
	v_lshl_add_u64 v[8:9], v[8:9], 0, s[14:15]
	global_load_dword v113, v[8:9], off
	v_lshl_add_u64 v[8:9], v[8:9], 0, s[14:15]
	global_load_dword v115, v[8:9], off
	v_lshl_add_u64 v[8:9], v[8:9], 0, s[14:15]
	global_load_dword v117, v[8:9], off
	v_lshl_add_u64 v[8:9], v[8:9], 0, s[14:15]
	global_load_dword v119, v[8:9], off
	v_lshl_add_u64 v[8:9], v[8:9], 0, s[14:15]
	global_load_dword v121, v[8:9], off
	v_lshl_add_u64 v[8:9], v[8:9], 0, s[14:15]
	global_load_dword v123, v[8:9], off
	v_lshl_add_u64 v[8:9], v[8:9], 0, s[14:15]
	global_load_dword v125, v[8:9], off
	v_lshl_add_u64 v[8:9], v[8:9], 0, s[14:15]
	global_load_dword v127, v[8:9], off
	v_lshl_add_u64 v[8:9], v[8:9], 0, s[14:15]
	global_load_dword v129, v[8:9], off
	v_lshl_add_u64 v[8:9], v[8:9], 0, s[14:15]
	global_load_dword v131, v[8:9], off
	v_lshl_add_u64 v[8:9], v[8:9], 0, s[14:15]
	global_load_dword v133, v[8:9], off
	v_lshl_add_u64 v[8:9], v[8:9], 0, s[14:15]
	global_load_dword v135, v[8:9], off
	v_lshl_add_u64 v[8:9], v[8:9], 0, s[14:15]
	global_load_dword v137, v[8:9], off
	v_lshl_add_u64 v[8:9], v[8:9], 0, s[14:15]
	global_load_dword v139, v[8:9], off
	v_lshl_add_u64 v[8:9], v[8:9], 0, s[14:15]
	global_load_dword v141, v[8:9], off
	v_lshl_add_u64 v[8:9], v[8:9], 0, s[14:15]
	global_load_dword v143, v[8:9], off
	v_lshl_add_u64 v[8:9], v[8:9], 0, s[14:15]
	global_load_dword v145, v[8:9], off
	v_lshl_add_u64 v[8:9], v[8:9], 0, s[14:15]
	global_load_dword v147, v[8:9], off
	v_lshl_add_u64 v[8:9], v[8:9], 0, s[14:15]
	global_load_dword v149, v[8:9], off
	v_lshl_add_u64 v[8:9], v[8:9], 0, s[14:15]
	global_load_dword v151, v[8:9], off
	v_lshl_add_u64 v[8:9], v[8:9], 0, s[14:15]
	global_load_dword v153, v[8:9], off
	v_lshl_add_u64 v[8:9], v[8:9], 0, s[14:15]
	global_load_dword v155, v[8:9], off
	v_lshl_add_u64 v[8:9], v[8:9], 0, s[14:15]
	global_load_dword v157, v[8:9], off
	v_lshl_add_u64 v[8:9], v[8:9], 0, s[14:15]
	global_load_dword v159, v[8:9], off
	v_lshl_add_u64 v[8:9], v[8:9], 0, s[14:15]
	global_load_dword v165, v[8:9], off
	v_lshl_add_u64 v[8:9], v[8:9], 0, s[14:15]
	global_load_dword v167, v[8:9], off
	v_lshl_add_u64 v[8:9], v[8:9], 0, s[14:15]
	global_load_dword v169, v[8:9], off
	v_lshl_add_u64 v[8:9], v[8:9], 0, s[14:15]
	global_load_dword v171, v[8:9], off
	s_waitcnt vmcnt(63)
	v_readlane_b32 s6, v3, 0
	v_readlane_b32 s7, v19, 0
	v_readlane_b32 s8, v20, 0
	v_readlane_b32 s9, v21, 0
	v_readlane_b32 s10, v22, 0
	v_readlane_b32 s11, v23, 0
	v_readlane_b32 s12, v24, 0
	v_readlane_b32 s13, v25, 0
	v_readlane_b32 s22, v3, 1
	v_readlane_b32 s23, v19, 1
	v_readlane_b32 s24, v20, 1
	v_readlane_b32 s25, v21, 1
	v_readlane_b32 s26, v22, 1
	v_readlane_b32 s27, v23, 1
	v_readlane_b32 s30, v24, 1
	v_readlane_b32 s31, v25, 1
	v_pk_fma_f32 v[16:17], v[40:41], s[6:7], v[16:17] op_sel_hi:[0,1,1]
	v_pk_fma_f32 v[14:15], v[40:41], s[8:9], v[14:15] op_sel_hi:[0,1,1]
	v_pk_fma_f32 v[12:13], v[40:41], s[10:11], v[12:13] op_sel_hi:[0,1,1]
	v_pk_fma_f32 v[10:11], v[40:41], s[12:13], v[10:11] op_sel_hi:[0,1,1]
	v_readlane_b32 s6, v3, 2
	v_readlane_b32 s7, v19, 2
	v_readlane_b32 s8, v20, 2
	v_readlane_b32 s9, v21, 2
	v_readlane_b32 s10, v22, 2
	v_readlane_b32 s11, v23, 2
	v_readlane_b32 s12, v24, 2
	v_readlane_b32 s13, v25, 2
	v_pk_fma_f32 v[16:17], v[42:43], s[22:23], v[16:17] op_sel_hi:[0,1,1]
	v_pk_fma_f32 v[14:15], v[42:43], s[24:25], v[14:15] op_sel_hi:[0,1,1]
	v_pk_fma_f32 v[12:13], v[42:43], s[26:27], v[12:13] op_sel_hi:[0,1,1]
	v_pk_fma_f32 v[10:11], v[42:43], s[30:31], v[10:11] op_sel_hi:[0,1,1]
	v_readlane_b32 s22, v3, 3
	v_readlane_b32 s23, v19, 3
	v_readlane_b32 s24, v20, 3
	v_readlane_b32 s25, v21, 3
	v_readlane_b32 s26, v22, 3
	v_readlane_b32 s27, v23, 3
	v_readlane_b32 s30, v24, 3
	v_readlane_b32 s31, v25, 3
	v_pk_fma_f32 v[16:17], v[44:45], s[6:7], v[16:17] op_sel_hi:[0,1,1]
	v_pk_fma_f32 v[14:15], v[44:45], s[8:9], v[14:15] op_sel_hi:[0,1,1]
	v_pk_fma_f32 v[12:13], v[44:45], s[10:11], v[12:13] op_sel_hi:[0,1,1]
	v_pk_fma_f32 v[10:11], v[44:45], s[12:13], v[10:11] op_sel_hi:[0,1,1]
	v_readlane_b32 s6, v3, 4
	v_readlane_b32 s7, v19, 4
	v_readlane_b32 s8, v20, 4
	v_readlane_b32 s9, v21, 4
	v_readlane_b32 s10, v22, 4
	v_readlane_b32 s11, v23, 4
	v_readlane_b32 s12, v24, 4
	v_readlane_b32 s13, v25, 4
	v_pk_fma_f32 v[16:17], v[46:47], s[22:23], v[16:17] op_sel_hi:[0,1,1]
	v_pk_fma_f32 v[14:15], v[46:47], s[24:25], v[14:15] op_sel_hi:[0,1,1]
	v_pk_fma_f32 v[12:13], v[46:47], s[26:27], v[12:13] op_sel_hi:[0,1,1]
	v_pk_fma_f32 v[10:11], v[46:47], s[30:31], v[10:11] op_sel_hi:[0,1,1]
	v_readlane_b32 s22, v3, 5
	v_readlane_b32 s23, v19, 5
	v_readlane_b32 s24, v20, 5
	v_readlane_b32 s25, v21, 5
	v_readlane_b32 s26, v22, 5
	v_readlane_b32 s27, v23, 5
	v_readlane_b32 s30, v24, 5
	v_readlane_b32 s31, v25, 5
	v_pk_fma_f32 v[16:17], v[48:49], s[6:7], v[16:17] op_sel_hi:[0,1,1]
	v_pk_fma_f32 v[14:15], v[48:49], s[8:9], v[14:15] op_sel_hi:[0,1,1]
	v_pk_fma_f32 v[12:13], v[48:49], s[10:11], v[12:13] op_sel_hi:[0,1,1]
	v_pk_fma_f32 v[10:11], v[48:49], s[12:13], v[10:11] op_sel_hi:[0,1,1]
	v_readlane_b32 s6, v3, 6
	v_readlane_b32 s7, v19, 6
	v_readlane_b32 s8, v20, 6
	v_readlane_b32 s9, v21, 6
	v_readlane_b32 s10, v22, 6
	v_readlane_b32 s11, v23, 6
	v_readlane_b32 s12, v24, 6
	v_readlane_b32 s13, v25, 6
	v_pk_fma_f32 v[16:17], v[50:51], s[22:23], v[16:17] op_sel_hi:[0,1,1]
	v_pk_fma_f32 v[14:15], v[50:51], s[24:25], v[14:15] op_sel_hi:[0,1,1]
	v_pk_fma_f32 v[12:13], v[50:51], s[26:27], v[12:13] op_sel_hi:[0,1,1]
	v_pk_fma_f32 v[10:11], v[50:51], s[30:31], v[10:11] op_sel_hi:[0,1,1]
	v_readlane_b32 s22, v3, 7
	v_readlane_b32 s23, v19, 7
	v_readlane_b32 s24, v20, 7
	v_readlane_b32 s25, v21, 7
	v_readlane_b32 s26, v22, 7
	v_readlane_b32 s27, v23, 7
	v_readlane_b32 s30, v24, 7
	v_readlane_b32 s31, v25, 7
	v_pk_fma_f32 v[16:17], v[52:53], s[6:7], v[16:17] op_sel_hi:[0,1,1]
	v_pk_fma_f32 v[14:15], v[52:53], s[8:9], v[14:15] op_sel_hi:[0,1,1]
	v_pk_fma_f32 v[12:13], v[52:53], s[10:11], v[12:13] op_sel_hi:[0,1,1]
	v_pk_fma_f32 v[10:11], v[52:53], s[12:13], v[10:11] op_sel_hi:[0,1,1]
	v_readlane_b32 s6, v3, 8
	v_readlane_b32 s7, v19, 8
	v_readlane_b32 s8, v20, 8
	v_readlane_b32 s9, v21, 8
	v_readlane_b32 s10, v22, 8
	v_readlane_b32 s11, v23, 8
	v_readlane_b32 s12, v24, 8
	v_readlane_b32 s13, v25, 8
	v_pk_fma_f32 v[16:17], v[54:55], s[22:23], v[16:17] op_sel_hi:[0,1,1]
	v_pk_fma_f32 v[14:15], v[54:55], s[24:25], v[14:15] op_sel_hi:[0,1,1]
	v_pk_fma_f32 v[12:13], v[54:55], s[26:27], v[12:13] op_sel_hi:[0,1,1]
	v_pk_fma_f32 v[10:11], v[54:55], s[30:31], v[10:11] op_sel_hi:[0,1,1]
	v_readlane_b32 s22, v3, 9
	v_readlane_b32 s23, v19, 9
	v_readlane_b32 s24, v20, 9
	v_readlane_b32 s25, v21, 9
	v_readlane_b32 s26, v22, 9
	v_readlane_b32 s27, v23, 9
	v_readlane_b32 s30, v24, 9
	v_readlane_b32 s31, v25, 9
	v_pk_fma_f32 v[16:17], v[56:57], s[6:7], v[16:17] op_sel_hi:[0,1,1]
	v_pk_fma_f32 v[14:15], v[56:57], s[8:9], v[14:15] op_sel_hi:[0,1,1]
	v_pk_fma_f32 v[12:13], v[56:57], s[10:11], v[12:13] op_sel_hi:[0,1,1]
	v_pk_fma_f32 v[10:11], v[56:57], s[12:13], v[10:11] op_sel_hi:[0,1,1]
	v_readlane_b32 s6, v3, 10
	v_readlane_b32 s7, v19, 10
	v_readlane_b32 s8, v20, 10
	v_readlane_b32 s9, v21, 10
	v_readlane_b32 s10, v22, 10
	v_readlane_b32 s11, v23, 10
	v_readlane_b32 s12, v24, 10
	v_readlane_b32 s13, v25, 10
	v_pk_fma_f32 v[16:17], v[58:59], s[22:23], v[16:17] op_sel_hi:[0,1,1]
	v_pk_fma_f32 v[14:15], v[58:59], s[24:25], v[14:15] op_sel_hi:[0,1,1]
	v_pk_fma_f32 v[12:13], v[58:59], s[26:27], v[12:13] op_sel_hi:[0,1,1]
	v_pk_fma_f32 v[10:11], v[58:59], s[30:31], v[10:11] op_sel_hi:[0,1,1]
	v_readlane_b32 s22, v3, 11
	v_readlane_b32 s23, v19, 11
	v_readlane_b32 s24, v20, 11
	v_readlane_b32 s25, v21, 11
	v_readlane_b32 s26, v22, 11
	v_readlane_b32 s27, v23, 11
	v_readlane_b32 s30, v24, 11
	v_readlane_b32 s31, v25, 11
	v_pk_fma_f32 v[16:17], v[60:61], s[6:7], v[16:17] op_sel_hi:[0,1,1]
	v_pk_fma_f32 v[14:15], v[60:61], s[8:9], v[14:15] op_sel_hi:[0,1,1]
	v_pk_fma_f32 v[12:13], v[60:61], s[10:11], v[12:13] op_sel_hi:[0,1,1]
	v_pk_fma_f32 v[10:11], v[60:61], s[12:13], v[10:11] op_sel_hi:[0,1,1]
	v_readlane_b32 s6, v3, 12
	v_readlane_b32 s7, v19, 12
	v_readlane_b32 s8, v20, 12
	v_readlane_b32 s9, v21, 12
	v_readlane_b32 s10, v22, 12
	v_readlane_b32 s11, v23, 12
	v_readlane_b32 s12, v24, 12
	v_readlane_b32 s13, v25, 12
	v_pk_fma_f32 v[16:17], v[62:63], s[22:23], v[16:17] op_sel_hi:[0,1,1]
	v_pk_fma_f32 v[14:15], v[62:63], s[24:25], v[14:15] op_sel_hi:[0,1,1]
	v_pk_fma_f32 v[12:13], v[62:63], s[26:27], v[12:13] op_sel_hi:[0,1,1]
	v_pk_fma_f32 v[10:11], v[62:63], s[30:31], v[10:11] op_sel_hi:[0,1,1]
	v_readlane_b32 s22, v3, 13
	v_readlane_b32 s23, v19, 13
	v_readlane_b32 s24, v20, 13
	v_readlane_b32 s25, v21, 13
	v_readlane_b32 s26, v22, 13
	v_readlane_b32 s27, v23, 13
	v_readlane_b32 s30, v24, 13
	v_readlane_b32 s31, v25, 13
	v_pk_fma_f32 v[16:17], v[64:65], s[6:7], v[16:17] op_sel_hi:[0,1,1]
	v_pk_fma_f32 v[14:15], v[64:65], s[8:9], v[14:15] op_sel_hi:[0,1,1]
	v_pk_fma_f32 v[12:13], v[64:65], s[10:11], v[12:13] op_sel_hi:[0,1,1]
	v_pk_fma_f32 v[10:11], v[64:65], s[12:13], v[10:11] op_sel_hi:[0,1,1]
	v_readlane_b32 s6, v3, 14
	v_readlane_b32 s7, v19, 14
	v_readlane_b32 s8, v20, 14
	v_readlane_b32 s9, v21, 14
	v_readlane_b32 s10, v22, 14
	v_readlane_b32 s11, v23, 14
	v_readlane_b32 s12, v24, 14
	v_readlane_b32 s13, v25, 14
	v_pk_fma_f32 v[16:17], v[66:67], s[22:23], v[16:17] op_sel_hi:[0,1,1]
	v_pk_fma_f32 v[14:15], v[66:67], s[24:25], v[14:15] op_sel_hi:[0,1,1]
	v_pk_fma_f32 v[12:13], v[66:67], s[26:27], v[12:13] op_sel_hi:[0,1,1]
	v_pk_fma_f32 v[10:11], v[66:67], s[30:31], v[10:11] op_sel_hi:[0,1,1]
	v_readlane_b32 s22, v3, 15
	v_readlane_b32 s23, v19, 15
	v_readlane_b32 s24, v20, 15
	v_readlane_b32 s25, v21, 15
	v_readlane_b32 s26, v22, 15
	v_readlane_b32 s27, v23, 15
	v_readlane_b32 s30, v24, 15
	v_readlane_b32 s31, v25, 15
	v_pk_fma_f32 v[16:17], v[68:69], s[6:7], v[16:17] op_sel_hi:[0,1,1]
	v_pk_fma_f32 v[14:15], v[68:69], s[8:9], v[14:15] op_sel_hi:[0,1,1]
	v_pk_fma_f32 v[12:13], v[68:69], s[10:11], v[12:13] op_sel_hi:[0,1,1]
	v_pk_fma_f32 v[10:11], v[68:69], s[12:13], v[10:11] op_sel_hi:[0,1,1]
	v_readlane_b32 s6, v3, 16
	v_readlane_b32 s7, v19, 16
	v_readlane_b32 s8, v20, 16
	v_readlane_b32 s9, v21, 16
	v_readlane_b32 s10, v22, 16
	v_readlane_b32 s11, v23, 16
	v_readlane_b32 s12, v24, 16
	v_readlane_b32 s13, v25, 16
	v_pk_fma_f32 v[16:17], v[70:71], s[22:23], v[16:17] op_sel_hi:[0,1,1]
	v_pk_fma_f32 v[14:15], v[70:71], s[24:25], v[14:15] op_sel_hi:[0,1,1]
	v_pk_fma_f32 v[12:13], v[70:71], s[26:27], v[12:13] op_sel_hi:[0,1,1]
	v_pk_fma_f32 v[10:11], v[70:71], s[30:31], v[10:11] op_sel_hi:[0,1,1]
	v_readlane_b32 s22, v3, 17
	v_readlane_b32 s23, v19, 17
	v_readlane_b32 s24, v20, 17
	v_readlane_b32 s25, v21, 17
	v_readlane_b32 s26, v22, 17
	v_readlane_b32 s27, v23, 17
	v_readlane_b32 s30, v24, 17
	v_readlane_b32 s31, v25, 17
	v_pk_fma_f32 v[16:17], v[72:73], s[6:7], v[16:17] op_sel_hi:[0,1,1]
	v_pk_fma_f32 v[14:15], v[72:73], s[8:9], v[14:15] op_sel_hi:[0,1,1]
	v_pk_fma_f32 v[12:13], v[72:73], s[10:11], v[12:13] op_sel_hi:[0,1,1]
	v_pk_fma_f32 v[10:11], v[72:73], s[12:13], v[10:11] op_sel_hi:[0,1,1]
	v_readlane_b32 s6, v3, 18
	v_readlane_b32 s7, v19, 18
	v_readlane_b32 s8, v20, 18
	v_readlane_b32 s9, v21, 18
	v_readlane_b32 s10, v22, 18
	v_readlane_b32 s11, v23, 18
	v_readlane_b32 s12, v24, 18
	v_readlane_b32 s13, v25, 18
	v_pk_fma_f32 v[16:17], v[74:75], s[22:23], v[16:17] op_sel_hi:[0,1,1]
	v_pk_fma_f32 v[14:15], v[74:75], s[24:25], v[14:15] op_sel_hi:[0,1,1]
	v_pk_fma_f32 v[12:13], v[74:75], s[26:27], v[12:13] op_sel_hi:[0,1,1]
	v_pk_fma_f32 v[10:11], v[74:75], s[30:31], v[10:11] op_sel_hi:[0,1,1]
	v_readlane_b32 s22, v3, 19
	v_readlane_b32 s23, v19, 19
	v_readlane_b32 s24, v20, 19
	v_readlane_b32 s25, v21, 19
	v_readlane_b32 s26, v22, 19
	v_readlane_b32 s27, v23, 19
	v_readlane_b32 s30, v24, 19
	v_readlane_b32 s31, v25, 19
	v_pk_fma_f32 v[16:17], v[76:77], s[6:7], v[16:17] op_sel_hi:[0,1,1]
	v_pk_fma_f32 v[14:15], v[76:77], s[8:9], v[14:15] op_sel_hi:[0,1,1]
	v_pk_fma_f32 v[12:13], v[76:77], s[10:11], v[12:13] op_sel_hi:[0,1,1]
	v_pk_fma_f32 v[10:11], v[76:77], s[12:13], v[10:11] op_sel_hi:[0,1,1]
	v_readlane_b32 s6, v3, 20
	v_readlane_b32 s7, v19, 20
	v_readlane_b32 s8, v20, 20
	v_readlane_b32 s9, v21, 20
	v_readlane_b32 s10, v22, 20
	v_readlane_b32 s11, v23, 20
	v_readlane_b32 s12, v24, 20
	v_readlane_b32 s13, v25, 20
	v_pk_fma_f32 v[16:17], v[78:79], s[22:23], v[16:17] op_sel_hi:[0,1,1]
	v_pk_fma_f32 v[14:15], v[78:79], s[24:25], v[14:15] op_sel_hi:[0,1,1]
	v_pk_fma_f32 v[12:13], v[78:79], s[26:27], v[12:13] op_sel_hi:[0,1,1]
	v_pk_fma_f32 v[10:11], v[78:79], s[30:31], v[10:11] op_sel_hi:[0,1,1]
	v_readlane_b32 s22, v3, 21
	v_readlane_b32 s23, v19, 21
	v_readlane_b32 s24, v20, 21
	v_readlane_b32 s25, v21, 21
	v_readlane_b32 s26, v22, 21
	v_readlane_b32 s27, v23, 21
	v_readlane_b32 s30, v24, 21
	v_readlane_b32 s31, v25, 21
	v_pk_fma_f32 v[16:17], v[80:81], s[6:7], v[16:17] op_sel_hi:[0,1,1]
	v_pk_fma_f32 v[14:15], v[80:81], s[8:9], v[14:15] op_sel_hi:[0,1,1]
	v_pk_fma_f32 v[12:13], v[80:81], s[10:11], v[12:13] op_sel_hi:[0,1,1]
	v_pk_fma_f32 v[10:11], v[80:81], s[12:13], v[10:11] op_sel_hi:[0,1,1]
	v_readlane_b32 s6, v3, 22
	v_readlane_b32 s7, v19, 22
	v_readlane_b32 s8, v20, 22
	v_readlane_b32 s9, v21, 22
	v_readlane_b32 s10, v22, 22
	v_readlane_b32 s11, v23, 22
	v_readlane_b32 s12, v24, 22
	v_readlane_b32 s13, v25, 22
	v_pk_fma_f32 v[16:17], v[82:83], s[22:23], v[16:17] op_sel_hi:[0,1,1]
	v_pk_fma_f32 v[14:15], v[82:83], s[24:25], v[14:15] op_sel_hi:[0,1,1]
	v_pk_fma_f32 v[12:13], v[82:83], s[26:27], v[12:13] op_sel_hi:[0,1,1]
	v_pk_fma_f32 v[10:11], v[82:83], s[30:31], v[10:11] op_sel_hi:[0,1,1]
	v_readlane_b32 s22, v3, 23
	v_readlane_b32 s23, v19, 23
	v_readlane_b32 s24, v20, 23
	v_readlane_b32 s25, v21, 23
	v_readlane_b32 s26, v22, 23
	v_readlane_b32 s27, v23, 23
	v_readlane_b32 s30, v24, 23
	v_readlane_b32 s31, v25, 23
	v_pk_fma_f32 v[16:17], v[84:85], s[6:7], v[16:17] op_sel_hi:[0,1,1]
	v_pk_fma_f32 v[14:15], v[84:85], s[8:9], v[14:15] op_sel_hi:[0,1,1]
	v_pk_fma_f32 v[12:13], v[84:85], s[10:11], v[12:13] op_sel_hi:[0,1,1]
	v_pk_fma_f32 v[10:11], v[84:85], s[12:13], v[10:11] op_sel_hi:[0,1,1]
	v_readlane_b32 s6, v3, 24
	v_readlane_b32 s7, v19, 24
	v_readlane_b32 s8, v20, 24
	v_readlane_b32 s9, v21, 24
	v_readlane_b32 s10, v22, 24
	v_readlane_b32 s11, v23, 24
	v_readlane_b32 s12, v24, 24
	v_readlane_b32 s13, v25, 24
	v_pk_fma_f32 v[16:17], v[86:87], s[22:23], v[16:17] op_sel_hi:[0,1,1]
	v_pk_fma_f32 v[14:15], v[86:87], s[24:25], v[14:15] op_sel_hi:[0,1,1]
	v_pk_fma_f32 v[12:13], v[86:87], s[26:27], v[12:13] op_sel_hi:[0,1,1]
	v_pk_fma_f32 v[10:11], v[86:87], s[30:31], v[10:11] op_sel_hi:[0,1,1]
	v_readlane_b32 s22, v3, 25
	v_readlane_b32 s23, v19, 25
	v_readlane_b32 s24, v20, 25
	v_readlane_b32 s25, v21, 25
	v_readlane_b32 s26, v22, 25
	v_readlane_b32 s27, v23, 25
	v_readlane_b32 s30, v24, 25
	v_readlane_b32 s31, v25, 25
	v_pk_fma_f32 v[16:17], v[88:89], s[6:7], v[16:17] op_sel_hi:[0,1,1]
	v_pk_fma_f32 v[14:15], v[88:89], s[8:9], v[14:15] op_sel_hi:[0,1,1]
	v_pk_fma_f32 v[12:13], v[88:89], s[10:11], v[12:13] op_sel_hi:[0,1,1]
	v_pk_fma_f32 v[10:11], v[88:89], s[12:13], v[10:11] op_sel_hi:[0,1,1]
	v_readlane_b32 s6, v3, 26
	v_readlane_b32 s7, v19, 26
	v_readlane_b32 s8, v20, 26
	v_readlane_b32 s9, v21, 26
	v_readlane_b32 s10, v22, 26
	v_readlane_b32 s11, v23, 26
	v_readlane_b32 s12, v24, 26
	v_readlane_b32 s13, v25, 26
	v_pk_fma_f32 v[16:17], v[90:91], s[22:23], v[16:17] op_sel_hi:[0,1,1]
	v_pk_fma_f32 v[14:15], v[90:91], s[24:25], v[14:15] op_sel_hi:[0,1,1]
	v_pk_fma_f32 v[12:13], v[90:91], s[26:27], v[12:13] op_sel_hi:[0,1,1]
	v_pk_fma_f32 v[10:11], v[90:91], s[30:31], v[10:11] op_sel_hi:[0,1,1]
	v_readlane_b32 s22, v3, 27
	v_readlane_b32 s23, v19, 27
	v_readlane_b32 s24, v20, 27
	v_readlane_b32 s25, v21, 27
	v_readlane_b32 s26, v22, 27
	v_readlane_b32 s27, v23, 27
	v_readlane_b32 s30, v24, 27
	v_readlane_b32 s31, v25, 27
	v_pk_fma_f32 v[16:17], v[92:93], s[6:7], v[16:17] op_sel_hi:[0,1,1]
	v_pk_fma_f32 v[14:15], v[92:93], s[8:9], v[14:15] op_sel_hi:[0,1,1]
	v_pk_fma_f32 v[12:13], v[92:93], s[10:11], v[12:13] op_sel_hi:[0,1,1]
	v_pk_fma_f32 v[10:11], v[92:93], s[12:13], v[10:11] op_sel_hi:[0,1,1]
	v_readlane_b32 s6, v3, 28
	v_readlane_b32 s7, v19, 28
	v_readlane_b32 s8, v20, 28
	v_readlane_b32 s9, v21, 28
	v_readlane_b32 s10, v22, 28
	v_readlane_b32 s11, v23, 28
	v_readlane_b32 s12, v24, 28
	v_readlane_b32 s13, v25, 28
	v_pk_fma_f32 v[16:17], v[94:95], s[22:23], v[16:17] op_sel_hi:[0,1,1]
	v_pk_fma_f32 v[14:15], v[94:95], s[24:25], v[14:15] op_sel_hi:[0,1,1]
	v_pk_fma_f32 v[12:13], v[94:95], s[26:27], v[12:13] op_sel_hi:[0,1,1]
	v_pk_fma_f32 v[10:11], v[94:95], s[30:31], v[10:11] op_sel_hi:[0,1,1]
	v_readlane_b32 s22, v3, 29
	v_readlane_b32 s23, v19, 29
	v_readlane_b32 s24, v20, 29
	v_readlane_b32 s25, v21, 29
	v_readlane_b32 s26, v22, 29
	v_readlane_b32 s27, v23, 29
	v_readlane_b32 s30, v24, 29
	v_readlane_b32 s31, v25, 29
	v_pk_fma_f32 v[16:17], v[96:97], s[6:7], v[16:17] op_sel_hi:[0,1,1]
	v_pk_fma_f32 v[14:15], v[96:97], s[8:9], v[14:15] op_sel_hi:[0,1,1]
	v_pk_fma_f32 v[12:13], v[96:97], s[10:11], v[12:13] op_sel_hi:[0,1,1]
	v_pk_fma_f32 v[10:11], v[96:97], s[12:13], v[10:11] op_sel_hi:[0,1,1]
	v_readlane_b32 s6, v3, 30
	v_readlane_b32 s7, v19, 30
	v_readlane_b32 s8, v20, 30
	v_readlane_b32 s9, v21, 30
	v_readlane_b32 s10, v22, 30
	v_readlane_b32 s11, v23, 30
	v_readlane_b32 s12, v24, 30
	v_readlane_b32 s13, v25, 30
	v_pk_fma_f32 v[16:17], v[98:99], s[22:23], v[16:17] op_sel_hi:[0,1,1]
	v_pk_fma_f32 v[14:15], v[98:99], s[24:25], v[14:15] op_sel_hi:[0,1,1]
	v_pk_fma_f32 v[12:13], v[98:99], s[26:27], v[12:13] op_sel_hi:[0,1,1]
	v_pk_fma_f32 v[10:11], v[98:99], s[30:31], v[10:11] op_sel_hi:[0,1,1]
	v_readlane_b32 s22, v3, 31
	v_readlane_b32 s23, v19, 31
	v_readlane_b32 s24, v20, 31
	v_readlane_b32 s25, v21, 31
	v_readlane_b32 s26, v22, 31
	v_readlane_b32 s27, v23, 31
	v_readlane_b32 s30, v24, 31
	v_readlane_b32 s31, v25, 31
	v_pk_fma_f32 v[16:17], v[100:101], s[6:7], v[16:17] op_sel_hi:[0,1,1]
	v_pk_fma_f32 v[14:15], v[100:101], s[8:9], v[14:15] op_sel_hi:[0,1,1]
	v_pk_fma_f32 v[12:13], v[100:101], s[10:11], v[12:13] op_sel_hi:[0,1,1]
	v_pk_fma_f32 v[10:11], v[100:101], s[12:13], v[10:11] op_sel_hi:[0,1,1]
	v_readlane_b32 s6, v3, 32
	v_readlane_b32 s7, v19, 32
	v_readlane_b32 s8, v20, 32
	v_readlane_b32 s9, v21, 32
	v_readlane_b32 s10, v22, 32
	v_readlane_b32 s11, v23, 32
	v_readlane_b32 s12, v24, 32
	v_readlane_b32 s13, v25, 32
	v_pk_fma_f32 v[16:17], v[102:103], s[22:23], v[16:17] op_sel_hi:[0,1,1]
	v_pk_fma_f32 v[14:15], v[102:103], s[24:25], v[14:15] op_sel_hi:[0,1,1]
	v_pk_fma_f32 v[12:13], v[102:103], s[26:27], v[12:13] op_sel_hi:[0,1,1]
	v_pk_fma_f32 v[10:11], v[102:103], s[30:31], v[10:11] op_sel_hi:[0,1,1]
	v_readlane_b32 s22, v3, 33
	v_readlane_b32 s23, v19, 33
	v_readlane_b32 s24, v20, 33
	v_readlane_b32 s25, v21, 33
	v_readlane_b32 s26, v22, 33
	v_readlane_b32 s27, v23, 33
	v_readlane_b32 s30, v24, 33
	v_readlane_b32 s31, v25, 33
	v_pk_fma_f32 v[16:17], v[104:105], s[6:7], v[16:17] op_sel_hi:[0,1,1]
	v_pk_fma_f32 v[14:15], v[104:105], s[8:9], v[14:15] op_sel_hi:[0,1,1]
	v_pk_fma_f32 v[12:13], v[104:105], s[10:11], v[12:13] op_sel_hi:[0,1,1]
	v_pk_fma_f32 v[10:11], v[104:105], s[12:13], v[10:11] op_sel_hi:[0,1,1]
	v_readlane_b32 s6, v3, 34
	v_readlane_b32 s7, v19, 34
	v_readlane_b32 s8, v20, 34
	v_readlane_b32 s9, v21, 34
	v_readlane_b32 s10, v22, 34
	v_readlane_b32 s11, v23, 34
	v_readlane_b32 s12, v24, 34
	v_readlane_b32 s13, v25, 34
	v_pk_fma_f32 v[16:17], v[106:107], s[22:23], v[16:17] op_sel_hi:[0,1,1]
	v_pk_fma_f32 v[14:15], v[106:107], s[24:25], v[14:15] op_sel_hi:[0,1,1]
	v_pk_fma_f32 v[12:13], v[106:107], s[26:27], v[12:13] op_sel_hi:[0,1,1]
	v_pk_fma_f32 v[10:11], v[106:107], s[30:31], v[10:11] op_sel_hi:[0,1,1]
	v_readlane_b32 s22, v3, 35
	v_readlane_b32 s23, v19, 35
	v_readlane_b32 s24, v20, 35
	v_readlane_b32 s25, v21, 35
	v_readlane_b32 s26, v22, 35
	v_readlane_b32 s27, v23, 35
	v_readlane_b32 s30, v24, 35
	v_readlane_b32 s31, v25, 35
	v_pk_fma_f32 v[16:17], v[108:109], s[6:7], v[16:17] op_sel_hi:[0,1,1]
	v_pk_fma_f32 v[14:15], v[108:109], s[8:9], v[14:15] op_sel_hi:[0,1,1]
	v_pk_fma_f32 v[12:13], v[108:109], s[10:11], v[12:13] op_sel_hi:[0,1,1]
	v_pk_fma_f32 v[10:11], v[108:109], s[12:13], v[10:11] op_sel_hi:[0,1,1]
	v_readlane_b32 s6, v3, 36
	v_readlane_b32 s7, v19, 36
	v_readlane_b32 s8, v20, 36
	v_readlane_b32 s9, v21, 36
	v_readlane_b32 s10, v22, 36
	v_readlane_b32 s11, v23, 36
	v_readlane_b32 s12, v24, 36
	v_readlane_b32 s13, v25, 36
	v_pk_fma_f32 v[16:17], v[110:111], s[22:23], v[16:17] op_sel_hi:[0,1,1]
	v_pk_fma_f32 v[14:15], v[110:111], s[24:25], v[14:15] op_sel_hi:[0,1,1]
	v_pk_fma_f32 v[12:13], v[110:111], s[26:27], v[12:13] op_sel_hi:[0,1,1]
	v_pk_fma_f32 v[10:11], v[110:111], s[30:31], v[10:11] op_sel_hi:[0,1,1]
	v_readlane_b32 s22, v3, 37
	v_readlane_b32 s23, v19, 37
	v_readlane_b32 s24, v20, 37
	v_readlane_b32 s25, v21, 37
	v_readlane_b32 s26, v22, 37
	v_readlane_b32 s27, v23, 37
	v_readlane_b32 s30, v24, 37
	v_readlane_b32 s31, v25, 37
	v_pk_fma_f32 v[16:17], v[112:113], s[6:7], v[16:17] op_sel_hi:[0,1,1]
	v_pk_fma_f32 v[14:15], v[112:113], s[8:9], v[14:15] op_sel_hi:[0,1,1]
	v_pk_fma_f32 v[12:13], v[112:113], s[10:11], v[12:13] op_sel_hi:[0,1,1]
	v_pk_fma_f32 v[10:11], v[112:113], s[12:13], v[10:11] op_sel_hi:[0,1,1]
	v_readlane_b32 s6, v3, 38
	v_readlane_b32 s7, v19, 38
	v_readlane_b32 s8, v20, 38
	v_readlane_b32 s9, v21, 38
	v_readlane_b32 s10, v22, 38
	v_readlane_b32 s11, v23, 38
	v_readlane_b32 s12, v24, 38
	v_readlane_b32 s13, v25, 38
	v_pk_fma_f32 v[16:17], v[114:115], s[22:23], v[16:17] op_sel_hi:[0,1,1]
	v_pk_fma_f32 v[14:15], v[114:115], s[24:25], v[14:15] op_sel_hi:[0,1,1]
	v_pk_fma_f32 v[12:13], v[114:115], s[26:27], v[12:13] op_sel_hi:[0,1,1]
	v_pk_fma_f32 v[10:11], v[114:115], s[30:31], v[10:11] op_sel_hi:[0,1,1]
	v_readlane_b32 s22, v3, 39
	v_readlane_b32 s23, v19, 39
	v_readlane_b32 s24, v20, 39
	v_readlane_b32 s25, v21, 39
	v_readlane_b32 s26, v22, 39
	v_readlane_b32 s27, v23, 39
	v_readlane_b32 s30, v24, 39
	v_readlane_b32 s31, v25, 39
	v_pk_fma_f32 v[16:17], v[116:117], s[6:7], v[16:17] op_sel_hi:[0,1,1]
	v_pk_fma_f32 v[14:15], v[116:117], s[8:9], v[14:15] op_sel_hi:[0,1,1]
	v_pk_fma_f32 v[12:13], v[116:117], s[10:11], v[12:13] op_sel_hi:[0,1,1]
	v_pk_fma_f32 v[10:11], v[116:117], s[12:13], v[10:11] op_sel_hi:[0,1,1]
	v_readlane_b32 s6, v3, 40
	v_readlane_b32 s7, v19, 40
	v_readlane_b32 s8, v20, 40
	v_readlane_b32 s9, v21, 40
	v_readlane_b32 s10, v22, 40
	v_readlane_b32 s11, v23, 40
	v_readlane_b32 s12, v24, 40
	v_readlane_b32 s13, v25, 40
	v_pk_fma_f32 v[16:17], v[118:119], s[22:23], v[16:17] op_sel_hi:[0,1,1]
	v_pk_fma_f32 v[14:15], v[118:119], s[24:25], v[14:15] op_sel_hi:[0,1,1]
	v_pk_fma_f32 v[12:13], v[118:119], s[26:27], v[12:13] op_sel_hi:[0,1,1]
	v_pk_fma_f32 v[10:11], v[118:119], s[30:31], v[10:11] op_sel_hi:[0,1,1]
	v_readlane_b32 s22, v3, 41
	v_readlane_b32 s23, v19, 41
	v_readlane_b32 s24, v20, 41
	v_readlane_b32 s25, v21, 41
	v_readlane_b32 s26, v22, 41
	v_readlane_b32 s27, v23, 41
	v_readlane_b32 s30, v24, 41
	v_readlane_b32 s31, v25, 41
	v_pk_fma_f32 v[16:17], v[120:121], s[6:7], v[16:17] op_sel_hi:[0,1,1]
	v_pk_fma_f32 v[14:15], v[120:121], s[8:9], v[14:15] op_sel_hi:[0,1,1]
	v_pk_fma_f32 v[12:13], v[120:121], s[10:11], v[12:13] op_sel_hi:[0,1,1]
	v_pk_fma_f32 v[10:11], v[120:121], s[12:13], v[10:11] op_sel_hi:[0,1,1]
	v_readlane_b32 s6, v3, 42
	v_readlane_b32 s7, v19, 42
	v_readlane_b32 s8, v20, 42
	v_readlane_b32 s9, v21, 42
	v_readlane_b32 s10, v22, 42
	v_readlane_b32 s11, v23, 42
	v_readlane_b32 s12, v24, 42
	v_readlane_b32 s13, v25, 42
	v_pk_fma_f32 v[16:17], v[122:123], s[22:23], v[16:17] op_sel_hi:[0,1,1]
	v_pk_fma_f32 v[14:15], v[122:123], s[24:25], v[14:15] op_sel_hi:[0,1,1]
	v_pk_fma_f32 v[12:13], v[122:123], s[26:27], v[12:13] op_sel_hi:[0,1,1]
	v_pk_fma_f32 v[10:11], v[122:123], s[30:31], v[10:11] op_sel_hi:[0,1,1]
	v_readlane_b32 s22, v3, 43
	v_readlane_b32 s23, v19, 43
	v_readlane_b32 s24, v20, 43
	v_readlane_b32 s25, v21, 43
	v_readlane_b32 s26, v22, 43
	v_readlane_b32 s27, v23, 43
	v_readlane_b32 s30, v24, 43
	v_readlane_b32 s31, v25, 43
	v_pk_fma_f32 v[16:17], v[124:125], s[6:7], v[16:17] op_sel_hi:[0,1,1]
	v_pk_fma_f32 v[14:15], v[124:125], s[8:9], v[14:15] op_sel_hi:[0,1,1]
	v_pk_fma_f32 v[12:13], v[124:125], s[10:11], v[12:13] op_sel_hi:[0,1,1]
	v_pk_fma_f32 v[10:11], v[124:125], s[12:13], v[10:11] op_sel_hi:[0,1,1]
	v_readlane_b32 s6, v3, 44
	v_readlane_b32 s7, v19, 44
	v_readlane_b32 s8, v20, 44
	v_readlane_b32 s9, v21, 44
	v_readlane_b32 s10, v22, 44
	v_readlane_b32 s11, v23, 44
	v_readlane_b32 s12, v24, 44
	v_readlane_b32 s13, v25, 44
	v_pk_fma_f32 v[16:17], v[126:127], s[22:23], v[16:17] op_sel_hi:[0,1,1]
	v_pk_fma_f32 v[14:15], v[126:127], s[24:25], v[14:15] op_sel_hi:[0,1,1]
	v_pk_fma_f32 v[12:13], v[126:127], s[26:27], v[12:13] op_sel_hi:[0,1,1]
	v_pk_fma_f32 v[10:11], v[126:127], s[30:31], v[10:11] op_sel_hi:[0,1,1]
	v_readlane_b32 s22, v3, 45
	v_readlane_b32 s23, v19, 45
	v_readlane_b32 s24, v20, 45
	v_readlane_b32 s25, v21, 45
	v_readlane_b32 s26, v22, 45
	v_readlane_b32 s27, v23, 45
	v_readlane_b32 s30, v24, 45
	v_readlane_b32 s31, v25, 45
	v_pk_fma_f32 v[16:17], v[128:129], s[6:7], v[16:17] op_sel_hi:[0,1,1]
	v_pk_fma_f32 v[14:15], v[128:129], s[8:9], v[14:15] op_sel_hi:[0,1,1]
	v_pk_fma_f32 v[12:13], v[128:129], s[10:11], v[12:13] op_sel_hi:[0,1,1]
	v_pk_fma_f32 v[10:11], v[128:129], s[12:13], v[10:11] op_sel_hi:[0,1,1]
	v_readlane_b32 s6, v3, 46
	v_readlane_b32 s7, v19, 46
	v_readlane_b32 s8, v20, 46
	v_readlane_b32 s9, v21, 46
	v_readlane_b32 s10, v22, 46
	v_readlane_b32 s11, v23, 46
	v_readlane_b32 s12, v24, 46
	v_readlane_b32 s13, v25, 46
	v_pk_fma_f32 v[16:17], v[130:131], s[22:23], v[16:17] op_sel_hi:[0,1,1]
	v_pk_fma_f32 v[14:15], v[130:131], s[24:25], v[14:15] op_sel_hi:[0,1,1]
	v_pk_fma_f32 v[12:13], v[130:131], s[26:27], v[12:13] op_sel_hi:[0,1,1]
	v_pk_fma_f32 v[10:11], v[130:131], s[30:31], v[10:11] op_sel_hi:[0,1,1]
	v_readlane_b32 s22, v3, 47
	v_readlane_b32 s23, v19, 47
	v_readlane_b32 s24, v20, 47
	v_readlane_b32 s25, v21, 47
	v_readlane_b32 s26, v22, 47
	v_readlane_b32 s27, v23, 47
	v_readlane_b32 s30, v24, 47
	v_readlane_b32 s31, v25, 47
	v_pk_fma_f32 v[16:17], v[132:133], s[6:7], v[16:17] op_sel_hi:[0,1,1]
	v_pk_fma_f32 v[14:15], v[132:133], s[8:9], v[14:15] op_sel_hi:[0,1,1]
	v_pk_fma_f32 v[12:13], v[132:133], s[10:11], v[12:13] op_sel_hi:[0,1,1]
	v_pk_fma_f32 v[10:11], v[132:133], s[12:13], v[10:11] op_sel_hi:[0,1,1]
	v_readlane_b32 s6, v3, 48
	v_readlane_b32 s7, v19, 48
	v_readlane_b32 s8, v20, 48
	v_readlane_b32 s9, v21, 48
	v_readlane_b32 s10, v22, 48
	v_readlane_b32 s11, v23, 48
	v_readlane_b32 s12, v24, 48
	v_readlane_b32 s13, v25, 48
	v_pk_fma_f32 v[16:17], v[134:135], s[22:23], v[16:17] op_sel_hi:[0,1,1]
	v_pk_fma_f32 v[14:15], v[134:135], s[24:25], v[14:15] op_sel_hi:[0,1,1]
	v_pk_fma_f32 v[12:13], v[134:135], s[26:27], v[12:13] op_sel_hi:[0,1,1]
	v_pk_fma_f32 v[10:11], v[134:135], s[30:31], v[10:11] op_sel_hi:[0,1,1]
	v_readlane_b32 s22, v3, 49
	v_readlane_b32 s23, v19, 49
	v_readlane_b32 s24, v20, 49
	v_readlane_b32 s25, v21, 49
	v_readlane_b32 s26, v22, 49
	v_readlane_b32 s27, v23, 49
	v_readlane_b32 s30, v24, 49
	v_readlane_b32 s31, v25, 49
	v_pk_fma_f32 v[16:17], v[136:137], s[6:7], v[16:17] op_sel_hi:[0,1,1]
	v_pk_fma_f32 v[14:15], v[136:137], s[8:9], v[14:15] op_sel_hi:[0,1,1]
	v_pk_fma_f32 v[12:13], v[136:137], s[10:11], v[12:13] op_sel_hi:[0,1,1]
	v_pk_fma_f32 v[10:11], v[136:137], s[12:13], v[10:11] op_sel_hi:[0,1,1]
	v_readlane_b32 s6, v3, 50
	v_readlane_b32 s7, v19, 50
	v_readlane_b32 s8, v20, 50
	v_readlane_b32 s9, v21, 50
	v_readlane_b32 s10, v22, 50
	v_readlane_b32 s11, v23, 50
	v_readlane_b32 s12, v24, 50
	v_readlane_b32 s13, v25, 50
	v_pk_fma_f32 v[16:17], v[138:139], s[22:23], v[16:17] op_sel_hi:[0,1,1]
	v_pk_fma_f32 v[14:15], v[138:139], s[24:25], v[14:15] op_sel_hi:[0,1,1]
	v_pk_fma_f32 v[12:13], v[138:139], s[26:27], v[12:13] op_sel_hi:[0,1,1]
	v_pk_fma_f32 v[10:11], v[138:139], s[30:31], v[10:11] op_sel_hi:[0,1,1]
	v_readlane_b32 s22, v3, 51
	v_readlane_b32 s23, v19, 51
	v_readlane_b32 s24, v20, 51
	v_readlane_b32 s25, v21, 51
	v_readlane_b32 s26, v22, 51
	v_readlane_b32 s27, v23, 51
	v_readlane_b32 s30, v24, 51
	v_readlane_b32 s31, v25, 51
	v_pk_fma_f32 v[16:17], v[140:141], s[6:7], v[16:17] op_sel_hi:[0,1,1]
	v_pk_fma_f32 v[14:15], v[140:141], s[8:9], v[14:15] op_sel_hi:[0,1,1]
	v_pk_fma_f32 v[12:13], v[140:141], s[10:11], v[12:13] op_sel_hi:[0,1,1]
	v_pk_fma_f32 v[10:11], v[140:141], s[12:13], v[10:11] op_sel_hi:[0,1,1]
	v_readlane_b32 s6, v3, 52
	v_readlane_b32 s7, v19, 52
	v_readlane_b32 s8, v20, 52
	v_readlane_b32 s9, v21, 52
	v_readlane_b32 s10, v22, 52
	v_readlane_b32 s11, v23, 52
	v_readlane_b32 s12, v24, 52
	v_readlane_b32 s13, v25, 52
	v_pk_fma_f32 v[16:17], v[142:143], s[22:23], v[16:17] op_sel_hi:[0,1,1]
	v_pk_fma_f32 v[14:15], v[142:143], s[24:25], v[14:15] op_sel_hi:[0,1,1]
	v_pk_fma_f32 v[12:13], v[142:143], s[26:27], v[12:13] op_sel_hi:[0,1,1]
	v_pk_fma_f32 v[10:11], v[142:143], s[30:31], v[10:11] op_sel_hi:[0,1,1]
	v_readlane_b32 s22, v3, 53
	v_readlane_b32 s23, v19, 53
	v_readlane_b32 s24, v20, 53
	v_readlane_b32 s25, v21, 53
	v_readlane_b32 s26, v22, 53
	v_readlane_b32 s27, v23, 53
	v_readlane_b32 s30, v24, 53
	v_readlane_b32 s31, v25, 53
	v_pk_fma_f32 v[16:17], v[144:145], s[6:7], v[16:17] op_sel_hi:[0,1,1]
	v_pk_fma_f32 v[14:15], v[144:145], s[8:9], v[14:15] op_sel_hi:[0,1,1]
	v_pk_fma_f32 v[12:13], v[144:145], s[10:11], v[12:13] op_sel_hi:[0,1,1]
	v_pk_fma_f32 v[10:11], v[144:145], s[12:13], v[10:11] op_sel_hi:[0,1,1]
	v_readlane_b32 s6, v3, 54
	v_readlane_b32 s7, v19, 54
	v_readlane_b32 s8, v20, 54
	v_readlane_b32 s9, v21, 54
	v_readlane_b32 s10, v22, 54
	v_readlane_b32 s11, v23, 54
	v_readlane_b32 s12, v24, 54
	v_readlane_b32 s13, v25, 54
	v_pk_fma_f32 v[16:17], v[146:147], s[22:23], v[16:17] op_sel_hi:[0,1,1]
	v_pk_fma_f32 v[14:15], v[146:147], s[24:25], v[14:15] op_sel_hi:[0,1,1]
	v_pk_fma_f32 v[12:13], v[146:147], s[26:27], v[12:13] op_sel_hi:[0,1,1]
	v_pk_fma_f32 v[10:11], v[146:147], s[30:31], v[10:11] op_sel_hi:[0,1,1]
	v_readlane_b32 s22, v3, 55
	v_readlane_b32 s23, v19, 55
	v_readlane_b32 s24, v20, 55
	v_readlane_b32 s25, v21, 55
	v_readlane_b32 s26, v22, 55
	v_readlane_b32 s27, v23, 55
	v_readlane_b32 s30, v24, 55
	v_readlane_b32 s31, v25, 55
	v_pk_fma_f32 v[16:17], v[148:149], s[6:7], v[16:17] op_sel_hi:[0,1,1]
	v_pk_fma_f32 v[14:15], v[148:149], s[8:9], v[14:15] op_sel_hi:[0,1,1]
	v_pk_fma_f32 v[12:13], v[148:149], s[10:11], v[12:13] op_sel_hi:[0,1,1]
	v_pk_fma_f32 v[10:11], v[148:149], s[12:13], v[10:11] op_sel_hi:[0,1,1]
	v_readlane_b32 s6, v3, 56
	v_readlane_b32 s7, v19, 56
	v_readlane_b32 s8, v20, 56
	v_readlane_b32 s9, v21, 56
	v_readlane_b32 s10, v22, 56
	v_readlane_b32 s11, v23, 56
	v_readlane_b32 s12, v24, 56
	v_readlane_b32 s13, v25, 56
	v_pk_fma_f32 v[16:17], v[150:151], s[22:23], v[16:17] op_sel_hi:[0,1,1]
	v_pk_fma_f32 v[14:15], v[150:151], s[24:25], v[14:15] op_sel_hi:[0,1,1]
	v_pk_fma_f32 v[12:13], v[150:151], s[26:27], v[12:13] op_sel_hi:[0,1,1]
	v_pk_fma_f32 v[10:11], v[150:151], s[30:31], v[10:11] op_sel_hi:[0,1,1]
	v_readlane_b32 s22, v3, 57
	v_readlane_b32 s23, v19, 57
	v_readlane_b32 s24, v20, 57
	v_readlane_b32 s25, v21, 57
	v_readlane_b32 s26, v22, 57
	v_readlane_b32 s27, v23, 57
	v_readlane_b32 s30, v24, 57
	v_readlane_b32 s31, v25, 57
	v_pk_fma_f32 v[16:17], v[152:153], s[6:7], v[16:17] op_sel_hi:[0,1,1]
	v_pk_fma_f32 v[14:15], v[152:153], s[8:9], v[14:15] op_sel_hi:[0,1,1]
	v_pk_fma_f32 v[12:13], v[152:153], s[10:11], v[12:13] op_sel_hi:[0,1,1]
	v_pk_fma_f32 v[10:11], v[152:153], s[12:13], v[10:11] op_sel_hi:[0,1,1]
	v_readlane_b32 s6, v3, 58
	v_readlane_b32 s7, v19, 58
	v_readlane_b32 s8, v20, 58
	v_readlane_b32 s9, v21, 58
	v_readlane_b32 s10, v22, 58
	v_readlane_b32 s11, v23, 58
	v_readlane_b32 s12, v24, 58
	v_readlane_b32 s13, v25, 58
	v_pk_fma_f32 v[16:17], v[154:155], s[22:23], v[16:17] op_sel_hi:[0,1,1]
	v_pk_fma_f32 v[14:15], v[154:155], s[24:25], v[14:15] op_sel_hi:[0,1,1]
	v_pk_fma_f32 v[12:13], v[154:155], s[26:27], v[12:13] op_sel_hi:[0,1,1]
	v_pk_fma_f32 v[10:11], v[154:155], s[30:31], v[10:11] op_sel_hi:[0,1,1]
	v_readlane_b32 s22, v3, 59
	v_readlane_b32 s23, v19, 59
	v_readlane_b32 s24, v20, 59
	v_readlane_b32 s25, v21, 59
	v_readlane_b32 s26, v22, 59
	v_readlane_b32 s27, v23, 59
	v_readlane_b32 s30, v24, 59
	v_readlane_b32 s31, v25, 59
	v_pk_fma_f32 v[16:17], v[156:157], s[6:7], v[16:17] op_sel_hi:[0,1,1]
	v_pk_fma_f32 v[14:15], v[156:157], s[8:9], v[14:15] op_sel_hi:[0,1,1]
	v_pk_fma_f32 v[12:13], v[156:157], s[10:11], v[12:13] op_sel_hi:[0,1,1]
	v_pk_fma_f32 v[10:11], v[156:157], s[12:13], v[10:11] op_sel_hi:[0,1,1]
	v_readlane_b32 s6, v3, 60
	v_readlane_b32 s7, v19, 60
	v_readlane_b32 s8, v20, 60
	v_readlane_b32 s9, v21, 60
	v_readlane_b32 s10, v22, 60
	v_readlane_b32 s11, v23, 60
	v_readlane_b32 s12, v24, 60
	v_readlane_b32 s13, v25, 60
	v_pk_fma_f32 v[16:17], v[158:159], s[22:23], v[16:17] op_sel_hi:[0,1,1]
	v_pk_fma_f32 v[14:15], v[158:159], s[24:25], v[14:15] op_sel_hi:[0,1,1]
	v_pk_fma_f32 v[12:13], v[158:159], s[26:27], v[12:13] op_sel_hi:[0,1,1]
	v_pk_fma_f32 v[10:11], v[158:159], s[30:31], v[10:11] op_sel_hi:[0,1,1]
	v_readlane_b32 s22, v3, 61
	v_readlane_b32 s23, v19, 61
	v_readlane_b32 s24, v20, 61
	v_readlane_b32 s25, v21, 61
	v_readlane_b32 s26, v22, 61
	v_readlane_b32 s27, v23, 61
	v_readlane_b32 s30, v24, 61
	v_readlane_b32 s31, v25, 61
	v_pk_fma_f32 v[16:17], v[164:165], s[6:7], v[16:17] op_sel_hi:[0,1,1]
	v_pk_fma_f32 v[14:15], v[164:165], s[8:9], v[14:15] op_sel_hi:[0,1,1]
	v_pk_fma_f32 v[12:13], v[164:165], s[10:11], v[12:13] op_sel_hi:[0,1,1]
	v_pk_fma_f32 v[10:11], v[164:165], s[12:13], v[10:11] op_sel_hi:[0,1,1]
	v_readlane_b32 s6, v3, 62
	v_readlane_b32 s7, v19, 62
	v_readlane_b32 s8, v20, 62
	v_readlane_b32 s9, v21, 62
	v_readlane_b32 s10, v22, 62
	v_readlane_b32 s11, v23, 62
	v_readlane_b32 s12, v24, 62
	v_readlane_b32 s13, v25, 62
	v_pk_fma_f32 v[16:17], v[166:167], s[22:23], v[16:17] op_sel_hi:[0,1,1]
	v_pk_fma_f32 v[14:15], v[166:167], s[24:25], v[14:15] op_sel_hi:[0,1,1]
	v_pk_fma_f32 v[12:13], v[166:167], s[26:27], v[12:13] op_sel_hi:[0,1,1]
	v_pk_fma_f32 v[10:11], v[166:167], s[30:31], v[10:11] op_sel_hi:[0,1,1]
	v_readlane_b32 s22, v3, 63
	v_readlane_b32 s23, v19, 63
	v_readlane_b32 s24, v20, 63
	v_readlane_b32 s25, v21, 63
	v_readlane_b32 s26, v22, 63
	v_readlane_b32 s27, v23, 63
	v_readlane_b32 s30, v24, 63
	v_readlane_b32 s31, v25, 63
	v_pk_fma_f32 v[16:17], v[168:169], s[6:7], v[16:17] op_sel_hi:[0,1,1]
	v_pk_fma_f32 v[14:15], v[168:169], s[8:9], v[14:15] op_sel_hi:[0,1,1]
	v_pk_fma_f32 v[12:13], v[168:169], s[10:11], v[12:13] op_sel_hi:[0,1,1]
	v_pk_fma_f32 v[10:11], v[168:169], s[12:13], v[10:11] op_sel_hi:[0,1,1]
	v_pk_fma_f32 v[16:17], v[170:171], s[22:23], v[16:17] op_sel_hi:[0,1,1]
	v_pk_fma_f32 v[14:15], v[170:171], s[24:25], v[14:15] op_sel_hi:[0,1,1]
	v_pk_fma_f32 v[12:13], v[170:171], s[26:27], v[12:13] op_sel_hi:[0,1,1]
	v_pk_fma_f32 v[10:11], v[170:171], s[30:31], v[10:11] op_sel_hi:[0,1,1]
	v_lshl_add_u64 v[8:9], v[8:9], 0, s[16:17]
	global_load_dword v40, v[8:9], off
	v_lshl_add_u64 v[8:9], v[8:9], 0, s[14:15]
	global_load_dword v42, v[8:9], off
	v_lshl_add_u64 v[8:9], v[8:9], 0, s[14:15]
	global_load_dword v44, v[8:9], off
	v_lshl_add_u64 v[8:9], v[8:9], 0, s[14:15]
	global_load_dword v46, v[8:9], off
	v_lshl_add_u64 v[8:9], v[8:9], 0, s[14:15]
	global_load_dword v48, v[8:9], off
	v_lshl_add_u64 v[8:9], v[8:9], 0, s[14:15]
	global_load_dword v50, v[8:9], off
	v_lshl_add_u64 v[8:9], v[8:9], 0, s[14:15]
	global_load_dword v52, v[8:9], off
	v_lshl_add_u64 v[8:9], v[8:9], 0, s[14:15]
	global_load_dword v54, v[8:9], off
	v_lshl_add_u64 v[8:9], v[8:9], 0, s[14:15]
	global_load_dword v56, v[8:9], off
	v_lshl_add_u64 v[8:9], v[8:9], 0, s[14:15]
	global_load_dword v58, v[8:9], off
	v_lshl_add_u64 v[8:9], v[8:9], 0, s[14:15]
	global_load_dword v60, v[8:9], off
	v_lshl_add_u64 v[8:9], v[8:9], 0, s[14:15]
	global_load_dword v62, v[8:9], off
	v_lshl_add_u64 v[8:9], v[8:9], 0, s[14:15]
	global_load_dword v64, v[8:9], off
	v_lshl_add_u64 v[8:9], v[8:9], 0, s[14:15]
	global_load_dword v66, v[8:9], off
	v_lshl_add_u64 v[8:9], v[8:9], 0, s[14:15]
	global_load_dword v68, v[8:9], off
	v_lshl_add_u64 v[8:9], v[8:9], 0, s[14:15]
	global_load_dword v70, v[8:9], off
	v_lshl_add_u64 v[8:9], v[8:9], 0, s[14:15]
	global_load_dword v72, v[8:9], off
	v_lshl_add_u64 v[8:9], v[8:9], 0, s[14:15]
	global_load_dword v74, v[8:9], off
	v_lshl_add_u64 v[8:9], v[8:9], 0, s[14:15]
	global_load_dword v76, v[8:9], off
	v_lshl_add_u64 v[8:9], v[8:9], 0, s[14:15]
	global_load_dword v78, v[8:9], off
	v_lshl_add_u64 v[8:9], v[8:9], 0, s[14:15]
	global_load_dword v80, v[8:9], off
	v_lshl_add_u64 v[8:9], v[8:9], 0, s[14:15]
	global_load_dword v82, v[8:9], off
	v_lshl_add_u64 v[8:9], v[8:9], 0, s[14:15]
	global_load_dword v84, v[8:9], off
	v_lshl_add_u64 v[8:9], v[8:9], 0, s[14:15]
	global_load_dword v86, v[8:9], off
	v_lshl_add_u64 v[8:9], v[8:9], 0, s[14:15]
	global_load_dword v88, v[8:9], off
	v_lshl_add_u64 v[8:9], v[8:9], 0, s[14:15]
	global_load_dword v90, v[8:9], off
	v_lshl_add_u64 v[8:9], v[8:9], 0, s[14:15]
	global_load_dword v92, v[8:9], off
	v_lshl_add_u64 v[8:9], v[8:9], 0, s[14:15]
	global_load_dword v94, v[8:9], off
	v_lshl_add_u64 v[8:9], v[8:9], 0, s[14:15]
	global_load_dword v96, v[8:9], off
	v_lshl_add_u64 v[8:9], v[8:9], 0, s[14:15]
	global_load_dword v98, v[8:9], off
	v_lshl_add_u64 v[8:9], v[8:9], 0, s[14:15]
	global_load_dword v100, v[8:9], off
	v_lshl_add_u64 v[8:9], v[8:9], 0, s[14:15]
	global_load_dword v102, v[8:9], off
	v_lshl_add_u64 v[8:9], v[8:9], 0, s[14:15]
	global_load_dword v104, v[8:9], off
	v_lshl_add_u64 v[8:9], v[8:9], 0, s[14:15]
	global_load_dword v106, v[8:9], off
	v_lshl_add_u64 v[8:9], v[8:9], 0, s[14:15]
	global_load_dword v108, v[8:9], off
	v_lshl_add_u64 v[8:9], v[8:9], 0, s[14:15]
	global_load_dword v110, v[8:9], off
	v_lshl_add_u64 v[8:9], v[8:9], 0, s[14:15]
	global_load_dword v112, v[8:9], off
	v_lshl_add_u64 v[8:9], v[8:9], 0, s[14:15]
	global_load_dword v114, v[8:9], off
	v_lshl_add_u64 v[8:9], v[8:9], 0, s[14:15]
	global_load_dword v116, v[8:9], off
	v_lshl_add_u64 v[8:9], v[8:9], 0, s[14:15]
	global_load_dword v118, v[8:9], off
	v_lshl_add_u64 v[8:9], v[8:9], 0, s[14:15]
	global_load_dword v120, v[8:9], off
	v_lshl_add_u64 v[8:9], v[8:9], 0, s[14:15]
	global_load_dword v122, v[8:9], off
	v_lshl_add_u64 v[8:9], v[8:9], 0, s[14:15]
	global_load_dword v124, v[8:9], off
	v_lshl_add_u64 v[8:9], v[8:9], 0, s[14:15]
	global_load_dword v126, v[8:9], off
	v_lshl_add_u64 v[8:9], v[8:9], 0, s[14:15]
	global_load_dword v128, v[8:9], off
	v_lshl_add_u64 v[8:9], v[8:9], 0, s[14:15]
	global_load_dword v130, v[8:9], off
	v_lshl_add_u64 v[8:9], v[8:9], 0, s[14:15]
	global_load_dword v132, v[8:9], off
	v_lshl_add_u64 v[8:9], v[8:9], 0, s[14:15]
	global_load_dword v134, v[8:9], off
	v_lshl_add_u64 v[8:9], v[8:9], 0, s[14:15]
	global_load_dword v136, v[8:9], off
	v_lshl_add_u64 v[8:9], v[8:9], 0, s[14:15]
	global_load_dword v138, v[8:9], off
	v_lshl_add_u64 v[8:9], v[8:9], 0, s[14:15]
	global_load_dword v140, v[8:9], off
	v_lshl_add_u64 v[8:9], v[8:9], 0, s[14:15]
	global_load_dword v142, v[8:9], off
	v_lshl_add_u64 v[8:9], v[8:9], 0, s[14:15]
	global_load_dword v144, v[8:9], off
	v_lshl_add_u64 v[8:9], v[8:9], 0, s[14:15]
	global_load_dword v146, v[8:9], off
	v_lshl_add_u64 v[8:9], v[8:9], 0, s[14:15]
	global_load_dword v148, v[8:9], off
	v_lshl_add_u64 v[8:9], v[8:9], 0, s[14:15]
	global_load_dword v150, v[8:9], off
	v_lshl_add_u64 v[8:9], v[8:9], 0, s[14:15]
	global_load_dword v152, v[8:9], off
	v_lshl_add_u64 v[8:9], v[8:9], 0, s[14:15]
	global_load_dword v154, v[8:9], off
	v_lshl_add_u64 v[8:9], v[8:9], 0, s[14:15]
	global_load_dword v156, v[8:9], off
	v_lshl_add_u64 v[8:9], v[8:9], 0, s[14:15]
	global_load_dword v158, v[8:9], off
	v_lshl_add_u64 v[8:9], v[8:9], 0, s[14:15]
	global_load_dword v164, v[8:9], off
	v_lshl_add_u64 v[8:9], v[8:9], 0, s[14:15]
	global_load_dword v166, v[8:9], off
	v_lshl_add_u64 v[8:9], v[8:9], 0, s[14:15]
	global_load_dword v168, v[8:9], off
	v_lshl_add_u64 v[8:9], v[8:9], 0, s[14:15]
	global_load_dword v170, v[8:9], off
	s_waitcnt vmcnt(63)
	v_readlane_b32 s6, v26, 0
	v_readlane_b32 s7, v27, 0
	v_readlane_b32 s8, v28, 0
	v_readlane_b32 s9, v29, 0
	v_readlane_b32 s10, v30, 0
	v_readlane_b32 s11, v31, 0
	v_readlane_b32 s12, v32, 0
	v_readlane_b32 s13, v33, 0
	v_readlane_b32 s22, v26, 1
	v_readlane_b32 s23, v27, 1
	v_readlane_b32 s24, v28, 1
	v_readlane_b32 s25, v29, 1
	v_readlane_b32 s26, v30, 1
	v_readlane_b32 s27, v31, 1
	v_readlane_b32 s30, v32, 1
	v_readlane_b32 s31, v33, 1
	v_pk_fma_f32 v[16:17], v[40:41], s[6:7], v[16:17] op_sel:[1,0,0] op_sel_hi:[1,1,1]
	v_pk_fma_f32 v[14:15], v[40:41], s[8:9], v[14:15] op_sel:[1,0,0] op_sel_hi:[1,1,1]
	v_pk_fma_f32 v[12:13], v[40:41], s[10:11], v[12:13] op_sel:[1,0,0] op_sel_hi:[1,1,1]
	v_pk_fma_f32 v[10:11], v[40:41], s[12:13], v[10:11] op_sel:[1,0,0] op_sel_hi:[1,1,1]
	v_readlane_b32 s6, v26, 2
	v_readlane_b32 s7, v27, 2
	v_readlane_b32 s8, v28, 2
	v_readlane_b32 s9, v29, 2
	v_readlane_b32 s10, v30, 2
	v_readlane_b32 s11, v31, 2
	v_readlane_b32 s12, v32, 2
	v_readlane_b32 s13, v33, 2
	v_pk_fma_f32 v[16:17], v[42:43], s[22:23], v[16:17] op_sel:[1,0,0] op_sel_hi:[1,1,1]
	v_pk_fma_f32 v[14:15], v[42:43], s[24:25], v[14:15] op_sel:[1,0,0] op_sel_hi:[1,1,1]
	v_pk_fma_f32 v[12:13], v[42:43], s[26:27], v[12:13] op_sel:[1,0,0] op_sel_hi:[1,1,1]
	v_pk_fma_f32 v[10:11], v[42:43], s[30:31], v[10:11] op_sel:[1,0,0] op_sel_hi:[1,1,1]
	v_readlane_b32 s22, v26, 3
	v_readlane_b32 s23, v27, 3
	v_readlane_b32 s24, v28, 3
	v_readlane_b32 s25, v29, 3
	v_readlane_b32 s26, v30, 3
	v_readlane_b32 s27, v31, 3
	v_readlane_b32 s30, v32, 3
	v_readlane_b32 s31, v33, 3
	v_pk_fma_f32 v[16:17], v[44:45], s[6:7], v[16:17] op_sel:[1,0,0] op_sel_hi:[1,1,1]
	v_pk_fma_f32 v[14:15], v[44:45], s[8:9], v[14:15] op_sel:[1,0,0] op_sel_hi:[1,1,1]
	v_pk_fma_f32 v[12:13], v[44:45], s[10:11], v[12:13] op_sel:[1,0,0] op_sel_hi:[1,1,1]
	v_pk_fma_f32 v[10:11], v[44:45], s[12:13], v[10:11] op_sel:[1,0,0] op_sel_hi:[1,1,1]
	v_readlane_b32 s6, v26, 4
	v_readlane_b32 s7, v27, 4
	v_readlane_b32 s8, v28, 4
	v_readlane_b32 s9, v29, 4
	v_readlane_b32 s10, v30, 4
	v_readlane_b32 s11, v31, 4
	v_readlane_b32 s12, v32, 4
	v_readlane_b32 s13, v33, 4
	v_pk_fma_f32 v[16:17], v[46:47], s[22:23], v[16:17] op_sel:[1,0,0] op_sel_hi:[1,1,1]
	v_pk_fma_f32 v[14:15], v[46:47], s[24:25], v[14:15] op_sel:[1,0,0] op_sel_hi:[1,1,1]
	v_pk_fma_f32 v[12:13], v[46:47], s[26:27], v[12:13] op_sel:[1,0,0] op_sel_hi:[1,1,1]
	v_pk_fma_f32 v[10:11], v[46:47], s[30:31], v[10:11] op_sel:[1,0,0] op_sel_hi:[1,1,1]
	v_readlane_b32 s22, v26, 5
	v_readlane_b32 s23, v27, 5
	v_readlane_b32 s24, v28, 5
	v_readlane_b32 s25, v29, 5
	v_readlane_b32 s26, v30, 5
	v_readlane_b32 s27, v31, 5
	v_readlane_b32 s30, v32, 5
	v_readlane_b32 s31, v33, 5
	v_pk_fma_f32 v[16:17], v[48:49], s[6:7], v[16:17] op_sel:[1,0,0] op_sel_hi:[1,1,1]
	v_pk_fma_f32 v[14:15], v[48:49], s[8:9], v[14:15] op_sel:[1,0,0] op_sel_hi:[1,1,1]
	v_pk_fma_f32 v[12:13], v[48:49], s[10:11], v[12:13] op_sel:[1,0,0] op_sel_hi:[1,1,1]
	v_pk_fma_f32 v[10:11], v[48:49], s[12:13], v[10:11] op_sel:[1,0,0] op_sel_hi:[1,1,1]
	v_readlane_b32 s6, v26, 6
	v_readlane_b32 s7, v27, 6
	v_readlane_b32 s8, v28, 6
	v_readlane_b32 s9, v29, 6
	v_readlane_b32 s10, v30, 6
	v_readlane_b32 s11, v31, 6
	v_readlane_b32 s12, v32, 6
	v_readlane_b32 s13, v33, 6
	v_pk_fma_f32 v[16:17], v[50:51], s[22:23], v[16:17] op_sel:[1,0,0] op_sel_hi:[1,1,1]
	v_pk_fma_f32 v[14:15], v[50:51], s[24:25], v[14:15] op_sel:[1,0,0] op_sel_hi:[1,1,1]
	v_pk_fma_f32 v[12:13], v[50:51], s[26:27], v[12:13] op_sel:[1,0,0] op_sel_hi:[1,1,1]
	v_pk_fma_f32 v[10:11], v[50:51], s[30:31], v[10:11] op_sel:[1,0,0] op_sel_hi:[1,1,1]
	v_readlane_b32 s22, v26, 7
	v_readlane_b32 s23, v27, 7
	v_readlane_b32 s24, v28, 7
	v_readlane_b32 s25, v29, 7
	v_readlane_b32 s26, v30, 7
	v_readlane_b32 s27, v31, 7
	v_readlane_b32 s30, v32, 7
	v_readlane_b32 s31, v33, 7
	v_pk_fma_f32 v[16:17], v[52:53], s[6:7], v[16:17] op_sel:[1,0,0] op_sel_hi:[1,1,1]
	v_pk_fma_f32 v[14:15], v[52:53], s[8:9], v[14:15] op_sel:[1,0,0] op_sel_hi:[1,1,1]
	v_pk_fma_f32 v[12:13], v[52:53], s[10:11], v[12:13] op_sel:[1,0,0] op_sel_hi:[1,1,1]
	v_pk_fma_f32 v[10:11], v[52:53], s[12:13], v[10:11] op_sel:[1,0,0] op_sel_hi:[1,1,1]
	v_readlane_b32 s6, v26, 8
	v_readlane_b32 s7, v27, 8
	v_readlane_b32 s8, v28, 8
	v_readlane_b32 s9, v29, 8
	v_readlane_b32 s10, v30, 8
	v_readlane_b32 s11, v31, 8
	v_readlane_b32 s12, v32, 8
	v_readlane_b32 s13, v33, 8
	v_pk_fma_f32 v[16:17], v[54:55], s[22:23], v[16:17] op_sel:[1,0,0] op_sel_hi:[1,1,1]
	v_pk_fma_f32 v[14:15], v[54:55], s[24:25], v[14:15] op_sel:[1,0,0] op_sel_hi:[1,1,1]
	v_pk_fma_f32 v[12:13], v[54:55], s[26:27], v[12:13] op_sel:[1,0,0] op_sel_hi:[1,1,1]
	v_pk_fma_f32 v[10:11], v[54:55], s[30:31], v[10:11] op_sel:[1,0,0] op_sel_hi:[1,1,1]
	v_readlane_b32 s22, v26, 9
	v_readlane_b32 s23, v27, 9
	v_readlane_b32 s24, v28, 9
	v_readlane_b32 s25, v29, 9
	v_readlane_b32 s26, v30, 9
	v_readlane_b32 s27, v31, 9
	v_readlane_b32 s30, v32, 9
	v_readlane_b32 s31, v33, 9
	v_pk_fma_f32 v[16:17], v[56:57], s[6:7], v[16:17] op_sel:[1,0,0] op_sel_hi:[1,1,1]
	v_pk_fma_f32 v[14:15], v[56:57], s[8:9], v[14:15] op_sel:[1,0,0] op_sel_hi:[1,1,1]
	v_pk_fma_f32 v[12:13], v[56:57], s[10:11], v[12:13] op_sel:[1,0,0] op_sel_hi:[1,1,1]
	v_pk_fma_f32 v[10:11], v[56:57], s[12:13], v[10:11] op_sel:[1,0,0] op_sel_hi:[1,1,1]
	v_readlane_b32 s6, v26, 10
	v_readlane_b32 s7, v27, 10
	v_readlane_b32 s8, v28, 10
	v_readlane_b32 s9, v29, 10
	v_readlane_b32 s10, v30, 10
	v_readlane_b32 s11, v31, 10
	v_readlane_b32 s12, v32, 10
	v_readlane_b32 s13, v33, 10
	v_pk_fma_f32 v[16:17], v[58:59], s[22:23], v[16:17] op_sel:[1,0,0] op_sel_hi:[1,1,1]
	v_pk_fma_f32 v[14:15], v[58:59], s[24:25], v[14:15] op_sel:[1,0,0] op_sel_hi:[1,1,1]
	v_pk_fma_f32 v[12:13], v[58:59], s[26:27], v[12:13] op_sel:[1,0,0] op_sel_hi:[1,1,1]
	v_pk_fma_f32 v[10:11], v[58:59], s[30:31], v[10:11] op_sel:[1,0,0] op_sel_hi:[1,1,1]
	v_readlane_b32 s22, v26, 11
	v_readlane_b32 s23, v27, 11
	v_readlane_b32 s24, v28, 11
	v_readlane_b32 s25, v29, 11
	v_readlane_b32 s26, v30, 11
	v_readlane_b32 s27, v31, 11
	v_readlane_b32 s30, v32, 11
	v_readlane_b32 s31, v33, 11
	v_pk_fma_f32 v[16:17], v[60:61], s[6:7], v[16:17] op_sel:[1,0,0] op_sel_hi:[1,1,1]
	v_pk_fma_f32 v[14:15], v[60:61], s[8:9], v[14:15] op_sel:[1,0,0] op_sel_hi:[1,1,1]
	v_pk_fma_f32 v[12:13], v[60:61], s[10:11], v[12:13] op_sel:[1,0,0] op_sel_hi:[1,1,1]
	v_pk_fma_f32 v[10:11], v[60:61], s[12:13], v[10:11] op_sel:[1,0,0] op_sel_hi:[1,1,1]
	v_readlane_b32 s6, v26, 12
	v_readlane_b32 s7, v27, 12
	v_readlane_b32 s8, v28, 12
	v_readlane_b32 s9, v29, 12
	v_readlane_b32 s10, v30, 12
	v_readlane_b32 s11, v31, 12
	v_readlane_b32 s12, v32, 12
	v_readlane_b32 s13, v33, 12
	v_pk_fma_f32 v[16:17], v[62:63], s[22:23], v[16:17] op_sel:[1,0,0] op_sel_hi:[1,1,1]
	v_pk_fma_f32 v[14:15], v[62:63], s[24:25], v[14:15] op_sel:[1,0,0] op_sel_hi:[1,1,1]
	v_pk_fma_f32 v[12:13], v[62:63], s[26:27], v[12:13] op_sel:[1,0,0] op_sel_hi:[1,1,1]
	v_pk_fma_f32 v[10:11], v[62:63], s[30:31], v[10:11] op_sel:[1,0,0] op_sel_hi:[1,1,1]
	v_readlane_b32 s22, v26, 13
	v_readlane_b32 s23, v27, 13
	v_readlane_b32 s24, v28, 13
	v_readlane_b32 s25, v29, 13
	v_readlane_b32 s26, v30, 13
	v_readlane_b32 s27, v31, 13
	v_readlane_b32 s30, v32, 13
	v_readlane_b32 s31, v33, 13
	v_pk_fma_f32 v[16:17], v[64:65], s[6:7], v[16:17] op_sel:[1,0,0] op_sel_hi:[1,1,1]
	v_pk_fma_f32 v[14:15], v[64:65], s[8:9], v[14:15] op_sel:[1,0,0] op_sel_hi:[1,1,1]
	v_pk_fma_f32 v[12:13], v[64:65], s[10:11], v[12:13] op_sel:[1,0,0] op_sel_hi:[1,1,1]
	v_pk_fma_f32 v[10:11], v[64:65], s[12:13], v[10:11] op_sel:[1,0,0] op_sel_hi:[1,1,1]
	v_readlane_b32 s6, v26, 14
	v_readlane_b32 s7, v27, 14
	v_readlane_b32 s8, v28, 14
	v_readlane_b32 s9, v29, 14
	v_readlane_b32 s10, v30, 14
	v_readlane_b32 s11, v31, 14
	v_readlane_b32 s12, v32, 14
	v_readlane_b32 s13, v33, 14
	v_pk_fma_f32 v[16:17], v[66:67], s[22:23], v[16:17] op_sel:[1,0,0] op_sel_hi:[1,1,1]
	v_pk_fma_f32 v[14:15], v[66:67], s[24:25], v[14:15] op_sel:[1,0,0] op_sel_hi:[1,1,1]
	v_pk_fma_f32 v[12:13], v[66:67], s[26:27], v[12:13] op_sel:[1,0,0] op_sel_hi:[1,1,1]
	v_pk_fma_f32 v[10:11], v[66:67], s[30:31], v[10:11] op_sel:[1,0,0] op_sel_hi:[1,1,1]
	v_readlane_b32 s22, v26, 15
	v_readlane_b32 s23, v27, 15
	v_readlane_b32 s24, v28, 15
	v_readlane_b32 s25, v29, 15
	v_readlane_b32 s26, v30, 15
	v_readlane_b32 s27, v31, 15
	v_readlane_b32 s30, v32, 15
	v_readlane_b32 s31, v33, 15
	v_pk_fma_f32 v[16:17], v[68:69], s[6:7], v[16:17] op_sel:[1,0,0] op_sel_hi:[1,1,1]
	v_pk_fma_f32 v[14:15], v[68:69], s[8:9], v[14:15] op_sel:[1,0,0] op_sel_hi:[1,1,1]
	v_pk_fma_f32 v[12:13], v[68:69], s[10:11], v[12:13] op_sel:[1,0,0] op_sel_hi:[1,1,1]
	v_pk_fma_f32 v[10:11], v[68:69], s[12:13], v[10:11] op_sel:[1,0,0] op_sel_hi:[1,1,1]
	v_readlane_b32 s6, v26, 16
	v_readlane_b32 s7, v27, 16
	v_readlane_b32 s8, v28, 16
	v_readlane_b32 s9, v29, 16
	v_readlane_b32 s10, v30, 16
	v_readlane_b32 s11, v31, 16
	v_readlane_b32 s12, v32, 16
	v_readlane_b32 s13, v33, 16
	v_pk_fma_f32 v[16:17], v[70:71], s[22:23], v[16:17] op_sel:[1,0,0] op_sel_hi:[1,1,1]
	v_pk_fma_f32 v[14:15], v[70:71], s[24:25], v[14:15] op_sel:[1,0,0] op_sel_hi:[1,1,1]
	v_pk_fma_f32 v[12:13], v[70:71], s[26:27], v[12:13] op_sel:[1,0,0] op_sel_hi:[1,1,1]
	v_pk_fma_f32 v[10:11], v[70:71], s[30:31], v[10:11] op_sel:[1,0,0] op_sel_hi:[1,1,1]
	v_readlane_b32 s22, v26, 17
	v_readlane_b32 s23, v27, 17
	v_readlane_b32 s24, v28, 17
	v_readlane_b32 s25, v29, 17
	v_readlane_b32 s26, v30, 17
	v_readlane_b32 s27, v31, 17
	v_readlane_b32 s30, v32, 17
	v_readlane_b32 s31, v33, 17
	v_pk_fma_f32 v[16:17], v[72:73], s[6:7], v[16:17] op_sel:[1,0,0] op_sel_hi:[1,1,1]
	v_pk_fma_f32 v[14:15], v[72:73], s[8:9], v[14:15] op_sel:[1,0,0] op_sel_hi:[1,1,1]
	v_pk_fma_f32 v[12:13], v[72:73], s[10:11], v[12:13] op_sel:[1,0,0] op_sel_hi:[1,1,1]
	v_pk_fma_f32 v[10:11], v[72:73], s[12:13], v[10:11] op_sel:[1,0,0] op_sel_hi:[1,1,1]
	v_readlane_b32 s6, v26, 18
	v_readlane_b32 s7, v27, 18
	v_readlane_b32 s8, v28, 18
	v_readlane_b32 s9, v29, 18
	v_readlane_b32 s10, v30, 18
	v_readlane_b32 s11, v31, 18
	v_readlane_b32 s12, v32, 18
	v_readlane_b32 s13, v33, 18
	v_pk_fma_f32 v[16:17], v[74:75], s[22:23], v[16:17] op_sel:[1,0,0] op_sel_hi:[1,1,1]
	v_pk_fma_f32 v[14:15], v[74:75], s[24:25], v[14:15] op_sel:[1,0,0] op_sel_hi:[1,1,1]
	v_pk_fma_f32 v[12:13], v[74:75], s[26:27], v[12:13] op_sel:[1,0,0] op_sel_hi:[1,1,1]
	v_pk_fma_f32 v[10:11], v[74:75], s[30:31], v[10:11] op_sel:[1,0,0] op_sel_hi:[1,1,1]
	v_readlane_b32 s22, v26, 19
	v_readlane_b32 s23, v27, 19
	v_readlane_b32 s24, v28, 19
	v_readlane_b32 s25, v29, 19
	v_readlane_b32 s26, v30, 19
	v_readlane_b32 s27, v31, 19
	v_readlane_b32 s30, v32, 19
	v_readlane_b32 s31, v33, 19
	v_pk_fma_f32 v[16:17], v[76:77], s[6:7], v[16:17] op_sel:[1,0,0] op_sel_hi:[1,1,1]
	v_pk_fma_f32 v[14:15], v[76:77], s[8:9], v[14:15] op_sel:[1,0,0] op_sel_hi:[1,1,1]
	v_pk_fma_f32 v[12:13], v[76:77], s[10:11], v[12:13] op_sel:[1,0,0] op_sel_hi:[1,1,1]
	v_pk_fma_f32 v[10:11], v[76:77], s[12:13], v[10:11] op_sel:[1,0,0] op_sel_hi:[1,1,1]
	v_readlane_b32 s6, v26, 20
	v_readlane_b32 s7, v27, 20
	v_readlane_b32 s8, v28, 20
	v_readlane_b32 s9, v29, 20
	v_readlane_b32 s10, v30, 20
	v_readlane_b32 s11, v31, 20
	v_readlane_b32 s12, v32, 20
	v_readlane_b32 s13, v33, 20
	v_pk_fma_f32 v[16:17], v[78:79], s[22:23], v[16:17] op_sel:[1,0,0] op_sel_hi:[1,1,1]
	v_pk_fma_f32 v[14:15], v[78:79], s[24:25], v[14:15] op_sel:[1,0,0] op_sel_hi:[1,1,1]
	v_pk_fma_f32 v[12:13], v[78:79], s[26:27], v[12:13] op_sel:[1,0,0] op_sel_hi:[1,1,1]
	v_pk_fma_f32 v[10:11], v[78:79], s[30:31], v[10:11] op_sel:[1,0,0] op_sel_hi:[1,1,1]
	v_readlane_b32 s22, v26, 21
	v_readlane_b32 s23, v27, 21
	v_readlane_b32 s24, v28, 21
	v_readlane_b32 s25, v29, 21
	v_readlane_b32 s26, v30, 21
	v_readlane_b32 s27, v31, 21
	v_readlane_b32 s30, v32, 21
	v_readlane_b32 s31, v33, 21
	v_pk_fma_f32 v[16:17], v[80:81], s[6:7], v[16:17] op_sel:[1,0,0] op_sel_hi:[1,1,1]
	v_pk_fma_f32 v[14:15], v[80:81], s[8:9], v[14:15] op_sel:[1,0,0] op_sel_hi:[1,1,1]
	v_pk_fma_f32 v[12:13], v[80:81], s[10:11], v[12:13] op_sel:[1,0,0] op_sel_hi:[1,1,1]
	v_pk_fma_f32 v[10:11], v[80:81], s[12:13], v[10:11] op_sel:[1,0,0] op_sel_hi:[1,1,1]
	v_readlane_b32 s6, v26, 22
	v_readlane_b32 s7, v27, 22
	v_readlane_b32 s8, v28, 22
	v_readlane_b32 s9, v29, 22
	v_readlane_b32 s10, v30, 22
	v_readlane_b32 s11, v31, 22
	v_readlane_b32 s12, v32, 22
	v_readlane_b32 s13, v33, 22
	v_pk_fma_f32 v[16:17], v[82:83], s[22:23], v[16:17] op_sel:[1,0,0] op_sel_hi:[1,1,1]
	v_pk_fma_f32 v[14:15], v[82:83], s[24:25], v[14:15] op_sel:[1,0,0] op_sel_hi:[1,1,1]
	v_pk_fma_f32 v[12:13], v[82:83], s[26:27], v[12:13] op_sel:[1,0,0] op_sel_hi:[1,1,1]
	v_pk_fma_f32 v[10:11], v[82:83], s[30:31], v[10:11] op_sel:[1,0,0] op_sel_hi:[1,1,1]
	v_readlane_b32 s22, v26, 23
	v_readlane_b32 s23, v27, 23
	v_readlane_b32 s24, v28, 23
	v_readlane_b32 s25, v29, 23
	v_readlane_b32 s26, v30, 23
	v_readlane_b32 s27, v31, 23
	v_readlane_b32 s30, v32, 23
	v_readlane_b32 s31, v33, 23
	v_pk_fma_f32 v[16:17], v[84:85], s[6:7], v[16:17] op_sel:[1,0,0] op_sel_hi:[1,1,1]
	v_pk_fma_f32 v[14:15], v[84:85], s[8:9], v[14:15] op_sel:[1,0,0] op_sel_hi:[1,1,1]
	v_pk_fma_f32 v[12:13], v[84:85], s[10:11], v[12:13] op_sel:[1,0,0] op_sel_hi:[1,1,1]
	v_pk_fma_f32 v[10:11], v[84:85], s[12:13], v[10:11] op_sel:[1,0,0] op_sel_hi:[1,1,1]
	v_readlane_b32 s6, v26, 24
	v_readlane_b32 s7, v27, 24
	v_readlane_b32 s8, v28, 24
	v_readlane_b32 s9, v29, 24
	v_readlane_b32 s10, v30, 24
	v_readlane_b32 s11, v31, 24
	v_readlane_b32 s12, v32, 24
	v_readlane_b32 s13, v33, 24
	v_pk_fma_f32 v[16:17], v[86:87], s[22:23], v[16:17] op_sel:[1,0,0] op_sel_hi:[1,1,1]
	v_pk_fma_f32 v[14:15], v[86:87], s[24:25], v[14:15] op_sel:[1,0,0] op_sel_hi:[1,1,1]
	v_pk_fma_f32 v[12:13], v[86:87], s[26:27], v[12:13] op_sel:[1,0,0] op_sel_hi:[1,1,1]
	v_pk_fma_f32 v[10:11], v[86:87], s[30:31], v[10:11] op_sel:[1,0,0] op_sel_hi:[1,1,1]
	v_readlane_b32 s22, v26, 25
	v_readlane_b32 s23, v27, 25
	v_readlane_b32 s24, v28, 25
	v_readlane_b32 s25, v29, 25
	v_readlane_b32 s26, v30, 25
	v_readlane_b32 s27, v31, 25
	v_readlane_b32 s30, v32, 25
	v_readlane_b32 s31, v33, 25
	v_pk_fma_f32 v[16:17], v[88:89], s[6:7], v[16:17] op_sel:[1,0,0] op_sel_hi:[1,1,1]
	v_pk_fma_f32 v[14:15], v[88:89], s[8:9], v[14:15] op_sel:[1,0,0] op_sel_hi:[1,1,1]
	v_pk_fma_f32 v[12:13], v[88:89], s[10:11], v[12:13] op_sel:[1,0,0] op_sel_hi:[1,1,1]
	v_pk_fma_f32 v[10:11], v[88:89], s[12:13], v[10:11] op_sel:[1,0,0] op_sel_hi:[1,1,1]
	v_readlane_b32 s6, v26, 26
	v_readlane_b32 s7, v27, 26
	v_readlane_b32 s8, v28, 26
	v_readlane_b32 s9, v29, 26
	v_readlane_b32 s10, v30, 26
	v_readlane_b32 s11, v31, 26
	v_readlane_b32 s12, v32, 26
	v_readlane_b32 s13, v33, 26
	v_pk_fma_f32 v[16:17], v[90:91], s[22:23], v[16:17] op_sel:[1,0,0] op_sel_hi:[1,1,1]
	v_pk_fma_f32 v[14:15], v[90:91], s[24:25], v[14:15] op_sel:[1,0,0] op_sel_hi:[1,1,1]
	v_pk_fma_f32 v[12:13], v[90:91], s[26:27], v[12:13] op_sel:[1,0,0] op_sel_hi:[1,1,1]
	v_pk_fma_f32 v[10:11], v[90:91], s[30:31], v[10:11] op_sel:[1,0,0] op_sel_hi:[1,1,1]
	v_readlane_b32 s22, v26, 27
	v_readlane_b32 s23, v27, 27
	v_readlane_b32 s24, v28, 27
	v_readlane_b32 s25, v29, 27
	v_readlane_b32 s26, v30, 27
	v_readlane_b32 s27, v31, 27
	v_readlane_b32 s30, v32, 27
	v_readlane_b32 s31, v33, 27
	v_pk_fma_f32 v[16:17], v[92:93], s[6:7], v[16:17] op_sel:[1,0,0] op_sel_hi:[1,1,1]
	v_pk_fma_f32 v[14:15], v[92:93], s[8:9], v[14:15] op_sel:[1,0,0] op_sel_hi:[1,1,1]
	v_pk_fma_f32 v[12:13], v[92:93], s[10:11], v[12:13] op_sel:[1,0,0] op_sel_hi:[1,1,1]
	v_pk_fma_f32 v[10:11], v[92:93], s[12:13], v[10:11] op_sel:[1,0,0] op_sel_hi:[1,1,1]
	v_readlane_b32 s6, v26, 28
	v_readlane_b32 s7, v27, 28
	v_readlane_b32 s8, v28, 28
	v_readlane_b32 s9, v29, 28
	v_readlane_b32 s10, v30, 28
	v_readlane_b32 s11, v31, 28
	v_readlane_b32 s12, v32, 28
	v_readlane_b32 s13, v33, 28
	v_pk_fma_f32 v[16:17], v[94:95], s[22:23], v[16:17] op_sel:[1,0,0] op_sel_hi:[1,1,1]
	v_pk_fma_f32 v[14:15], v[94:95], s[24:25], v[14:15] op_sel:[1,0,0] op_sel_hi:[1,1,1]
	v_pk_fma_f32 v[12:13], v[94:95], s[26:27], v[12:13] op_sel:[1,0,0] op_sel_hi:[1,1,1]
	v_pk_fma_f32 v[10:11], v[94:95], s[30:31], v[10:11] op_sel:[1,0,0] op_sel_hi:[1,1,1]
	v_readlane_b32 s22, v26, 29
	v_readlane_b32 s23, v27, 29
	v_readlane_b32 s24, v28, 29
	v_readlane_b32 s25, v29, 29
	v_readlane_b32 s26, v30, 29
	v_readlane_b32 s27, v31, 29
	v_readlane_b32 s30, v32, 29
	v_readlane_b32 s31, v33, 29
	v_pk_fma_f32 v[16:17], v[96:97], s[6:7], v[16:17] op_sel:[1,0,0] op_sel_hi:[1,1,1]
	v_pk_fma_f32 v[14:15], v[96:97], s[8:9], v[14:15] op_sel:[1,0,0] op_sel_hi:[1,1,1]
	v_pk_fma_f32 v[12:13], v[96:97], s[10:11], v[12:13] op_sel:[1,0,0] op_sel_hi:[1,1,1]
	v_pk_fma_f32 v[10:11], v[96:97], s[12:13], v[10:11] op_sel:[1,0,0] op_sel_hi:[1,1,1]
	v_readlane_b32 s6, v26, 30
	v_readlane_b32 s7, v27, 30
	v_readlane_b32 s8, v28, 30
	v_readlane_b32 s9, v29, 30
	v_readlane_b32 s10, v30, 30
	v_readlane_b32 s11, v31, 30
	v_readlane_b32 s12, v32, 30
	v_readlane_b32 s13, v33, 30
	v_pk_fma_f32 v[16:17], v[98:99], s[22:23], v[16:17] op_sel:[1,0,0] op_sel_hi:[1,1,1]
	v_pk_fma_f32 v[14:15], v[98:99], s[24:25], v[14:15] op_sel:[1,0,0] op_sel_hi:[1,1,1]
	v_pk_fma_f32 v[12:13], v[98:99], s[26:27], v[12:13] op_sel:[1,0,0] op_sel_hi:[1,1,1]
	v_pk_fma_f32 v[10:11], v[98:99], s[30:31], v[10:11] op_sel:[1,0,0] op_sel_hi:[1,1,1]
	v_readlane_b32 s22, v26, 31
	v_readlane_b32 s23, v27, 31
	v_readlane_b32 s24, v28, 31
	v_readlane_b32 s25, v29, 31
	v_readlane_b32 s26, v30, 31
	v_readlane_b32 s27, v31, 31
	v_readlane_b32 s30, v32, 31
	v_readlane_b32 s31, v33, 31
	v_pk_fma_f32 v[16:17], v[100:101], s[6:7], v[16:17] op_sel:[1,0,0] op_sel_hi:[1,1,1]
	v_pk_fma_f32 v[14:15], v[100:101], s[8:9], v[14:15] op_sel:[1,0,0] op_sel_hi:[1,1,1]
	v_pk_fma_f32 v[12:13], v[100:101], s[10:11], v[12:13] op_sel:[1,0,0] op_sel_hi:[1,1,1]
	v_pk_fma_f32 v[10:11], v[100:101], s[12:13], v[10:11] op_sel:[1,0,0] op_sel_hi:[1,1,1]
	v_readlane_b32 s6, v26, 32
	v_readlane_b32 s7, v27, 32
	v_readlane_b32 s8, v28, 32
	v_readlane_b32 s9, v29, 32
	v_readlane_b32 s10, v30, 32
	v_readlane_b32 s11, v31, 32
	v_readlane_b32 s12, v32, 32
	v_readlane_b32 s13, v33, 32
	v_pk_fma_f32 v[16:17], v[102:103], s[22:23], v[16:17] op_sel:[1,0,0] op_sel_hi:[1,1,1]
	v_pk_fma_f32 v[14:15], v[102:103], s[24:25], v[14:15] op_sel:[1,0,0] op_sel_hi:[1,1,1]
	v_pk_fma_f32 v[12:13], v[102:103], s[26:27], v[12:13] op_sel:[1,0,0] op_sel_hi:[1,1,1]
	v_pk_fma_f32 v[10:11], v[102:103], s[30:31], v[10:11] op_sel:[1,0,0] op_sel_hi:[1,1,1]
	v_readlane_b32 s22, v26, 33
	v_readlane_b32 s23, v27, 33
	v_readlane_b32 s24, v28, 33
	v_readlane_b32 s25, v29, 33
	v_readlane_b32 s26, v30, 33
	v_readlane_b32 s27, v31, 33
	v_readlane_b32 s30, v32, 33
	v_readlane_b32 s31, v33, 33
	v_pk_fma_f32 v[16:17], v[104:105], s[6:7], v[16:17] op_sel:[1,0,0] op_sel_hi:[1,1,1]
	v_pk_fma_f32 v[14:15], v[104:105], s[8:9], v[14:15] op_sel:[1,0,0] op_sel_hi:[1,1,1]
	v_pk_fma_f32 v[12:13], v[104:105], s[10:11], v[12:13] op_sel:[1,0,0] op_sel_hi:[1,1,1]
	v_pk_fma_f32 v[10:11], v[104:105], s[12:13], v[10:11] op_sel:[1,0,0] op_sel_hi:[1,1,1]
	v_readlane_b32 s6, v26, 34
	v_readlane_b32 s7, v27, 34
	v_readlane_b32 s8, v28, 34
	v_readlane_b32 s9, v29, 34
	v_readlane_b32 s10, v30, 34
	v_readlane_b32 s11, v31, 34
	v_readlane_b32 s12, v32, 34
	v_readlane_b32 s13, v33, 34
	v_pk_fma_f32 v[16:17], v[106:107], s[22:23], v[16:17] op_sel:[1,0,0] op_sel_hi:[1,1,1]
	v_pk_fma_f32 v[14:15], v[106:107], s[24:25], v[14:15] op_sel:[1,0,0] op_sel_hi:[1,1,1]
	v_pk_fma_f32 v[12:13], v[106:107], s[26:27], v[12:13] op_sel:[1,0,0] op_sel_hi:[1,1,1]
	v_pk_fma_f32 v[10:11], v[106:107], s[30:31], v[10:11] op_sel:[1,0,0] op_sel_hi:[1,1,1]
	v_readlane_b32 s22, v26, 35
	v_readlane_b32 s23, v27, 35
	v_readlane_b32 s24, v28, 35
	v_readlane_b32 s25, v29, 35
	v_readlane_b32 s26, v30, 35
	v_readlane_b32 s27, v31, 35
	v_readlane_b32 s30, v32, 35
	v_readlane_b32 s31, v33, 35
	v_pk_fma_f32 v[16:17], v[108:109], s[6:7], v[16:17] op_sel:[1,0,0] op_sel_hi:[1,1,1]
	v_pk_fma_f32 v[14:15], v[108:109], s[8:9], v[14:15] op_sel:[1,0,0] op_sel_hi:[1,1,1]
	v_pk_fma_f32 v[12:13], v[108:109], s[10:11], v[12:13] op_sel:[1,0,0] op_sel_hi:[1,1,1]
	v_pk_fma_f32 v[10:11], v[108:109], s[12:13], v[10:11] op_sel:[1,0,0] op_sel_hi:[1,1,1]
	v_readlane_b32 s6, v26, 36
	v_readlane_b32 s7, v27, 36
	v_readlane_b32 s8, v28, 36
	v_readlane_b32 s9, v29, 36
	v_readlane_b32 s10, v30, 36
	v_readlane_b32 s11, v31, 36
	v_readlane_b32 s12, v32, 36
	v_readlane_b32 s13, v33, 36
	v_pk_fma_f32 v[16:17], v[110:111], s[22:23], v[16:17] op_sel:[1,0,0] op_sel_hi:[1,1,1]
	v_pk_fma_f32 v[14:15], v[110:111], s[24:25], v[14:15] op_sel:[1,0,0] op_sel_hi:[1,1,1]
	v_pk_fma_f32 v[12:13], v[110:111], s[26:27], v[12:13] op_sel:[1,0,0] op_sel_hi:[1,1,1]
	v_pk_fma_f32 v[10:11], v[110:111], s[30:31], v[10:11] op_sel:[1,0,0] op_sel_hi:[1,1,1]
	v_readlane_b32 s22, v26, 37
	v_readlane_b32 s23, v27, 37
	v_readlane_b32 s24, v28, 37
	v_readlane_b32 s25, v29, 37
	v_readlane_b32 s26, v30, 37
	v_readlane_b32 s27, v31, 37
	v_readlane_b32 s30, v32, 37
	v_readlane_b32 s31, v33, 37
	v_pk_fma_f32 v[16:17], v[112:113], s[6:7], v[16:17] op_sel:[1,0,0] op_sel_hi:[1,1,1]
	v_pk_fma_f32 v[14:15], v[112:113], s[8:9], v[14:15] op_sel:[1,0,0] op_sel_hi:[1,1,1]
	v_pk_fma_f32 v[12:13], v[112:113], s[10:11], v[12:13] op_sel:[1,0,0] op_sel_hi:[1,1,1]
	v_pk_fma_f32 v[10:11], v[112:113], s[12:13], v[10:11] op_sel:[1,0,0] op_sel_hi:[1,1,1]
	v_readlane_b32 s6, v26, 38
	v_readlane_b32 s7, v27, 38
	v_readlane_b32 s8, v28, 38
	v_readlane_b32 s9, v29, 38
	v_readlane_b32 s10, v30, 38
	v_readlane_b32 s11, v31, 38
	v_readlane_b32 s12, v32, 38
	v_readlane_b32 s13, v33, 38
	v_pk_fma_f32 v[16:17], v[114:115], s[22:23], v[16:17] op_sel:[1,0,0] op_sel_hi:[1,1,1]
	v_pk_fma_f32 v[14:15], v[114:115], s[24:25], v[14:15] op_sel:[1,0,0] op_sel_hi:[1,1,1]
	v_pk_fma_f32 v[12:13], v[114:115], s[26:27], v[12:13] op_sel:[1,0,0] op_sel_hi:[1,1,1]
	v_pk_fma_f32 v[10:11], v[114:115], s[30:31], v[10:11] op_sel:[1,0,0] op_sel_hi:[1,1,1]
	v_readlane_b32 s22, v26, 39
	v_readlane_b32 s23, v27, 39
	v_readlane_b32 s24, v28, 39
	v_readlane_b32 s25, v29, 39
	v_readlane_b32 s26, v30, 39
	v_readlane_b32 s27, v31, 39
	v_readlane_b32 s30, v32, 39
	v_readlane_b32 s31, v33, 39
	v_pk_fma_f32 v[16:17], v[116:117], s[6:7], v[16:17] op_sel:[1,0,0] op_sel_hi:[1,1,1]
	v_pk_fma_f32 v[14:15], v[116:117], s[8:9], v[14:15] op_sel:[1,0,0] op_sel_hi:[1,1,1]
	v_pk_fma_f32 v[12:13], v[116:117], s[10:11], v[12:13] op_sel:[1,0,0] op_sel_hi:[1,1,1]
	v_pk_fma_f32 v[10:11], v[116:117], s[12:13], v[10:11] op_sel:[1,0,0] op_sel_hi:[1,1,1]
	v_readlane_b32 s6, v26, 40
	v_readlane_b32 s7, v27, 40
	v_readlane_b32 s8, v28, 40
	v_readlane_b32 s9, v29, 40
	v_readlane_b32 s10, v30, 40
	v_readlane_b32 s11, v31, 40
	v_readlane_b32 s12, v32, 40
	v_readlane_b32 s13, v33, 40
	v_pk_fma_f32 v[16:17], v[118:119], s[22:23], v[16:17] op_sel:[1,0,0] op_sel_hi:[1,1,1]
	v_pk_fma_f32 v[14:15], v[118:119], s[24:25], v[14:15] op_sel:[1,0,0] op_sel_hi:[1,1,1]
	v_pk_fma_f32 v[12:13], v[118:119], s[26:27], v[12:13] op_sel:[1,0,0] op_sel_hi:[1,1,1]
	v_pk_fma_f32 v[10:11], v[118:119], s[30:31], v[10:11] op_sel:[1,0,0] op_sel_hi:[1,1,1]
	v_readlane_b32 s22, v26, 41
	v_readlane_b32 s23, v27, 41
	v_readlane_b32 s24, v28, 41
	v_readlane_b32 s25, v29, 41
	v_readlane_b32 s26, v30, 41
	v_readlane_b32 s27, v31, 41
	v_readlane_b32 s30, v32, 41
	v_readlane_b32 s31, v33, 41
	v_pk_fma_f32 v[16:17], v[120:121], s[6:7], v[16:17] op_sel:[1,0,0] op_sel_hi:[1,1,1]
	v_pk_fma_f32 v[14:15], v[120:121], s[8:9], v[14:15] op_sel:[1,0,0] op_sel_hi:[1,1,1]
	v_pk_fma_f32 v[12:13], v[120:121], s[10:11], v[12:13] op_sel:[1,0,0] op_sel_hi:[1,1,1]
	v_pk_fma_f32 v[10:11], v[120:121], s[12:13], v[10:11] op_sel:[1,0,0] op_sel_hi:[1,1,1]
	v_readlane_b32 s6, v26, 42
	v_readlane_b32 s7, v27, 42
	v_readlane_b32 s8, v28, 42
	v_readlane_b32 s9, v29, 42
	v_readlane_b32 s10, v30, 42
	v_readlane_b32 s11, v31, 42
	v_readlane_b32 s12, v32, 42
	v_readlane_b32 s13, v33, 42
	v_pk_fma_f32 v[16:17], v[122:123], s[22:23], v[16:17] op_sel:[1,0,0] op_sel_hi:[1,1,1]
	v_pk_fma_f32 v[14:15], v[122:123], s[24:25], v[14:15] op_sel:[1,0,0] op_sel_hi:[1,1,1]
	v_pk_fma_f32 v[12:13], v[122:123], s[26:27], v[12:13] op_sel:[1,0,0] op_sel_hi:[1,1,1]
	v_pk_fma_f32 v[10:11], v[122:123], s[30:31], v[10:11] op_sel:[1,0,0] op_sel_hi:[1,1,1]
	v_readlane_b32 s22, v26, 43
	v_readlane_b32 s23, v27, 43
	v_readlane_b32 s24, v28, 43
	v_readlane_b32 s25, v29, 43
	v_readlane_b32 s26, v30, 43
	v_readlane_b32 s27, v31, 43
	v_readlane_b32 s30, v32, 43
	v_readlane_b32 s31, v33, 43
	v_pk_fma_f32 v[16:17], v[124:125], s[6:7], v[16:17] op_sel:[1,0,0] op_sel_hi:[1,1,1]
	v_pk_fma_f32 v[14:15], v[124:125], s[8:9], v[14:15] op_sel:[1,0,0] op_sel_hi:[1,1,1]
	v_pk_fma_f32 v[12:13], v[124:125], s[10:11], v[12:13] op_sel:[1,0,0] op_sel_hi:[1,1,1]
	v_pk_fma_f32 v[10:11], v[124:125], s[12:13], v[10:11] op_sel:[1,0,0] op_sel_hi:[1,1,1]
	v_readlane_b32 s6, v26, 44
	v_readlane_b32 s7, v27, 44
	v_readlane_b32 s8, v28, 44
	v_readlane_b32 s9, v29, 44
	v_readlane_b32 s10, v30, 44
	v_readlane_b32 s11, v31, 44
	v_readlane_b32 s12, v32, 44
	v_readlane_b32 s13, v33, 44
	v_pk_fma_f32 v[16:17], v[126:127], s[22:23], v[16:17] op_sel:[1,0,0] op_sel_hi:[1,1,1]
	v_pk_fma_f32 v[14:15], v[126:127], s[24:25], v[14:15] op_sel:[1,0,0] op_sel_hi:[1,1,1]
	v_pk_fma_f32 v[12:13], v[126:127], s[26:27], v[12:13] op_sel:[1,0,0] op_sel_hi:[1,1,1]
	v_pk_fma_f32 v[10:11], v[126:127], s[30:31], v[10:11] op_sel:[1,0,0] op_sel_hi:[1,1,1]
	v_readlane_b32 s22, v26, 45
	v_readlane_b32 s23, v27, 45
	v_readlane_b32 s24, v28, 45
	v_readlane_b32 s25, v29, 45
	v_readlane_b32 s26, v30, 45
	v_readlane_b32 s27, v31, 45
	v_readlane_b32 s30, v32, 45
	v_readlane_b32 s31, v33, 45
	v_pk_fma_f32 v[16:17], v[128:129], s[6:7], v[16:17] op_sel:[1,0,0] op_sel_hi:[1,1,1]
	v_pk_fma_f32 v[14:15], v[128:129], s[8:9], v[14:15] op_sel:[1,0,0] op_sel_hi:[1,1,1]
	v_pk_fma_f32 v[12:13], v[128:129], s[10:11], v[12:13] op_sel:[1,0,0] op_sel_hi:[1,1,1]
	v_pk_fma_f32 v[10:11], v[128:129], s[12:13], v[10:11] op_sel:[1,0,0] op_sel_hi:[1,1,1]
	v_readlane_b32 s6, v26, 46
	v_readlane_b32 s7, v27, 46
	v_readlane_b32 s8, v28, 46
	v_readlane_b32 s9, v29, 46
	v_readlane_b32 s10, v30, 46
	v_readlane_b32 s11, v31, 46
	v_readlane_b32 s12, v32, 46
	v_readlane_b32 s13, v33, 46
	v_pk_fma_f32 v[16:17], v[130:131], s[22:23], v[16:17] op_sel:[1,0,0] op_sel_hi:[1,1,1]
	v_pk_fma_f32 v[14:15], v[130:131], s[24:25], v[14:15] op_sel:[1,0,0] op_sel_hi:[1,1,1]
	v_pk_fma_f32 v[12:13], v[130:131], s[26:27], v[12:13] op_sel:[1,0,0] op_sel_hi:[1,1,1]
	v_pk_fma_f32 v[10:11], v[130:131], s[30:31], v[10:11] op_sel:[1,0,0] op_sel_hi:[1,1,1]
	v_readlane_b32 s22, v26, 47
	v_readlane_b32 s23, v27, 47
	v_readlane_b32 s24, v28, 47
	v_readlane_b32 s25, v29, 47
	v_readlane_b32 s26, v30, 47
	v_readlane_b32 s27, v31, 47
	v_readlane_b32 s30, v32, 47
	v_readlane_b32 s31, v33, 47
	v_pk_fma_f32 v[16:17], v[132:133], s[6:7], v[16:17] op_sel:[1,0,0] op_sel_hi:[1,1,1]
	v_pk_fma_f32 v[14:15], v[132:133], s[8:9], v[14:15] op_sel:[1,0,0] op_sel_hi:[1,1,1]
	v_pk_fma_f32 v[12:13], v[132:133], s[10:11], v[12:13] op_sel:[1,0,0] op_sel_hi:[1,1,1]
	v_pk_fma_f32 v[10:11], v[132:133], s[12:13], v[10:11] op_sel:[1,0,0] op_sel_hi:[1,1,1]
	v_readlane_b32 s6, v26, 48
	v_readlane_b32 s7, v27, 48
	v_readlane_b32 s8, v28, 48
	v_readlane_b32 s9, v29, 48
	v_readlane_b32 s10, v30, 48
	v_readlane_b32 s11, v31, 48
	v_readlane_b32 s12, v32, 48
	v_readlane_b32 s13, v33, 48
	v_pk_fma_f32 v[16:17], v[134:135], s[22:23], v[16:17] op_sel:[1,0,0] op_sel_hi:[1,1,1]
	v_pk_fma_f32 v[14:15], v[134:135], s[24:25], v[14:15] op_sel:[1,0,0] op_sel_hi:[1,1,1]
	v_pk_fma_f32 v[12:13], v[134:135], s[26:27], v[12:13] op_sel:[1,0,0] op_sel_hi:[1,1,1]
	v_pk_fma_f32 v[10:11], v[134:135], s[30:31], v[10:11] op_sel:[1,0,0] op_sel_hi:[1,1,1]
	v_readlane_b32 s22, v26, 49
	v_readlane_b32 s23, v27, 49
	v_readlane_b32 s24, v28, 49
	v_readlane_b32 s25, v29, 49
	v_readlane_b32 s26, v30, 49
	v_readlane_b32 s27, v31, 49
	v_readlane_b32 s30, v32, 49
	v_readlane_b32 s31, v33, 49
	v_pk_fma_f32 v[16:17], v[136:137], s[6:7], v[16:17] op_sel:[1,0,0] op_sel_hi:[1,1,1]
	v_pk_fma_f32 v[14:15], v[136:137], s[8:9], v[14:15] op_sel:[1,0,0] op_sel_hi:[1,1,1]
	v_pk_fma_f32 v[12:13], v[136:137], s[10:11], v[12:13] op_sel:[1,0,0] op_sel_hi:[1,1,1]
	v_pk_fma_f32 v[10:11], v[136:137], s[12:13], v[10:11] op_sel:[1,0,0] op_sel_hi:[1,1,1]
	v_readlane_b32 s6, v26, 50
	v_readlane_b32 s7, v27, 50
	v_readlane_b32 s8, v28, 50
	v_readlane_b32 s9, v29, 50
	v_readlane_b32 s10, v30, 50
	v_readlane_b32 s11, v31, 50
	v_readlane_b32 s12, v32, 50
	v_readlane_b32 s13, v33, 50
	v_pk_fma_f32 v[16:17], v[138:139], s[22:23], v[16:17] op_sel:[1,0,0] op_sel_hi:[1,1,1]
	v_pk_fma_f32 v[14:15], v[138:139], s[24:25], v[14:15] op_sel:[1,0,0] op_sel_hi:[1,1,1]
	v_pk_fma_f32 v[12:13], v[138:139], s[26:27], v[12:13] op_sel:[1,0,0] op_sel_hi:[1,1,1]
	v_pk_fma_f32 v[10:11], v[138:139], s[30:31], v[10:11] op_sel:[1,0,0] op_sel_hi:[1,1,1]
	v_readlane_b32 s22, v26, 51
	v_readlane_b32 s23, v27, 51
	v_readlane_b32 s24, v28, 51
	v_readlane_b32 s25, v29, 51
	v_readlane_b32 s26, v30, 51
	v_readlane_b32 s27, v31, 51
	v_readlane_b32 s30, v32, 51
	v_readlane_b32 s31, v33, 51
	v_pk_fma_f32 v[16:17], v[140:141], s[6:7], v[16:17] op_sel:[1,0,0] op_sel_hi:[1,1,1]
	v_pk_fma_f32 v[14:15], v[140:141], s[8:9], v[14:15] op_sel:[1,0,0] op_sel_hi:[1,1,1]
	v_pk_fma_f32 v[12:13], v[140:141], s[10:11], v[12:13] op_sel:[1,0,0] op_sel_hi:[1,1,1]
	v_pk_fma_f32 v[10:11], v[140:141], s[12:13], v[10:11] op_sel:[1,0,0] op_sel_hi:[1,1,1]
	v_readlane_b32 s6, v26, 52
	v_readlane_b32 s7, v27, 52
	v_readlane_b32 s8, v28, 52
	v_readlane_b32 s9, v29, 52
	v_readlane_b32 s10, v30, 52
	v_readlane_b32 s11, v31, 52
	v_readlane_b32 s12, v32, 52
	v_readlane_b32 s13, v33, 52
	v_pk_fma_f32 v[16:17], v[142:143], s[22:23], v[16:17] op_sel:[1,0,0] op_sel_hi:[1,1,1]
	v_pk_fma_f32 v[14:15], v[142:143], s[24:25], v[14:15] op_sel:[1,0,0] op_sel_hi:[1,1,1]
	v_pk_fma_f32 v[12:13], v[142:143], s[26:27], v[12:13] op_sel:[1,0,0] op_sel_hi:[1,1,1]
	v_pk_fma_f32 v[10:11], v[142:143], s[30:31], v[10:11] op_sel:[1,0,0] op_sel_hi:[1,1,1]
	v_readlane_b32 s22, v26, 53
	v_readlane_b32 s23, v27, 53
	v_readlane_b32 s24, v28, 53
	v_readlane_b32 s25, v29, 53
	v_readlane_b32 s26, v30, 53
	v_readlane_b32 s27, v31, 53
	v_readlane_b32 s30, v32, 53
	v_readlane_b32 s31, v33, 53
	v_pk_fma_f32 v[16:17], v[144:145], s[6:7], v[16:17] op_sel:[1,0,0] op_sel_hi:[1,1,1]
	v_pk_fma_f32 v[14:15], v[144:145], s[8:9], v[14:15] op_sel:[1,0,0] op_sel_hi:[1,1,1]
	v_pk_fma_f32 v[12:13], v[144:145], s[10:11], v[12:13] op_sel:[1,0,0] op_sel_hi:[1,1,1]
	v_pk_fma_f32 v[10:11], v[144:145], s[12:13], v[10:11] op_sel:[1,0,0] op_sel_hi:[1,1,1]
	v_readlane_b32 s6, v26, 54
	v_readlane_b32 s7, v27, 54
	v_readlane_b32 s8, v28, 54
	v_readlane_b32 s9, v29, 54
	v_readlane_b32 s10, v30, 54
	v_readlane_b32 s11, v31, 54
	v_readlane_b32 s12, v32, 54
	v_readlane_b32 s13, v33, 54
	v_pk_fma_f32 v[16:17], v[146:147], s[22:23], v[16:17] op_sel:[1,0,0] op_sel_hi:[1,1,1]
	v_pk_fma_f32 v[14:15], v[146:147], s[24:25], v[14:15] op_sel:[1,0,0] op_sel_hi:[1,1,1]
	v_pk_fma_f32 v[12:13], v[146:147], s[26:27], v[12:13] op_sel:[1,0,0] op_sel_hi:[1,1,1]
	v_pk_fma_f32 v[10:11], v[146:147], s[30:31], v[10:11] op_sel:[1,0,0] op_sel_hi:[1,1,1]
	v_readlane_b32 s22, v26, 55
	v_readlane_b32 s23, v27, 55
	v_readlane_b32 s24, v28, 55
	v_readlane_b32 s25, v29, 55
	v_readlane_b32 s26, v30, 55
	v_readlane_b32 s27, v31, 55
	v_readlane_b32 s30, v32, 55
	v_readlane_b32 s31, v33, 55
	v_pk_fma_f32 v[16:17], v[148:149], s[6:7], v[16:17] op_sel:[1,0,0] op_sel_hi:[1,1,1]
	v_pk_fma_f32 v[14:15], v[148:149], s[8:9], v[14:15] op_sel:[1,0,0] op_sel_hi:[1,1,1]
	v_pk_fma_f32 v[12:13], v[148:149], s[10:11], v[12:13] op_sel:[1,0,0] op_sel_hi:[1,1,1]
	v_pk_fma_f32 v[10:11], v[148:149], s[12:13], v[10:11] op_sel:[1,0,0] op_sel_hi:[1,1,1]
	v_readlane_b32 s6, v26, 56
	v_readlane_b32 s7, v27, 56
	v_readlane_b32 s8, v28, 56
	v_readlane_b32 s9, v29, 56
	v_readlane_b32 s10, v30, 56
	v_readlane_b32 s11, v31, 56
	v_readlane_b32 s12, v32, 56
	v_readlane_b32 s13, v33, 56
	v_pk_fma_f32 v[16:17], v[150:151], s[22:23], v[16:17] op_sel:[1,0,0] op_sel_hi:[1,1,1]
	v_pk_fma_f32 v[14:15], v[150:151], s[24:25], v[14:15] op_sel:[1,0,0] op_sel_hi:[1,1,1]
	v_pk_fma_f32 v[12:13], v[150:151], s[26:27], v[12:13] op_sel:[1,0,0] op_sel_hi:[1,1,1]
	v_pk_fma_f32 v[10:11], v[150:151], s[30:31], v[10:11] op_sel:[1,0,0] op_sel_hi:[1,1,1]
	v_readlane_b32 s22, v26, 57
	v_readlane_b32 s23, v27, 57
	v_readlane_b32 s24, v28, 57
	v_readlane_b32 s25, v29, 57
	v_readlane_b32 s26, v30, 57
	v_readlane_b32 s27, v31, 57
	v_readlane_b32 s30, v32, 57
	v_readlane_b32 s31, v33, 57
	v_pk_fma_f32 v[16:17], v[152:153], s[6:7], v[16:17] op_sel:[1,0,0] op_sel_hi:[1,1,1]
	v_pk_fma_f32 v[14:15], v[152:153], s[8:9], v[14:15] op_sel:[1,0,0] op_sel_hi:[1,1,1]
	v_pk_fma_f32 v[12:13], v[152:153], s[10:11], v[12:13] op_sel:[1,0,0] op_sel_hi:[1,1,1]
	v_pk_fma_f32 v[10:11], v[152:153], s[12:13], v[10:11] op_sel:[1,0,0] op_sel_hi:[1,1,1]
	v_readlane_b32 s6, v26, 58
	v_readlane_b32 s7, v27, 58
	v_readlane_b32 s8, v28, 58
	v_readlane_b32 s9, v29, 58
	v_readlane_b32 s10, v30, 58
	v_readlane_b32 s11, v31, 58
	v_readlane_b32 s12, v32, 58
	v_readlane_b32 s13, v33, 58
	v_pk_fma_f32 v[16:17], v[154:155], s[22:23], v[16:17] op_sel:[1,0,0] op_sel_hi:[1,1,1]
	v_pk_fma_f32 v[14:15], v[154:155], s[24:25], v[14:15] op_sel:[1,0,0] op_sel_hi:[1,1,1]
	v_pk_fma_f32 v[12:13], v[154:155], s[26:27], v[12:13] op_sel:[1,0,0] op_sel_hi:[1,1,1]
	v_pk_fma_f32 v[10:11], v[154:155], s[30:31], v[10:11] op_sel:[1,0,0] op_sel_hi:[1,1,1]
	v_readlane_b32 s22, v26, 59
	v_readlane_b32 s23, v27, 59
	v_readlane_b32 s24, v28, 59
	v_readlane_b32 s25, v29, 59
	v_readlane_b32 s26, v30, 59
	v_readlane_b32 s27, v31, 59
	v_readlane_b32 s30, v32, 59
	v_readlane_b32 s31, v33, 59
	v_pk_fma_f32 v[16:17], v[156:157], s[6:7], v[16:17] op_sel:[1,0,0] op_sel_hi:[1,1,1]
	v_pk_fma_f32 v[14:15], v[156:157], s[8:9], v[14:15] op_sel:[1,0,0] op_sel_hi:[1,1,1]
	v_pk_fma_f32 v[12:13], v[156:157], s[10:11], v[12:13] op_sel:[1,0,0] op_sel_hi:[1,1,1]
	v_pk_fma_f32 v[10:11], v[156:157], s[12:13], v[10:11] op_sel:[1,0,0] op_sel_hi:[1,1,1]
	v_readlane_b32 s6, v26, 60
	v_readlane_b32 s7, v27, 60
	v_readlane_b32 s8, v28, 60
	v_readlane_b32 s9, v29, 60
	v_readlane_b32 s10, v30, 60
	v_readlane_b32 s11, v31, 60
	v_readlane_b32 s12, v32, 60
	v_readlane_b32 s13, v33, 60
	v_pk_fma_f32 v[16:17], v[158:159], s[22:23], v[16:17] op_sel:[1,0,0] op_sel_hi:[1,1,1]
	v_pk_fma_f32 v[14:15], v[158:159], s[24:25], v[14:15] op_sel:[1,0,0] op_sel_hi:[1,1,1]
	v_pk_fma_f32 v[12:13], v[158:159], s[26:27], v[12:13] op_sel:[1,0,0] op_sel_hi:[1,1,1]
	v_pk_fma_f32 v[10:11], v[158:159], s[30:31], v[10:11] op_sel:[1,0,0] op_sel_hi:[1,1,1]
	v_readlane_b32 s22, v26, 61
	v_readlane_b32 s23, v27, 61
	v_readlane_b32 s24, v28, 61
	v_readlane_b32 s25, v29, 61
	v_readlane_b32 s26, v30, 61
	v_readlane_b32 s27, v31, 61
	v_readlane_b32 s30, v32, 61
	v_readlane_b32 s31, v33, 61
	v_pk_fma_f32 v[16:17], v[164:165], s[6:7], v[16:17] op_sel:[1,0,0] op_sel_hi:[1,1,1]
	v_pk_fma_f32 v[14:15], v[164:165], s[8:9], v[14:15] op_sel:[1,0,0] op_sel_hi:[1,1,1]
	v_pk_fma_f32 v[12:13], v[164:165], s[10:11], v[12:13] op_sel:[1,0,0] op_sel_hi:[1,1,1]
	v_pk_fma_f32 v[10:11], v[164:165], s[12:13], v[10:11] op_sel:[1,0,0] op_sel_hi:[1,1,1]
	v_readlane_b32 s6, v26, 62
	v_readlane_b32 s7, v27, 62
	v_readlane_b32 s8, v28, 62
	v_readlane_b32 s9, v29, 62
	v_readlane_b32 s10, v30, 62
	v_readlane_b32 s11, v31, 62
	v_readlane_b32 s12, v32, 62
	v_readlane_b32 s13, v33, 62
	v_pk_fma_f32 v[16:17], v[166:167], s[22:23], v[16:17] op_sel:[1,0,0] op_sel_hi:[1,1,1]
	v_pk_fma_f32 v[14:15], v[166:167], s[24:25], v[14:15] op_sel:[1,0,0] op_sel_hi:[1,1,1]
	v_pk_fma_f32 v[12:13], v[166:167], s[26:27], v[12:13] op_sel:[1,0,0] op_sel_hi:[1,1,1]
	v_pk_fma_f32 v[10:11], v[166:167], s[30:31], v[10:11] op_sel:[1,0,0] op_sel_hi:[1,1,1]
	v_readlane_b32 s22, v26, 63
	v_readlane_b32 s23, v27, 63
	v_readlane_b32 s24, v28, 63
	v_readlane_b32 s25, v29, 63
	v_readlane_b32 s26, v30, 63
	v_readlane_b32 s27, v31, 63
	v_readlane_b32 s30, v32, 63
	v_readlane_b32 s31, v33, 63
	v_pk_fma_f32 v[16:17], v[168:169], s[6:7], v[16:17] op_sel:[1,0,0] op_sel_hi:[1,1,1]
	v_pk_fma_f32 v[14:15], v[168:169], s[8:9], v[14:15] op_sel:[1,0,0] op_sel_hi:[1,1,1]
	v_pk_fma_f32 v[12:13], v[168:169], s[10:11], v[12:13] op_sel:[1,0,0] op_sel_hi:[1,1,1]
	v_pk_fma_f32 v[10:11], v[168:169], s[12:13], v[10:11] op_sel:[1,0,0] op_sel_hi:[1,1,1]
	v_pk_fma_f32 v[16:17], v[170:171], s[22:23], v[16:17] op_sel:[1,0,0] op_sel_hi:[1,1,1]
	v_pk_fma_f32 v[14:15], v[170:171], s[24:25], v[14:15] op_sel:[1,0,0] op_sel_hi:[1,1,1]
	v_pk_fma_f32 v[12:13], v[170:171], s[26:27], v[12:13] op_sel:[1,0,0] op_sel_hi:[1,1,1]
	v_pk_fma_f32 v[10:11], v[170:171], s[30:31], v[10:11] op_sel:[1,0,0] op_sel_hi:[1,1,1]
	v_lshl_add_u64 v[8:9], v[8:9], 0, s[14:15]
	global_load_dword v41, v[8:9], off
	v_lshl_add_u64 v[8:9], v[8:9], 0, s[14:15]
	global_load_dword v43, v[8:9], off
	v_lshl_add_u64 v[8:9], v[8:9], 0, s[14:15]
	global_load_dword v45, v[8:9], off
	v_lshl_add_u64 v[8:9], v[8:9], 0, s[14:15]
	global_load_dword v47, v[8:9], off
	v_lshl_add_u64 v[8:9], v[8:9], 0, s[14:15]
	global_load_dword v49, v[8:9], off
	v_lshl_add_u64 v[8:9], v[8:9], 0, s[14:15]
	global_load_dword v51, v[8:9], off
	v_lshl_add_u64 v[8:9], v[8:9], 0, s[14:15]
	global_load_dword v53, v[8:9], off
	v_lshl_add_u64 v[8:9], v[8:9], 0, s[14:15]
	global_load_dword v55, v[8:9], off
	v_lshl_add_u64 v[8:9], v[8:9], 0, s[14:15]
	global_load_dword v57, v[8:9], off
	v_lshl_add_u64 v[8:9], v[8:9], 0, s[14:15]
	global_load_dword v59, v[8:9], off
	v_lshl_add_u64 v[8:9], v[8:9], 0, s[14:15]
	global_load_dword v61, v[8:9], off
	v_lshl_add_u64 v[8:9], v[8:9], 0, s[14:15]
	global_load_dword v63, v[8:9], off
	v_lshl_add_u64 v[8:9], v[8:9], 0, s[14:15]
	global_load_dword v65, v[8:9], off
	v_lshl_add_u64 v[8:9], v[8:9], 0, s[14:15]
	global_load_dword v67, v[8:9], off
	v_lshl_add_u64 v[8:9], v[8:9], 0, s[14:15]
	global_load_dword v69, v[8:9], off
	v_lshl_add_u64 v[8:9], v[8:9], 0, s[14:15]
	global_load_dword v71, v[8:9], off
	v_lshl_add_u64 v[8:9], v[8:9], 0, s[14:15]
	global_load_dword v73, v[8:9], off
	v_lshl_add_u64 v[8:9], v[8:9], 0, s[14:15]
	global_load_dword v75, v[8:9], off
	v_lshl_add_u64 v[8:9], v[8:9], 0, s[14:15]
	global_load_dword v77, v[8:9], off
	v_lshl_add_u64 v[8:9], v[8:9], 0, s[14:15]
	global_load_dword v79, v[8:9], off
	v_lshl_add_u64 v[8:9], v[8:9], 0, s[14:15]
	global_load_dword v81, v[8:9], off
	v_lshl_add_u64 v[8:9], v[8:9], 0, s[14:15]
	global_load_dword v83, v[8:9], off
	v_lshl_add_u64 v[8:9], v[8:9], 0, s[14:15]
	global_load_dword v85, v[8:9], off
	v_lshl_add_u64 v[8:9], v[8:9], 0, s[14:15]
	global_load_dword v87, v[8:9], off
	v_lshl_add_u64 v[8:9], v[8:9], 0, s[14:15]
	global_load_dword v89, v[8:9], off
	v_lshl_add_u64 v[8:9], v[8:9], 0, s[14:15]
	global_load_dword v91, v[8:9], off
	v_lshl_add_u64 v[8:9], v[8:9], 0, s[14:15]
	global_load_dword v93, v[8:9], off
	v_lshl_add_u64 v[8:9], v[8:9], 0, s[14:15]
	global_load_dword v95, v[8:9], off
	v_lshl_add_u64 v[8:9], v[8:9], 0, s[14:15]
	global_load_dword v97, v[8:9], off
	v_lshl_add_u64 v[8:9], v[8:9], 0, s[14:15]
	global_load_dword v99, v[8:9], off
	v_lshl_add_u64 v[8:9], v[8:9], 0, s[14:15]
	global_load_dword v101, v[8:9], off
	v_lshl_add_u64 v[8:9], v[8:9], 0, s[14:15]
	global_load_dword v103, v[8:9], off
	v_lshl_add_u64 v[8:9], v[8:9], 0, s[14:15]
	global_load_dword v105, v[8:9], off
	v_lshl_add_u64 v[8:9], v[8:9], 0, s[14:15]
	global_load_dword v107, v[8:9], off
	v_lshl_add_u64 v[8:9], v[8:9], 0, s[14:15]
	global_load_dword v109, v[8:9], off
	v_lshl_add_u64 v[8:9], v[8:9], 0, s[14:15]
	global_load_dword v111, v[8:9], off
	v_lshl_add_u64 v[8:9], v[8:9], 0, s[14:15]
	global_load_dword v113, v[8:9], off
	v_lshl_add_u64 v[8:9], v[8:9], 0, s[14:15]
	global_load_dword v115, v[8:9], off
	v_lshl_add_u64 v[8:9], v[8:9], 0, s[14:15]
	global_load_dword v117, v[8:9], off
	v_lshl_add_u64 v[8:9], v[8:9], 0, s[14:15]
	global_load_dword v119, v[8:9], off
	v_lshl_add_u64 v[8:9], v[8:9], 0, s[14:15]
	global_load_dword v121, v[8:9], off
	v_lshl_add_u64 v[8:9], v[8:9], 0, s[14:15]
	global_load_dword v123, v[8:9], off
	v_lshl_add_u64 v[8:9], v[8:9], 0, s[14:15]
	global_load_dword v125, v[8:9], off
	v_lshl_add_u64 v[8:9], v[8:9], 0, s[14:15]
	global_load_dword v127, v[8:9], off
	v_lshl_add_u64 v[8:9], v[8:9], 0, s[14:15]
	global_load_dword v129, v[8:9], off
	v_lshl_add_u64 v[8:9], v[8:9], 0, s[14:15]
	global_load_dword v131, v[8:9], off
	v_lshl_add_u64 v[8:9], v[8:9], 0, s[14:15]
	global_load_dword v133, v[8:9], off
	v_lshl_add_u64 v[8:9], v[8:9], 0, s[14:15]
	global_load_dword v135, v[8:9], off
	v_lshl_add_u64 v[8:9], v[8:9], 0, s[14:15]
	global_load_dword v137, v[8:9], off
	v_lshl_add_u64 v[8:9], v[8:9], 0, s[14:15]
	global_load_dword v139, v[8:9], off
	v_lshl_add_u64 v[8:9], v[8:9], 0, s[14:15]
	global_load_dword v141, v[8:9], off
	v_lshl_add_u64 v[8:9], v[8:9], 0, s[14:15]
	global_load_dword v143, v[8:9], off
	v_lshl_add_u64 v[8:9], v[8:9], 0, s[14:15]
	global_load_dword v145, v[8:9], off
	v_lshl_add_u64 v[8:9], v[8:9], 0, s[14:15]
	global_load_dword v147, v[8:9], off
	v_lshl_add_u64 v[8:9], v[8:9], 0, s[14:15]
	global_load_dword v149, v[8:9], off
	v_lshl_add_u64 v[8:9], v[8:9], 0, s[14:15]
	global_load_dword v151, v[8:9], off
	v_lshl_add_u64 v[8:9], v[8:9], 0, s[14:15]
	global_load_dword v153, v[8:9], off
	v_lshl_add_u64 v[8:9], v[8:9], 0, s[14:15]
	global_load_dword v155, v[8:9], off
	v_lshl_add_u64 v[8:9], v[8:9], 0, s[14:15]
	global_load_dword v157, v[8:9], off
	v_lshl_add_u64 v[8:9], v[8:9], 0, s[14:15]
	global_load_dword v159, v[8:9], off
	v_lshl_add_u64 v[8:9], v[8:9], 0, s[14:15]
	global_load_dword v165, v[8:9], off
	v_lshl_add_u64 v[8:9], v[8:9], 0, s[14:15]
	global_load_dword v167, v[8:9], off
	v_lshl_add_u64 v[8:9], v[8:9], 0, s[14:15]
	global_load_dword v169, v[8:9], off
	v_lshl_add_u64 v[8:9], v[8:9], 0, s[14:15]
	global_load_dword v171, v[8:9], off
	s_waitcnt vmcnt(63)
	v_readlane_b32 s6, v172, 0
	v_readlane_b32 s7, v173, 0
	v_readlane_b32 s8, v174, 0
	v_readlane_b32 s9, v175, 0
	v_readlane_b32 s10, v176, 0
	v_readlane_b32 s11, v177, 0
	v_readlane_b32 s12, v178, 0
	v_readlane_b32 s13, v179, 0
	v_readlane_b32 s22, v172, 1
	v_readlane_b32 s23, v173, 1
	v_readlane_b32 s24, v174, 1
	v_readlane_b32 s25, v175, 1
	v_readlane_b32 s26, v176, 1
	v_readlane_b32 s27, v177, 1
	v_readlane_b32 s30, v178, 1
	v_readlane_b32 s31, v179, 1
	v_pk_fma_f32 v[16:17], v[40:41], s[6:7], v[16:17] op_sel_hi:[0,1,1]
	v_pk_fma_f32 v[14:15], v[40:41], s[8:9], v[14:15] op_sel_hi:[0,1,1]
	v_pk_fma_f32 v[12:13], v[40:41], s[10:11], v[12:13] op_sel_hi:[0,1,1]
	v_pk_fma_f32 v[10:11], v[40:41], s[12:13], v[10:11] op_sel_hi:[0,1,1]
	v_readlane_b32 s6, v172, 2
	v_readlane_b32 s7, v173, 2
	v_readlane_b32 s8, v174, 2
	v_readlane_b32 s9, v175, 2
	v_readlane_b32 s10, v176, 2
	v_readlane_b32 s11, v177, 2
	v_readlane_b32 s12, v178, 2
	v_readlane_b32 s13, v179, 2
	v_pk_fma_f32 v[16:17], v[42:43], s[22:23], v[16:17] op_sel_hi:[0,1,1]
	v_pk_fma_f32 v[14:15], v[42:43], s[24:25], v[14:15] op_sel_hi:[0,1,1]
	v_pk_fma_f32 v[12:13], v[42:43], s[26:27], v[12:13] op_sel_hi:[0,1,1]
	v_pk_fma_f32 v[10:11], v[42:43], s[30:31], v[10:11] op_sel_hi:[0,1,1]
	v_readlane_b32 s22, v172, 3
	v_readlane_b32 s23, v173, 3
	v_readlane_b32 s24, v174, 3
	v_readlane_b32 s25, v175, 3
	v_readlane_b32 s26, v176, 3
	v_readlane_b32 s27, v177, 3
	v_readlane_b32 s30, v178, 3
	v_readlane_b32 s31, v179, 3
	v_pk_fma_f32 v[16:17], v[44:45], s[6:7], v[16:17] op_sel_hi:[0,1,1]
	v_pk_fma_f32 v[14:15], v[44:45], s[8:9], v[14:15] op_sel_hi:[0,1,1]
	v_pk_fma_f32 v[12:13], v[44:45], s[10:11], v[12:13] op_sel_hi:[0,1,1]
	v_pk_fma_f32 v[10:11], v[44:45], s[12:13], v[10:11] op_sel_hi:[0,1,1]
	v_readlane_b32 s6, v172, 4
	v_readlane_b32 s7, v173, 4
	v_readlane_b32 s8, v174, 4
	v_readlane_b32 s9, v175, 4
	v_readlane_b32 s10, v176, 4
	v_readlane_b32 s11, v177, 4
	v_readlane_b32 s12, v178, 4
	v_readlane_b32 s13, v179, 4
	v_pk_fma_f32 v[16:17], v[46:47], s[22:23], v[16:17] op_sel_hi:[0,1,1]
	v_pk_fma_f32 v[14:15], v[46:47], s[24:25], v[14:15] op_sel_hi:[0,1,1]
	v_pk_fma_f32 v[12:13], v[46:47], s[26:27], v[12:13] op_sel_hi:[0,1,1]
	v_pk_fma_f32 v[10:11], v[46:47], s[30:31], v[10:11] op_sel_hi:[0,1,1]
	v_readlane_b32 s22, v172, 5
	v_readlane_b32 s23, v173, 5
	v_readlane_b32 s24, v174, 5
	v_readlane_b32 s25, v175, 5
	v_readlane_b32 s26, v176, 5
	v_readlane_b32 s27, v177, 5
	v_readlane_b32 s30, v178, 5
	v_readlane_b32 s31, v179, 5
	v_pk_fma_f32 v[16:17], v[48:49], s[6:7], v[16:17] op_sel_hi:[0,1,1]
	v_pk_fma_f32 v[14:15], v[48:49], s[8:9], v[14:15] op_sel_hi:[0,1,1]
	v_pk_fma_f32 v[12:13], v[48:49], s[10:11], v[12:13] op_sel_hi:[0,1,1]
	v_pk_fma_f32 v[10:11], v[48:49], s[12:13], v[10:11] op_sel_hi:[0,1,1]
	v_readlane_b32 s6, v172, 6
	v_readlane_b32 s7, v173, 6
	v_readlane_b32 s8, v174, 6
	v_readlane_b32 s9, v175, 6
	v_readlane_b32 s10, v176, 6
	v_readlane_b32 s11, v177, 6
	v_readlane_b32 s12, v178, 6
	v_readlane_b32 s13, v179, 6
	v_pk_fma_f32 v[16:17], v[50:51], s[22:23], v[16:17] op_sel_hi:[0,1,1]
	v_pk_fma_f32 v[14:15], v[50:51], s[24:25], v[14:15] op_sel_hi:[0,1,1]
	v_pk_fma_f32 v[12:13], v[50:51], s[26:27], v[12:13] op_sel_hi:[0,1,1]
	v_pk_fma_f32 v[10:11], v[50:51], s[30:31], v[10:11] op_sel_hi:[0,1,1]
	v_readlane_b32 s22, v172, 7
	v_readlane_b32 s23, v173, 7
	v_readlane_b32 s24, v174, 7
	v_readlane_b32 s25, v175, 7
	v_readlane_b32 s26, v176, 7
	v_readlane_b32 s27, v177, 7
	v_readlane_b32 s30, v178, 7
	v_readlane_b32 s31, v179, 7
	v_pk_fma_f32 v[16:17], v[52:53], s[6:7], v[16:17] op_sel_hi:[0,1,1]
	v_pk_fma_f32 v[14:15], v[52:53], s[8:9], v[14:15] op_sel_hi:[0,1,1]
	v_pk_fma_f32 v[12:13], v[52:53], s[10:11], v[12:13] op_sel_hi:[0,1,1]
	v_pk_fma_f32 v[10:11], v[52:53], s[12:13], v[10:11] op_sel_hi:[0,1,1]
	v_readlane_b32 s6, v172, 8
	v_readlane_b32 s7, v173, 8
	v_readlane_b32 s8, v174, 8
	v_readlane_b32 s9, v175, 8
	v_readlane_b32 s10, v176, 8
	v_readlane_b32 s11, v177, 8
	v_readlane_b32 s12, v178, 8
	v_readlane_b32 s13, v179, 8
	v_pk_fma_f32 v[16:17], v[54:55], s[22:23], v[16:17] op_sel_hi:[0,1,1]
	v_pk_fma_f32 v[14:15], v[54:55], s[24:25], v[14:15] op_sel_hi:[0,1,1]
	v_pk_fma_f32 v[12:13], v[54:55], s[26:27], v[12:13] op_sel_hi:[0,1,1]
	v_pk_fma_f32 v[10:11], v[54:55], s[30:31], v[10:11] op_sel_hi:[0,1,1]
	v_readlane_b32 s22, v172, 9
	v_readlane_b32 s23, v173, 9
	v_readlane_b32 s24, v174, 9
	v_readlane_b32 s25, v175, 9
	v_readlane_b32 s26, v176, 9
	v_readlane_b32 s27, v177, 9
	v_readlane_b32 s30, v178, 9
	v_readlane_b32 s31, v179, 9
	v_pk_fma_f32 v[16:17], v[56:57], s[6:7], v[16:17] op_sel_hi:[0,1,1]
	v_pk_fma_f32 v[14:15], v[56:57], s[8:9], v[14:15] op_sel_hi:[0,1,1]
	v_pk_fma_f32 v[12:13], v[56:57], s[10:11], v[12:13] op_sel_hi:[0,1,1]
	v_pk_fma_f32 v[10:11], v[56:57], s[12:13], v[10:11] op_sel_hi:[0,1,1]
	v_readlane_b32 s6, v172, 10
	v_readlane_b32 s7, v173, 10
	v_readlane_b32 s8, v174, 10
	v_readlane_b32 s9, v175, 10
	v_readlane_b32 s10, v176, 10
	v_readlane_b32 s11, v177, 10
	v_readlane_b32 s12, v178, 10
	v_readlane_b32 s13, v179, 10
	v_pk_fma_f32 v[16:17], v[58:59], s[22:23], v[16:17] op_sel_hi:[0,1,1]
	v_pk_fma_f32 v[14:15], v[58:59], s[24:25], v[14:15] op_sel_hi:[0,1,1]
	v_pk_fma_f32 v[12:13], v[58:59], s[26:27], v[12:13] op_sel_hi:[0,1,1]
	v_pk_fma_f32 v[10:11], v[58:59], s[30:31], v[10:11] op_sel_hi:[0,1,1]
	v_readlane_b32 s22, v172, 11
	v_readlane_b32 s23, v173, 11
	v_readlane_b32 s24, v174, 11
	v_readlane_b32 s25, v175, 11
	v_readlane_b32 s26, v176, 11
	v_readlane_b32 s27, v177, 11
	v_readlane_b32 s30, v178, 11
	v_readlane_b32 s31, v179, 11
	v_pk_fma_f32 v[16:17], v[60:61], s[6:7], v[16:17] op_sel_hi:[0,1,1]
	v_pk_fma_f32 v[14:15], v[60:61], s[8:9], v[14:15] op_sel_hi:[0,1,1]
	v_pk_fma_f32 v[12:13], v[60:61], s[10:11], v[12:13] op_sel_hi:[0,1,1]
	v_pk_fma_f32 v[10:11], v[60:61], s[12:13], v[10:11] op_sel_hi:[0,1,1]
	v_readlane_b32 s6, v172, 12
	v_readlane_b32 s7, v173, 12
	v_readlane_b32 s8, v174, 12
	v_readlane_b32 s9, v175, 12
	v_readlane_b32 s10, v176, 12
	v_readlane_b32 s11, v177, 12
	v_readlane_b32 s12, v178, 12
	v_readlane_b32 s13, v179, 12
	v_pk_fma_f32 v[16:17], v[62:63], s[22:23], v[16:17] op_sel_hi:[0,1,1]
	v_pk_fma_f32 v[14:15], v[62:63], s[24:25], v[14:15] op_sel_hi:[0,1,1]
	v_pk_fma_f32 v[12:13], v[62:63], s[26:27], v[12:13] op_sel_hi:[0,1,1]
	v_pk_fma_f32 v[10:11], v[62:63], s[30:31], v[10:11] op_sel_hi:[0,1,1]
	v_readlane_b32 s22, v172, 13
	v_readlane_b32 s23, v173, 13
	v_readlane_b32 s24, v174, 13
	v_readlane_b32 s25, v175, 13
	v_readlane_b32 s26, v176, 13
	v_readlane_b32 s27, v177, 13
	v_readlane_b32 s30, v178, 13
	v_readlane_b32 s31, v179, 13
	v_pk_fma_f32 v[16:17], v[64:65], s[6:7], v[16:17] op_sel_hi:[0,1,1]
	v_pk_fma_f32 v[14:15], v[64:65], s[8:9], v[14:15] op_sel_hi:[0,1,1]
	v_pk_fma_f32 v[12:13], v[64:65], s[10:11], v[12:13] op_sel_hi:[0,1,1]
	v_pk_fma_f32 v[10:11], v[64:65], s[12:13], v[10:11] op_sel_hi:[0,1,1]
	v_readlane_b32 s6, v172, 14
	v_readlane_b32 s7, v173, 14
	v_readlane_b32 s8, v174, 14
	v_readlane_b32 s9, v175, 14
	v_readlane_b32 s10, v176, 14
	v_readlane_b32 s11, v177, 14
	v_readlane_b32 s12, v178, 14
	v_readlane_b32 s13, v179, 14
	v_pk_fma_f32 v[16:17], v[66:67], s[22:23], v[16:17] op_sel_hi:[0,1,1]
	v_pk_fma_f32 v[14:15], v[66:67], s[24:25], v[14:15] op_sel_hi:[0,1,1]
	v_pk_fma_f32 v[12:13], v[66:67], s[26:27], v[12:13] op_sel_hi:[0,1,1]
	v_pk_fma_f32 v[10:11], v[66:67], s[30:31], v[10:11] op_sel_hi:[0,1,1]
	v_readlane_b32 s22, v172, 15
	v_readlane_b32 s23, v173, 15
	v_readlane_b32 s24, v174, 15
	v_readlane_b32 s25, v175, 15
	v_readlane_b32 s26, v176, 15
	v_readlane_b32 s27, v177, 15
	v_readlane_b32 s30, v178, 15
	v_readlane_b32 s31, v179, 15
	v_pk_fma_f32 v[16:17], v[68:69], s[6:7], v[16:17] op_sel_hi:[0,1,1]
	v_pk_fma_f32 v[14:15], v[68:69], s[8:9], v[14:15] op_sel_hi:[0,1,1]
	v_pk_fma_f32 v[12:13], v[68:69], s[10:11], v[12:13] op_sel_hi:[0,1,1]
	v_pk_fma_f32 v[10:11], v[68:69], s[12:13], v[10:11] op_sel_hi:[0,1,1]
	v_readlane_b32 s6, v172, 16
	v_readlane_b32 s7, v173, 16
	v_readlane_b32 s8, v174, 16
	v_readlane_b32 s9, v175, 16
	v_readlane_b32 s10, v176, 16
	v_readlane_b32 s11, v177, 16
	v_readlane_b32 s12, v178, 16
	v_readlane_b32 s13, v179, 16
	v_pk_fma_f32 v[16:17], v[70:71], s[22:23], v[16:17] op_sel_hi:[0,1,1]
	v_pk_fma_f32 v[14:15], v[70:71], s[24:25], v[14:15] op_sel_hi:[0,1,1]
	v_pk_fma_f32 v[12:13], v[70:71], s[26:27], v[12:13] op_sel_hi:[0,1,1]
	v_pk_fma_f32 v[10:11], v[70:71], s[30:31], v[10:11] op_sel_hi:[0,1,1]
	v_readlane_b32 s22, v172, 17
	v_readlane_b32 s23, v173, 17
	v_readlane_b32 s24, v174, 17
	v_readlane_b32 s25, v175, 17
	v_readlane_b32 s26, v176, 17
	v_readlane_b32 s27, v177, 17
	v_readlane_b32 s30, v178, 17
	v_readlane_b32 s31, v179, 17
	v_pk_fma_f32 v[16:17], v[72:73], s[6:7], v[16:17] op_sel_hi:[0,1,1]
	v_pk_fma_f32 v[14:15], v[72:73], s[8:9], v[14:15] op_sel_hi:[0,1,1]
	v_pk_fma_f32 v[12:13], v[72:73], s[10:11], v[12:13] op_sel_hi:[0,1,1]
	v_pk_fma_f32 v[10:11], v[72:73], s[12:13], v[10:11] op_sel_hi:[0,1,1]
	v_readlane_b32 s6, v172, 18
	v_readlane_b32 s7, v173, 18
	v_readlane_b32 s8, v174, 18
	v_readlane_b32 s9, v175, 18
	v_readlane_b32 s10, v176, 18
	v_readlane_b32 s11, v177, 18
	v_readlane_b32 s12, v178, 18
	v_readlane_b32 s13, v179, 18
	v_pk_fma_f32 v[16:17], v[74:75], s[22:23], v[16:17] op_sel_hi:[0,1,1]
	v_pk_fma_f32 v[14:15], v[74:75], s[24:25], v[14:15] op_sel_hi:[0,1,1]
	v_pk_fma_f32 v[12:13], v[74:75], s[26:27], v[12:13] op_sel_hi:[0,1,1]
	v_pk_fma_f32 v[10:11], v[74:75], s[30:31], v[10:11] op_sel_hi:[0,1,1]
	v_readlane_b32 s22, v172, 19
	v_readlane_b32 s23, v173, 19
	v_readlane_b32 s24, v174, 19
	v_readlane_b32 s25, v175, 19
	v_readlane_b32 s26, v176, 19
	v_readlane_b32 s27, v177, 19
	v_readlane_b32 s30, v178, 19
	v_readlane_b32 s31, v179, 19
	v_pk_fma_f32 v[16:17], v[76:77], s[6:7], v[16:17] op_sel_hi:[0,1,1]
	v_pk_fma_f32 v[14:15], v[76:77], s[8:9], v[14:15] op_sel_hi:[0,1,1]
	v_pk_fma_f32 v[12:13], v[76:77], s[10:11], v[12:13] op_sel_hi:[0,1,1]
	v_pk_fma_f32 v[10:11], v[76:77], s[12:13], v[10:11] op_sel_hi:[0,1,1]
	v_readlane_b32 s6, v172, 20
	v_readlane_b32 s7, v173, 20
	v_readlane_b32 s8, v174, 20
	v_readlane_b32 s9, v175, 20
	v_readlane_b32 s10, v176, 20
	v_readlane_b32 s11, v177, 20
	v_readlane_b32 s12, v178, 20
	v_readlane_b32 s13, v179, 20
	v_pk_fma_f32 v[16:17], v[78:79], s[22:23], v[16:17] op_sel_hi:[0,1,1]
	v_pk_fma_f32 v[14:15], v[78:79], s[24:25], v[14:15] op_sel_hi:[0,1,1]
	v_pk_fma_f32 v[12:13], v[78:79], s[26:27], v[12:13] op_sel_hi:[0,1,1]
	v_pk_fma_f32 v[10:11], v[78:79], s[30:31], v[10:11] op_sel_hi:[0,1,1]
	v_readlane_b32 s22, v172, 21
	v_readlane_b32 s23, v173, 21
	v_readlane_b32 s24, v174, 21
	v_readlane_b32 s25, v175, 21
	v_readlane_b32 s26, v176, 21
	v_readlane_b32 s27, v177, 21
	v_readlane_b32 s30, v178, 21
	v_readlane_b32 s31, v179, 21
	v_pk_fma_f32 v[16:17], v[80:81], s[6:7], v[16:17] op_sel_hi:[0,1,1]
	v_pk_fma_f32 v[14:15], v[80:81], s[8:9], v[14:15] op_sel_hi:[0,1,1]
	v_pk_fma_f32 v[12:13], v[80:81], s[10:11], v[12:13] op_sel_hi:[0,1,1]
	v_pk_fma_f32 v[10:11], v[80:81], s[12:13], v[10:11] op_sel_hi:[0,1,1]
	v_readlane_b32 s6, v172, 22
	v_readlane_b32 s7, v173, 22
	v_readlane_b32 s8, v174, 22
	v_readlane_b32 s9, v175, 22
	v_readlane_b32 s10, v176, 22
	v_readlane_b32 s11, v177, 22
	v_readlane_b32 s12, v178, 22
	v_readlane_b32 s13, v179, 22
	v_pk_fma_f32 v[16:17], v[82:83], s[22:23], v[16:17] op_sel_hi:[0,1,1]
	v_pk_fma_f32 v[14:15], v[82:83], s[24:25], v[14:15] op_sel_hi:[0,1,1]
	v_pk_fma_f32 v[12:13], v[82:83], s[26:27], v[12:13] op_sel_hi:[0,1,1]
	v_pk_fma_f32 v[10:11], v[82:83], s[30:31], v[10:11] op_sel_hi:[0,1,1]
	v_readlane_b32 s22, v172, 23
	v_readlane_b32 s23, v173, 23
	v_readlane_b32 s24, v174, 23
	v_readlane_b32 s25, v175, 23
	v_readlane_b32 s26, v176, 23
	v_readlane_b32 s27, v177, 23
	v_readlane_b32 s30, v178, 23
	v_readlane_b32 s31, v179, 23
	v_pk_fma_f32 v[16:17], v[84:85], s[6:7], v[16:17] op_sel_hi:[0,1,1]
	v_pk_fma_f32 v[14:15], v[84:85], s[8:9], v[14:15] op_sel_hi:[0,1,1]
	v_pk_fma_f32 v[12:13], v[84:85], s[10:11], v[12:13] op_sel_hi:[0,1,1]
	v_pk_fma_f32 v[10:11], v[84:85], s[12:13], v[10:11] op_sel_hi:[0,1,1]
	v_readlane_b32 s6, v172, 24
	v_readlane_b32 s7, v173, 24
	v_readlane_b32 s8, v174, 24
	v_readlane_b32 s9, v175, 24
	v_readlane_b32 s10, v176, 24
	v_readlane_b32 s11, v177, 24
	v_readlane_b32 s12, v178, 24
	v_readlane_b32 s13, v179, 24
	v_pk_fma_f32 v[16:17], v[86:87], s[22:23], v[16:17] op_sel_hi:[0,1,1]
	v_pk_fma_f32 v[14:15], v[86:87], s[24:25], v[14:15] op_sel_hi:[0,1,1]
	v_pk_fma_f32 v[12:13], v[86:87], s[26:27], v[12:13] op_sel_hi:[0,1,1]
	v_pk_fma_f32 v[10:11], v[86:87], s[30:31], v[10:11] op_sel_hi:[0,1,1]
	v_readlane_b32 s22, v172, 25
	v_readlane_b32 s23, v173, 25
	v_readlane_b32 s24, v174, 25
	v_readlane_b32 s25, v175, 25
	v_readlane_b32 s26, v176, 25
	v_readlane_b32 s27, v177, 25
	v_readlane_b32 s30, v178, 25
	v_readlane_b32 s31, v179, 25
	v_pk_fma_f32 v[16:17], v[88:89], s[6:7], v[16:17] op_sel_hi:[0,1,1]
	v_pk_fma_f32 v[14:15], v[88:89], s[8:9], v[14:15] op_sel_hi:[0,1,1]
	v_pk_fma_f32 v[12:13], v[88:89], s[10:11], v[12:13] op_sel_hi:[0,1,1]
	v_pk_fma_f32 v[10:11], v[88:89], s[12:13], v[10:11] op_sel_hi:[0,1,1]
	v_readlane_b32 s6, v172, 26
	v_readlane_b32 s7, v173, 26
	v_readlane_b32 s8, v174, 26
	v_readlane_b32 s9, v175, 26
	v_readlane_b32 s10, v176, 26
	v_readlane_b32 s11, v177, 26
	v_readlane_b32 s12, v178, 26
	v_readlane_b32 s13, v179, 26
	v_pk_fma_f32 v[16:17], v[90:91], s[22:23], v[16:17] op_sel_hi:[0,1,1]
	v_pk_fma_f32 v[14:15], v[90:91], s[24:25], v[14:15] op_sel_hi:[0,1,1]
	v_pk_fma_f32 v[12:13], v[90:91], s[26:27], v[12:13] op_sel_hi:[0,1,1]
	v_pk_fma_f32 v[10:11], v[90:91], s[30:31], v[10:11] op_sel_hi:[0,1,1]
	v_readlane_b32 s22, v172, 27
	v_readlane_b32 s23, v173, 27
	v_readlane_b32 s24, v174, 27
	v_readlane_b32 s25, v175, 27
	v_readlane_b32 s26, v176, 27
	v_readlane_b32 s27, v177, 27
	v_readlane_b32 s30, v178, 27
	v_readlane_b32 s31, v179, 27
	v_pk_fma_f32 v[16:17], v[92:93], s[6:7], v[16:17] op_sel_hi:[0,1,1]
	v_pk_fma_f32 v[14:15], v[92:93], s[8:9], v[14:15] op_sel_hi:[0,1,1]
	v_pk_fma_f32 v[12:13], v[92:93], s[10:11], v[12:13] op_sel_hi:[0,1,1]
	v_pk_fma_f32 v[10:11], v[92:93], s[12:13], v[10:11] op_sel_hi:[0,1,1]
	v_readlane_b32 s6, v172, 28
	v_readlane_b32 s7, v173, 28
	v_readlane_b32 s8, v174, 28
	v_readlane_b32 s9, v175, 28
	v_readlane_b32 s10, v176, 28
	v_readlane_b32 s11, v177, 28
	v_readlane_b32 s12, v178, 28
	v_readlane_b32 s13, v179, 28
	v_pk_fma_f32 v[16:17], v[94:95], s[22:23], v[16:17] op_sel_hi:[0,1,1]
	v_pk_fma_f32 v[14:15], v[94:95], s[24:25], v[14:15] op_sel_hi:[0,1,1]
	v_pk_fma_f32 v[12:13], v[94:95], s[26:27], v[12:13] op_sel_hi:[0,1,1]
	v_pk_fma_f32 v[10:11], v[94:95], s[30:31], v[10:11] op_sel_hi:[0,1,1]
	v_readlane_b32 s22, v172, 29
	v_readlane_b32 s23, v173, 29
	v_readlane_b32 s24, v174, 29
	v_readlane_b32 s25, v175, 29
	v_readlane_b32 s26, v176, 29
	v_readlane_b32 s27, v177, 29
	v_readlane_b32 s30, v178, 29
	v_readlane_b32 s31, v179, 29
	v_pk_fma_f32 v[16:17], v[96:97], s[6:7], v[16:17] op_sel_hi:[0,1,1]
	v_pk_fma_f32 v[14:15], v[96:97], s[8:9], v[14:15] op_sel_hi:[0,1,1]
	v_pk_fma_f32 v[12:13], v[96:97], s[10:11], v[12:13] op_sel_hi:[0,1,1]
	v_pk_fma_f32 v[10:11], v[96:97], s[12:13], v[10:11] op_sel_hi:[0,1,1]
	v_readlane_b32 s6, v172, 30
	v_readlane_b32 s7, v173, 30
	v_readlane_b32 s8, v174, 30
	v_readlane_b32 s9, v175, 30
	v_readlane_b32 s10, v176, 30
	v_readlane_b32 s11, v177, 30
	v_readlane_b32 s12, v178, 30
	v_readlane_b32 s13, v179, 30
	v_pk_fma_f32 v[16:17], v[98:99], s[22:23], v[16:17] op_sel_hi:[0,1,1]
	v_pk_fma_f32 v[14:15], v[98:99], s[24:25], v[14:15] op_sel_hi:[0,1,1]
	v_pk_fma_f32 v[12:13], v[98:99], s[26:27], v[12:13] op_sel_hi:[0,1,1]
	v_pk_fma_f32 v[10:11], v[98:99], s[30:31], v[10:11] op_sel_hi:[0,1,1]
	v_readlane_b32 s22, v172, 31
	v_readlane_b32 s23, v173, 31
	v_readlane_b32 s24, v174, 31
	v_readlane_b32 s25, v175, 31
	v_readlane_b32 s26, v176, 31
	v_readlane_b32 s27, v177, 31
	v_readlane_b32 s30, v178, 31
	v_readlane_b32 s31, v179, 31
	v_pk_fma_f32 v[16:17], v[100:101], s[6:7], v[16:17] op_sel_hi:[0,1,1]
	v_pk_fma_f32 v[14:15], v[100:101], s[8:9], v[14:15] op_sel_hi:[0,1,1]
	v_pk_fma_f32 v[12:13], v[100:101], s[10:11], v[12:13] op_sel_hi:[0,1,1]
	v_pk_fma_f32 v[10:11], v[100:101], s[12:13], v[10:11] op_sel_hi:[0,1,1]
	v_readlane_b32 s6, v172, 32
	v_readlane_b32 s7, v173, 32
	v_readlane_b32 s8, v174, 32
	v_readlane_b32 s9, v175, 32
	v_readlane_b32 s10, v176, 32
	v_readlane_b32 s11, v177, 32
	v_readlane_b32 s12, v178, 32
	v_readlane_b32 s13, v179, 32
	v_pk_fma_f32 v[16:17], v[102:103], s[22:23], v[16:17] op_sel_hi:[0,1,1]
	v_pk_fma_f32 v[14:15], v[102:103], s[24:25], v[14:15] op_sel_hi:[0,1,1]
	v_pk_fma_f32 v[12:13], v[102:103], s[26:27], v[12:13] op_sel_hi:[0,1,1]
	v_pk_fma_f32 v[10:11], v[102:103], s[30:31], v[10:11] op_sel_hi:[0,1,1]
	v_readlane_b32 s22, v172, 33
	v_readlane_b32 s23, v173, 33
	v_readlane_b32 s24, v174, 33
	v_readlane_b32 s25, v175, 33
	v_readlane_b32 s26, v176, 33
	v_readlane_b32 s27, v177, 33
	v_readlane_b32 s30, v178, 33
	v_readlane_b32 s31, v179, 33
	v_pk_fma_f32 v[16:17], v[104:105], s[6:7], v[16:17] op_sel_hi:[0,1,1]
	v_pk_fma_f32 v[14:15], v[104:105], s[8:9], v[14:15] op_sel_hi:[0,1,1]
	v_pk_fma_f32 v[12:13], v[104:105], s[10:11], v[12:13] op_sel_hi:[0,1,1]
	v_pk_fma_f32 v[10:11], v[104:105], s[12:13], v[10:11] op_sel_hi:[0,1,1]
	v_readlane_b32 s6, v172, 34
	v_readlane_b32 s7, v173, 34
	v_readlane_b32 s8, v174, 34
	v_readlane_b32 s9, v175, 34
	v_readlane_b32 s10, v176, 34
	v_readlane_b32 s11, v177, 34
	v_readlane_b32 s12, v178, 34
	v_readlane_b32 s13, v179, 34
	v_pk_fma_f32 v[16:17], v[106:107], s[22:23], v[16:17] op_sel_hi:[0,1,1]
	v_pk_fma_f32 v[14:15], v[106:107], s[24:25], v[14:15] op_sel_hi:[0,1,1]
	v_pk_fma_f32 v[12:13], v[106:107], s[26:27], v[12:13] op_sel_hi:[0,1,1]
	v_pk_fma_f32 v[10:11], v[106:107], s[30:31], v[10:11] op_sel_hi:[0,1,1]
	v_readlane_b32 s22, v172, 35
	v_readlane_b32 s23, v173, 35
	v_readlane_b32 s24, v174, 35
	v_readlane_b32 s25, v175, 35
	v_readlane_b32 s26, v176, 35
	v_readlane_b32 s27, v177, 35
	v_readlane_b32 s30, v178, 35
	v_readlane_b32 s31, v179, 35
	v_pk_fma_f32 v[16:17], v[108:109], s[6:7], v[16:17] op_sel_hi:[0,1,1]
	v_pk_fma_f32 v[14:15], v[108:109], s[8:9], v[14:15] op_sel_hi:[0,1,1]
	v_pk_fma_f32 v[12:13], v[108:109], s[10:11], v[12:13] op_sel_hi:[0,1,1]
	v_pk_fma_f32 v[10:11], v[108:109], s[12:13], v[10:11] op_sel_hi:[0,1,1]
	v_readlane_b32 s6, v172, 36
	v_readlane_b32 s7, v173, 36
	v_readlane_b32 s8, v174, 36
	v_readlane_b32 s9, v175, 36
	v_readlane_b32 s10, v176, 36
	v_readlane_b32 s11, v177, 36
	v_readlane_b32 s12, v178, 36
	v_readlane_b32 s13, v179, 36
	v_pk_fma_f32 v[16:17], v[110:111], s[22:23], v[16:17] op_sel_hi:[0,1,1]
	v_pk_fma_f32 v[14:15], v[110:111], s[24:25], v[14:15] op_sel_hi:[0,1,1]
	v_pk_fma_f32 v[12:13], v[110:111], s[26:27], v[12:13] op_sel_hi:[0,1,1]
	v_pk_fma_f32 v[10:11], v[110:111], s[30:31], v[10:11] op_sel_hi:[0,1,1]
	v_readlane_b32 s22, v172, 37
	v_readlane_b32 s23, v173, 37
	v_readlane_b32 s24, v174, 37
	v_readlane_b32 s25, v175, 37
	v_readlane_b32 s26, v176, 37
	v_readlane_b32 s27, v177, 37
	v_readlane_b32 s30, v178, 37
	v_readlane_b32 s31, v179, 37
	v_pk_fma_f32 v[16:17], v[112:113], s[6:7], v[16:17] op_sel_hi:[0,1,1]
	v_pk_fma_f32 v[14:15], v[112:113], s[8:9], v[14:15] op_sel_hi:[0,1,1]
	v_pk_fma_f32 v[12:13], v[112:113], s[10:11], v[12:13] op_sel_hi:[0,1,1]
	v_pk_fma_f32 v[10:11], v[112:113], s[12:13], v[10:11] op_sel_hi:[0,1,1]
	v_readlane_b32 s6, v172, 38
	v_readlane_b32 s7, v173, 38
	v_readlane_b32 s8, v174, 38
	v_readlane_b32 s9, v175, 38
	v_readlane_b32 s10, v176, 38
	v_readlane_b32 s11, v177, 38
	v_readlane_b32 s12, v178, 38
	v_readlane_b32 s13, v179, 38
	v_pk_fma_f32 v[16:17], v[114:115], s[22:23], v[16:17] op_sel_hi:[0,1,1]
	v_pk_fma_f32 v[14:15], v[114:115], s[24:25], v[14:15] op_sel_hi:[0,1,1]
	v_pk_fma_f32 v[12:13], v[114:115], s[26:27], v[12:13] op_sel_hi:[0,1,1]
	v_pk_fma_f32 v[10:11], v[114:115], s[30:31], v[10:11] op_sel_hi:[0,1,1]
	v_readlane_b32 s22, v172, 39
	v_readlane_b32 s23, v173, 39
	v_readlane_b32 s24, v174, 39
	v_readlane_b32 s25, v175, 39
	v_readlane_b32 s26, v176, 39
	v_readlane_b32 s27, v177, 39
	v_readlane_b32 s30, v178, 39
	v_readlane_b32 s31, v179, 39
	v_pk_fma_f32 v[16:17], v[116:117], s[6:7], v[16:17] op_sel_hi:[0,1,1]
	v_pk_fma_f32 v[14:15], v[116:117], s[8:9], v[14:15] op_sel_hi:[0,1,1]
	v_pk_fma_f32 v[12:13], v[116:117], s[10:11], v[12:13] op_sel_hi:[0,1,1]
	v_pk_fma_f32 v[10:11], v[116:117], s[12:13], v[10:11] op_sel_hi:[0,1,1]
	v_readlane_b32 s6, v172, 40
	v_readlane_b32 s7, v173, 40
	v_readlane_b32 s8, v174, 40
	v_readlane_b32 s9, v175, 40
	v_readlane_b32 s10, v176, 40
	v_readlane_b32 s11, v177, 40
	v_readlane_b32 s12, v178, 40
	v_readlane_b32 s13, v179, 40
	v_pk_fma_f32 v[16:17], v[118:119], s[22:23], v[16:17] op_sel_hi:[0,1,1]
	v_pk_fma_f32 v[14:15], v[118:119], s[24:25], v[14:15] op_sel_hi:[0,1,1]
	v_pk_fma_f32 v[12:13], v[118:119], s[26:27], v[12:13] op_sel_hi:[0,1,1]
	v_pk_fma_f32 v[10:11], v[118:119], s[30:31], v[10:11] op_sel_hi:[0,1,1]
	v_readlane_b32 s22, v172, 41
	v_readlane_b32 s23, v173, 41
	v_readlane_b32 s24, v174, 41
	v_readlane_b32 s25, v175, 41
	v_readlane_b32 s26, v176, 41
	v_readlane_b32 s27, v177, 41
	v_readlane_b32 s30, v178, 41
	v_readlane_b32 s31, v179, 41
	v_pk_fma_f32 v[16:17], v[120:121], s[6:7], v[16:17] op_sel_hi:[0,1,1]
	v_pk_fma_f32 v[14:15], v[120:121], s[8:9], v[14:15] op_sel_hi:[0,1,1]
	v_pk_fma_f32 v[12:13], v[120:121], s[10:11], v[12:13] op_sel_hi:[0,1,1]
	v_pk_fma_f32 v[10:11], v[120:121], s[12:13], v[10:11] op_sel_hi:[0,1,1]
	v_readlane_b32 s6, v172, 42
	v_readlane_b32 s7, v173, 42
	v_readlane_b32 s8, v174, 42
	v_readlane_b32 s9, v175, 42
	v_readlane_b32 s10, v176, 42
	v_readlane_b32 s11, v177, 42
	v_readlane_b32 s12, v178, 42
	v_readlane_b32 s13, v179, 42
	v_pk_fma_f32 v[16:17], v[122:123], s[22:23], v[16:17] op_sel_hi:[0,1,1]
	v_pk_fma_f32 v[14:15], v[122:123], s[24:25], v[14:15] op_sel_hi:[0,1,1]
	v_pk_fma_f32 v[12:13], v[122:123], s[26:27], v[12:13] op_sel_hi:[0,1,1]
	v_pk_fma_f32 v[10:11], v[122:123], s[30:31], v[10:11] op_sel_hi:[0,1,1]
	v_readlane_b32 s22, v172, 43
	v_readlane_b32 s23, v173, 43
	v_readlane_b32 s24, v174, 43
	v_readlane_b32 s25, v175, 43
	v_readlane_b32 s26, v176, 43
	v_readlane_b32 s27, v177, 43
	v_readlane_b32 s30, v178, 43
	v_readlane_b32 s31, v179, 43
	v_pk_fma_f32 v[16:17], v[124:125], s[6:7], v[16:17] op_sel_hi:[0,1,1]
	v_pk_fma_f32 v[14:15], v[124:125], s[8:9], v[14:15] op_sel_hi:[0,1,1]
	v_pk_fma_f32 v[12:13], v[124:125], s[10:11], v[12:13] op_sel_hi:[0,1,1]
	v_pk_fma_f32 v[10:11], v[124:125], s[12:13], v[10:11] op_sel_hi:[0,1,1]
	v_readlane_b32 s6, v172, 44
	v_readlane_b32 s7, v173, 44
	v_readlane_b32 s8, v174, 44
	v_readlane_b32 s9, v175, 44
	v_readlane_b32 s10, v176, 44
	v_readlane_b32 s11, v177, 44
	v_readlane_b32 s12, v178, 44
	v_readlane_b32 s13, v179, 44
	v_pk_fma_f32 v[16:17], v[126:127], s[22:23], v[16:17] op_sel_hi:[0,1,1]
	v_pk_fma_f32 v[14:15], v[126:127], s[24:25], v[14:15] op_sel_hi:[0,1,1]
	v_pk_fma_f32 v[12:13], v[126:127], s[26:27], v[12:13] op_sel_hi:[0,1,1]
	v_pk_fma_f32 v[10:11], v[126:127], s[30:31], v[10:11] op_sel_hi:[0,1,1]
	v_readlane_b32 s22, v172, 45
	v_readlane_b32 s23, v173, 45
	v_readlane_b32 s24, v174, 45
	v_readlane_b32 s25, v175, 45
	v_readlane_b32 s26, v176, 45
	v_readlane_b32 s27, v177, 45
	v_readlane_b32 s30, v178, 45
	v_readlane_b32 s31, v179, 45
	v_pk_fma_f32 v[16:17], v[128:129], s[6:7], v[16:17] op_sel_hi:[0,1,1]
	v_pk_fma_f32 v[14:15], v[128:129], s[8:9], v[14:15] op_sel_hi:[0,1,1]
	v_pk_fma_f32 v[12:13], v[128:129], s[10:11], v[12:13] op_sel_hi:[0,1,1]
	v_pk_fma_f32 v[10:11], v[128:129], s[12:13], v[10:11] op_sel_hi:[0,1,1]
	v_readlane_b32 s6, v172, 46
	v_readlane_b32 s7, v173, 46
	v_readlane_b32 s8, v174, 46
	v_readlane_b32 s9, v175, 46
	v_readlane_b32 s10, v176, 46
	v_readlane_b32 s11, v177, 46
	v_readlane_b32 s12, v178, 46
	v_readlane_b32 s13, v179, 46
	v_pk_fma_f32 v[16:17], v[130:131], s[22:23], v[16:17] op_sel_hi:[0,1,1]
	v_pk_fma_f32 v[14:15], v[130:131], s[24:25], v[14:15] op_sel_hi:[0,1,1]
	v_pk_fma_f32 v[12:13], v[130:131], s[26:27], v[12:13] op_sel_hi:[0,1,1]
	v_pk_fma_f32 v[10:11], v[130:131], s[30:31], v[10:11] op_sel_hi:[0,1,1]
	v_readlane_b32 s22, v172, 47
	v_readlane_b32 s23, v173, 47
	v_readlane_b32 s24, v174, 47
	v_readlane_b32 s25, v175, 47
	v_readlane_b32 s26, v176, 47
	v_readlane_b32 s27, v177, 47
	v_readlane_b32 s30, v178, 47
	v_readlane_b32 s31, v179, 47
	v_pk_fma_f32 v[16:17], v[132:133], s[6:7], v[16:17] op_sel_hi:[0,1,1]
	v_pk_fma_f32 v[14:15], v[132:133], s[8:9], v[14:15] op_sel_hi:[0,1,1]
	v_pk_fma_f32 v[12:13], v[132:133], s[10:11], v[12:13] op_sel_hi:[0,1,1]
	v_pk_fma_f32 v[10:11], v[132:133], s[12:13], v[10:11] op_sel_hi:[0,1,1]
	v_readlane_b32 s6, v172, 48
	v_readlane_b32 s7, v173, 48
	v_readlane_b32 s8, v174, 48
	v_readlane_b32 s9, v175, 48
	v_readlane_b32 s10, v176, 48
	v_readlane_b32 s11, v177, 48
	v_readlane_b32 s12, v178, 48
	v_readlane_b32 s13, v179, 48
	v_pk_fma_f32 v[16:17], v[134:135], s[22:23], v[16:17] op_sel_hi:[0,1,1]
	v_pk_fma_f32 v[14:15], v[134:135], s[24:25], v[14:15] op_sel_hi:[0,1,1]
	v_pk_fma_f32 v[12:13], v[134:135], s[26:27], v[12:13] op_sel_hi:[0,1,1]
	v_pk_fma_f32 v[10:11], v[134:135], s[30:31], v[10:11] op_sel_hi:[0,1,1]
	v_readlane_b32 s22, v172, 49
	v_readlane_b32 s23, v173, 49
	v_readlane_b32 s24, v174, 49
	v_readlane_b32 s25, v175, 49
	v_readlane_b32 s26, v176, 49
	v_readlane_b32 s27, v177, 49
	v_readlane_b32 s30, v178, 49
	v_readlane_b32 s31, v179, 49
	v_pk_fma_f32 v[16:17], v[136:137], s[6:7], v[16:17] op_sel_hi:[0,1,1]
	v_pk_fma_f32 v[14:15], v[136:137], s[8:9], v[14:15] op_sel_hi:[0,1,1]
	v_pk_fma_f32 v[12:13], v[136:137], s[10:11], v[12:13] op_sel_hi:[0,1,1]
	v_pk_fma_f32 v[10:11], v[136:137], s[12:13], v[10:11] op_sel_hi:[0,1,1]
	v_readlane_b32 s6, v172, 50
	v_readlane_b32 s7, v173, 50
	v_readlane_b32 s8, v174, 50
	v_readlane_b32 s9, v175, 50
	v_readlane_b32 s10, v176, 50
	v_readlane_b32 s11, v177, 50
	v_readlane_b32 s12, v178, 50
	v_readlane_b32 s13, v179, 50
	v_pk_fma_f32 v[16:17], v[138:139], s[22:23], v[16:17] op_sel_hi:[0,1,1]
	v_pk_fma_f32 v[14:15], v[138:139], s[24:25], v[14:15] op_sel_hi:[0,1,1]
	v_pk_fma_f32 v[12:13], v[138:139], s[26:27], v[12:13] op_sel_hi:[0,1,1]
	v_pk_fma_f32 v[10:11], v[138:139], s[30:31], v[10:11] op_sel_hi:[0,1,1]
	v_readlane_b32 s22, v172, 51
	v_readlane_b32 s23, v173, 51
	v_readlane_b32 s24, v174, 51
	v_readlane_b32 s25, v175, 51
	v_readlane_b32 s26, v176, 51
	v_readlane_b32 s27, v177, 51
	v_readlane_b32 s30, v178, 51
	v_readlane_b32 s31, v179, 51
	v_pk_fma_f32 v[16:17], v[140:141], s[6:7], v[16:17] op_sel_hi:[0,1,1]
	v_pk_fma_f32 v[14:15], v[140:141], s[8:9], v[14:15] op_sel_hi:[0,1,1]
	v_pk_fma_f32 v[12:13], v[140:141], s[10:11], v[12:13] op_sel_hi:[0,1,1]
	v_pk_fma_f32 v[10:11], v[140:141], s[12:13], v[10:11] op_sel_hi:[0,1,1]
	v_readlane_b32 s6, v172, 52
	v_readlane_b32 s7, v173, 52
	v_readlane_b32 s8, v174, 52
	v_readlane_b32 s9, v175, 52
	v_readlane_b32 s10, v176, 52
	v_readlane_b32 s11, v177, 52
	v_readlane_b32 s12, v178, 52
	v_readlane_b32 s13, v179, 52
	v_pk_fma_f32 v[16:17], v[142:143], s[22:23], v[16:17] op_sel_hi:[0,1,1]
	v_pk_fma_f32 v[14:15], v[142:143], s[24:25], v[14:15] op_sel_hi:[0,1,1]
	v_pk_fma_f32 v[12:13], v[142:143], s[26:27], v[12:13] op_sel_hi:[0,1,1]
	v_pk_fma_f32 v[10:11], v[142:143], s[30:31], v[10:11] op_sel_hi:[0,1,1]
	v_readlane_b32 s22, v172, 53
	v_readlane_b32 s23, v173, 53
	v_readlane_b32 s24, v174, 53
	v_readlane_b32 s25, v175, 53
	v_readlane_b32 s26, v176, 53
	v_readlane_b32 s27, v177, 53
	v_readlane_b32 s30, v178, 53
	v_readlane_b32 s31, v179, 53
	v_pk_fma_f32 v[16:17], v[144:145], s[6:7], v[16:17] op_sel_hi:[0,1,1]
	v_pk_fma_f32 v[14:15], v[144:145], s[8:9], v[14:15] op_sel_hi:[0,1,1]
	v_pk_fma_f32 v[12:13], v[144:145], s[10:11], v[12:13] op_sel_hi:[0,1,1]
	v_pk_fma_f32 v[10:11], v[144:145], s[12:13], v[10:11] op_sel_hi:[0,1,1]
	v_readlane_b32 s6, v172, 54
	v_readlane_b32 s7, v173, 54
	v_readlane_b32 s8, v174, 54
	v_readlane_b32 s9, v175, 54
	v_readlane_b32 s10, v176, 54
	v_readlane_b32 s11, v177, 54
	v_readlane_b32 s12, v178, 54
	v_readlane_b32 s13, v179, 54
	v_pk_fma_f32 v[16:17], v[146:147], s[22:23], v[16:17] op_sel_hi:[0,1,1]
	v_pk_fma_f32 v[14:15], v[146:147], s[24:25], v[14:15] op_sel_hi:[0,1,1]
	v_pk_fma_f32 v[12:13], v[146:147], s[26:27], v[12:13] op_sel_hi:[0,1,1]
	v_pk_fma_f32 v[10:11], v[146:147], s[30:31], v[10:11] op_sel_hi:[0,1,1]
	v_readlane_b32 s22, v172, 55
	v_readlane_b32 s23, v173, 55
	v_readlane_b32 s24, v174, 55
	v_readlane_b32 s25, v175, 55
	v_readlane_b32 s26, v176, 55
	v_readlane_b32 s27, v177, 55
	v_readlane_b32 s30, v178, 55
	v_readlane_b32 s31, v179, 55
	v_pk_fma_f32 v[16:17], v[148:149], s[6:7], v[16:17] op_sel_hi:[0,1,1]
	v_pk_fma_f32 v[14:15], v[148:149], s[8:9], v[14:15] op_sel_hi:[0,1,1]
	v_pk_fma_f32 v[12:13], v[148:149], s[10:11], v[12:13] op_sel_hi:[0,1,1]
	v_pk_fma_f32 v[10:11], v[148:149], s[12:13], v[10:11] op_sel_hi:[0,1,1]
	v_readlane_b32 s6, v172, 56
	v_readlane_b32 s7, v173, 56
	v_readlane_b32 s8, v174, 56
	v_readlane_b32 s9, v175, 56
	v_readlane_b32 s10, v176, 56
	v_readlane_b32 s11, v177, 56
	v_readlane_b32 s12, v178, 56
	v_readlane_b32 s13, v179, 56
	v_pk_fma_f32 v[16:17], v[150:151], s[22:23], v[16:17] op_sel_hi:[0,1,1]
	v_pk_fma_f32 v[14:15], v[150:151], s[24:25], v[14:15] op_sel_hi:[0,1,1]
	v_pk_fma_f32 v[12:13], v[150:151], s[26:27], v[12:13] op_sel_hi:[0,1,1]
	v_pk_fma_f32 v[10:11], v[150:151], s[30:31], v[10:11] op_sel_hi:[0,1,1]
	v_readlane_b32 s22, v172, 57
	v_readlane_b32 s23, v173, 57
	v_readlane_b32 s24, v174, 57
	v_readlane_b32 s25, v175, 57
	v_readlane_b32 s26, v176, 57
	v_readlane_b32 s27, v177, 57
	v_readlane_b32 s30, v178, 57
	v_readlane_b32 s31, v179, 57
	v_pk_fma_f32 v[16:17], v[152:153], s[6:7], v[16:17] op_sel_hi:[0,1,1]
	v_pk_fma_f32 v[14:15], v[152:153], s[8:9], v[14:15] op_sel_hi:[0,1,1]
	v_pk_fma_f32 v[12:13], v[152:153], s[10:11], v[12:13] op_sel_hi:[0,1,1]
	v_pk_fma_f32 v[10:11], v[152:153], s[12:13], v[10:11] op_sel_hi:[0,1,1]
	v_readlane_b32 s6, v172, 58
	v_readlane_b32 s7, v173, 58
	v_readlane_b32 s8, v174, 58
	v_readlane_b32 s9, v175, 58
	v_readlane_b32 s10, v176, 58
	v_readlane_b32 s11, v177, 58
	v_readlane_b32 s12, v178, 58
	v_readlane_b32 s13, v179, 58
	v_pk_fma_f32 v[16:17], v[154:155], s[22:23], v[16:17] op_sel_hi:[0,1,1]
	v_pk_fma_f32 v[14:15], v[154:155], s[24:25], v[14:15] op_sel_hi:[0,1,1]
	v_pk_fma_f32 v[12:13], v[154:155], s[26:27], v[12:13] op_sel_hi:[0,1,1]
	v_pk_fma_f32 v[10:11], v[154:155], s[30:31], v[10:11] op_sel_hi:[0,1,1]
	v_readlane_b32 s22, v172, 59
	v_readlane_b32 s23, v173, 59
	v_readlane_b32 s24, v174, 59
	v_readlane_b32 s25, v175, 59
	v_readlane_b32 s26, v176, 59
	v_readlane_b32 s27, v177, 59
	v_readlane_b32 s30, v178, 59
	v_readlane_b32 s31, v179, 59
	v_pk_fma_f32 v[16:17], v[156:157], s[6:7], v[16:17] op_sel_hi:[0,1,1]
	v_pk_fma_f32 v[14:15], v[156:157], s[8:9], v[14:15] op_sel_hi:[0,1,1]
	v_pk_fma_f32 v[12:13], v[156:157], s[10:11], v[12:13] op_sel_hi:[0,1,1]
	v_pk_fma_f32 v[10:11], v[156:157], s[12:13], v[10:11] op_sel_hi:[0,1,1]
	v_readlane_b32 s6, v172, 60
	v_readlane_b32 s7, v173, 60
	v_readlane_b32 s8, v174, 60
	v_readlane_b32 s9, v175, 60
	v_readlane_b32 s10, v176, 60
	v_readlane_b32 s11, v177, 60
	v_readlane_b32 s12, v178, 60
	v_readlane_b32 s13, v179, 60
	v_pk_fma_f32 v[16:17], v[158:159], s[22:23], v[16:17] op_sel_hi:[0,1,1]
	v_pk_fma_f32 v[14:15], v[158:159], s[24:25], v[14:15] op_sel_hi:[0,1,1]
	v_pk_fma_f32 v[12:13], v[158:159], s[26:27], v[12:13] op_sel_hi:[0,1,1]
	v_pk_fma_f32 v[10:11], v[158:159], s[30:31], v[10:11] op_sel_hi:[0,1,1]
	v_readlane_b32 s22, v172, 61
	v_readlane_b32 s23, v173, 61
	v_readlane_b32 s24, v174, 61
	v_readlane_b32 s25, v175, 61
	v_readlane_b32 s26, v176, 61
	v_readlane_b32 s27, v177, 61
	v_readlane_b32 s30, v178, 61
	v_readlane_b32 s31, v179, 61
	v_pk_fma_f32 v[16:17], v[164:165], s[6:7], v[16:17] op_sel_hi:[0,1,1]
	v_pk_fma_f32 v[14:15], v[164:165], s[8:9], v[14:15] op_sel_hi:[0,1,1]
	v_pk_fma_f32 v[12:13], v[164:165], s[10:11], v[12:13] op_sel_hi:[0,1,1]
	v_pk_fma_f32 v[10:11], v[164:165], s[12:13], v[10:11] op_sel_hi:[0,1,1]
	v_readlane_b32 s6, v172, 62
	v_readlane_b32 s7, v173, 62
	v_readlane_b32 s8, v174, 62
	v_readlane_b32 s9, v175, 62
	v_readlane_b32 s10, v176, 62
	v_readlane_b32 s11, v177, 62
	v_readlane_b32 s12, v178, 62
	v_readlane_b32 s13, v179, 62
	v_pk_fma_f32 v[16:17], v[166:167], s[22:23], v[16:17] op_sel_hi:[0,1,1]
	v_pk_fma_f32 v[14:15], v[166:167], s[24:25], v[14:15] op_sel_hi:[0,1,1]
	v_pk_fma_f32 v[12:13], v[166:167], s[26:27], v[12:13] op_sel_hi:[0,1,1]
	v_pk_fma_f32 v[10:11], v[166:167], s[30:31], v[10:11] op_sel_hi:[0,1,1]
	v_readlane_b32 s22, v172, 63
	v_readlane_b32 s23, v173, 63
	v_readlane_b32 s24, v174, 63
	v_readlane_b32 s25, v175, 63
	v_readlane_b32 s26, v176, 63
	v_readlane_b32 s27, v177, 63
	v_readlane_b32 s30, v178, 63
	v_readlane_b32 s31, v179, 63
	v_pk_fma_f32 v[16:17], v[168:169], s[6:7], v[16:17] op_sel_hi:[0,1,1]
	v_pk_fma_f32 v[14:15], v[168:169], s[8:9], v[14:15] op_sel_hi:[0,1,1]
	v_pk_fma_f32 v[12:13], v[168:169], s[10:11], v[12:13] op_sel_hi:[0,1,1]
	v_pk_fma_f32 v[10:11], v[168:169], s[12:13], v[10:11] op_sel_hi:[0,1,1]
	v_pk_fma_f32 v[16:17], v[170:171], s[22:23], v[16:17] op_sel_hi:[0,1,1]
	v_pk_fma_f32 v[14:15], v[170:171], s[24:25], v[14:15] op_sel_hi:[0,1,1]
	v_pk_fma_f32 v[12:13], v[170:171], s[26:27], v[12:13] op_sel_hi:[0,1,1]
	v_pk_fma_f32 v[10:11], v[170:171], s[30:31], v[10:11] op_sel_hi:[0,1,1]
	s_waitcnt vmcnt(63)
	v_readlane_b32 s6, v180, 0
	v_readlane_b32 s7, v181, 0
	v_readlane_b32 s8, v182, 0
	v_readlane_b32 s9, v183, 0
	v_readlane_b32 s10, v184, 0
	v_readlane_b32 s11, v185, 0
	v_readlane_b32 s12, v186, 0
	v_readlane_b32 s13, v187, 0
	v_readlane_b32 s22, v180, 1
	v_readlane_b32 s23, v181, 1
	v_readlane_b32 s24, v182, 1
	v_readlane_b32 s25, v183, 1
	v_readlane_b32 s26, v184, 1
	v_readlane_b32 s27, v185, 1
	v_readlane_b32 s30, v186, 1
	v_readlane_b32 s31, v187, 1
	v_pk_fma_f32 v[16:17], v[40:41], s[6:7], v[16:17] op_sel:[1,0,0] op_sel_hi:[1,1,1]
	v_pk_fma_f32 v[14:15], v[40:41], s[8:9], v[14:15] op_sel:[1,0,0] op_sel_hi:[1,1,1]
	v_pk_fma_f32 v[12:13], v[40:41], s[10:11], v[12:13] op_sel:[1,0,0] op_sel_hi:[1,1,1]
	v_pk_fma_f32 v[10:11], v[40:41], s[12:13], v[10:11] op_sel:[1,0,0] op_sel_hi:[1,1,1]
	v_readlane_b32 s6, v180, 2
	v_readlane_b32 s7, v181, 2
	v_readlane_b32 s8, v182, 2
	v_readlane_b32 s9, v183, 2
	v_readlane_b32 s10, v184, 2
	v_readlane_b32 s11, v185, 2
	v_readlane_b32 s12, v186, 2
	v_readlane_b32 s13, v187, 2
	s_waitcnt vmcnt(62)
	v_pk_fma_f32 v[16:17], v[42:43], s[22:23], v[16:17] op_sel:[1,0,0] op_sel_hi:[1,1,1]
	v_pk_fma_f32 v[14:15], v[42:43], s[24:25], v[14:15] op_sel:[1,0,0] op_sel_hi:[1,1,1]
	v_pk_fma_f32 v[12:13], v[42:43], s[26:27], v[12:13] op_sel:[1,0,0] op_sel_hi:[1,1,1]
	v_pk_fma_f32 v[10:11], v[42:43], s[30:31], v[10:11] op_sel:[1,0,0] op_sel_hi:[1,1,1]
	v_readlane_b32 s22, v180, 3
	v_readlane_b32 s23, v181, 3
	v_readlane_b32 s24, v182, 3
	v_readlane_b32 s25, v183, 3
	v_readlane_b32 s26, v184, 3
	v_readlane_b32 s27, v185, 3
	v_readlane_b32 s30, v186, 3
	v_readlane_b32 s31, v187, 3
	s_waitcnt vmcnt(61)
	v_pk_fma_f32 v[16:17], v[44:45], s[6:7], v[16:17] op_sel:[1,0,0] op_sel_hi:[1,1,1]
	v_pk_fma_f32 v[14:15], v[44:45], s[8:9], v[14:15] op_sel:[1,0,0] op_sel_hi:[1,1,1]
	v_pk_fma_f32 v[12:13], v[44:45], s[10:11], v[12:13] op_sel:[1,0,0] op_sel_hi:[1,1,1]
	v_pk_fma_f32 v[10:11], v[44:45], s[12:13], v[10:11] op_sel:[1,0,0] op_sel_hi:[1,1,1]
	v_readlane_b32 s6, v180, 4
	v_readlane_b32 s7, v181, 4
	v_readlane_b32 s8, v182, 4
	v_readlane_b32 s9, v183, 4
	v_readlane_b32 s10, v184, 4
	v_readlane_b32 s11, v185, 4
	v_readlane_b32 s12, v186, 4
	v_readlane_b32 s13, v187, 4
	s_waitcnt vmcnt(60)
	v_pk_fma_f32 v[16:17], v[46:47], s[22:23], v[16:17] op_sel:[1,0,0] op_sel_hi:[1,1,1]
	v_pk_fma_f32 v[14:15], v[46:47], s[24:25], v[14:15] op_sel:[1,0,0] op_sel_hi:[1,1,1]
	v_pk_fma_f32 v[12:13], v[46:47], s[26:27], v[12:13] op_sel:[1,0,0] op_sel_hi:[1,1,1]
	v_pk_fma_f32 v[10:11], v[46:47], s[30:31], v[10:11] op_sel:[1,0,0] op_sel_hi:[1,1,1]
	v_readlane_b32 s22, v180, 5
	v_readlane_b32 s23, v181, 5
	v_readlane_b32 s24, v182, 5
	v_readlane_b32 s25, v183, 5
	v_readlane_b32 s26, v184, 5
	v_readlane_b32 s27, v185, 5
	v_readlane_b32 s30, v186, 5
	v_readlane_b32 s31, v187, 5
	s_waitcnt vmcnt(59)
	v_pk_fma_f32 v[16:17], v[48:49], s[6:7], v[16:17] op_sel:[1,0,0] op_sel_hi:[1,1,1]
	v_pk_fma_f32 v[14:15], v[48:49], s[8:9], v[14:15] op_sel:[1,0,0] op_sel_hi:[1,1,1]
	v_pk_fma_f32 v[12:13], v[48:49], s[10:11], v[12:13] op_sel:[1,0,0] op_sel_hi:[1,1,1]
	v_pk_fma_f32 v[10:11], v[48:49], s[12:13], v[10:11] op_sel:[1,0,0] op_sel_hi:[1,1,1]
	v_readlane_b32 s6, v180, 6
	v_readlane_b32 s7, v181, 6
	v_readlane_b32 s8, v182, 6
	v_readlane_b32 s9, v183, 6
	v_readlane_b32 s10, v184, 6
	v_readlane_b32 s11, v185, 6
	v_readlane_b32 s12, v186, 6
	v_readlane_b32 s13, v187, 6
	s_waitcnt vmcnt(58)
	v_pk_fma_f32 v[16:17], v[50:51], s[22:23], v[16:17] op_sel:[1,0,0] op_sel_hi:[1,1,1]
	v_pk_fma_f32 v[14:15], v[50:51], s[24:25], v[14:15] op_sel:[1,0,0] op_sel_hi:[1,1,1]
	v_pk_fma_f32 v[12:13], v[50:51], s[26:27], v[12:13] op_sel:[1,0,0] op_sel_hi:[1,1,1]
	v_pk_fma_f32 v[10:11], v[50:51], s[30:31], v[10:11] op_sel:[1,0,0] op_sel_hi:[1,1,1]
	v_readlane_b32 s22, v180, 7
	v_readlane_b32 s23, v181, 7
	v_readlane_b32 s24, v182, 7
	v_readlane_b32 s25, v183, 7
	v_readlane_b32 s26, v184, 7
	v_readlane_b32 s27, v185, 7
	v_readlane_b32 s30, v186, 7
	v_readlane_b32 s31, v187, 7
	s_waitcnt vmcnt(57)
	v_pk_fma_f32 v[16:17], v[52:53], s[6:7], v[16:17] op_sel:[1,0,0] op_sel_hi:[1,1,1]
	v_pk_fma_f32 v[14:15], v[52:53], s[8:9], v[14:15] op_sel:[1,0,0] op_sel_hi:[1,1,1]
	v_pk_fma_f32 v[12:13], v[52:53], s[10:11], v[12:13] op_sel:[1,0,0] op_sel_hi:[1,1,1]
	v_pk_fma_f32 v[10:11], v[52:53], s[12:13], v[10:11] op_sel:[1,0,0] op_sel_hi:[1,1,1]
	v_readlane_b32 s6, v180, 8
	v_readlane_b32 s7, v181, 8
	v_readlane_b32 s8, v182, 8
	v_readlane_b32 s9, v183, 8
	v_readlane_b32 s10, v184, 8
	v_readlane_b32 s11, v185, 8
	v_readlane_b32 s12, v186, 8
	v_readlane_b32 s13, v187, 8
	s_waitcnt vmcnt(56)
	v_pk_fma_f32 v[16:17], v[54:55], s[22:23], v[16:17] op_sel:[1,0,0] op_sel_hi:[1,1,1]
	v_pk_fma_f32 v[14:15], v[54:55], s[24:25], v[14:15] op_sel:[1,0,0] op_sel_hi:[1,1,1]
	v_pk_fma_f32 v[12:13], v[54:55], s[26:27], v[12:13] op_sel:[1,0,0] op_sel_hi:[1,1,1]
	v_pk_fma_f32 v[10:11], v[54:55], s[30:31], v[10:11] op_sel:[1,0,0] op_sel_hi:[1,1,1]
	v_readlane_b32 s22, v180, 9
	v_readlane_b32 s23, v181, 9
	v_readlane_b32 s24, v182, 9
	v_readlane_b32 s25, v183, 9
	v_readlane_b32 s26, v184, 9
	v_readlane_b32 s27, v185, 9
	v_readlane_b32 s30, v186, 9
	v_readlane_b32 s31, v187, 9
	s_waitcnt vmcnt(55)
	v_pk_fma_f32 v[16:17], v[56:57], s[6:7], v[16:17] op_sel:[1,0,0] op_sel_hi:[1,1,1]
	v_pk_fma_f32 v[14:15], v[56:57], s[8:9], v[14:15] op_sel:[1,0,0] op_sel_hi:[1,1,1]
	v_pk_fma_f32 v[12:13], v[56:57], s[10:11], v[12:13] op_sel:[1,0,0] op_sel_hi:[1,1,1]
	v_pk_fma_f32 v[10:11], v[56:57], s[12:13], v[10:11] op_sel:[1,0,0] op_sel_hi:[1,1,1]
	v_readlane_b32 s6, v180, 10
	v_readlane_b32 s7, v181, 10
	v_readlane_b32 s8, v182, 10
	v_readlane_b32 s9, v183, 10
	v_readlane_b32 s10, v184, 10
	v_readlane_b32 s11, v185, 10
	v_readlane_b32 s12, v186, 10
	v_readlane_b32 s13, v187, 10
	s_waitcnt vmcnt(54)
	v_pk_fma_f32 v[16:17], v[58:59], s[22:23], v[16:17] op_sel:[1,0,0] op_sel_hi:[1,1,1]
	v_pk_fma_f32 v[14:15], v[58:59], s[24:25], v[14:15] op_sel:[1,0,0] op_sel_hi:[1,1,1]
	v_pk_fma_f32 v[12:13], v[58:59], s[26:27], v[12:13] op_sel:[1,0,0] op_sel_hi:[1,1,1]
	v_pk_fma_f32 v[10:11], v[58:59], s[30:31], v[10:11] op_sel:[1,0,0] op_sel_hi:[1,1,1]
	v_readlane_b32 s22, v180, 11
	v_readlane_b32 s23, v181, 11
	v_readlane_b32 s24, v182, 11
	v_readlane_b32 s25, v183, 11
	v_readlane_b32 s26, v184, 11
	v_readlane_b32 s27, v185, 11
	v_readlane_b32 s30, v186, 11
	v_readlane_b32 s31, v187, 11
	s_waitcnt vmcnt(53)
	v_pk_fma_f32 v[16:17], v[60:61], s[6:7], v[16:17] op_sel:[1,0,0] op_sel_hi:[1,1,1]
	v_pk_fma_f32 v[14:15], v[60:61], s[8:9], v[14:15] op_sel:[1,0,0] op_sel_hi:[1,1,1]
	v_pk_fma_f32 v[12:13], v[60:61], s[10:11], v[12:13] op_sel:[1,0,0] op_sel_hi:[1,1,1]
	v_pk_fma_f32 v[10:11], v[60:61], s[12:13], v[10:11] op_sel:[1,0,0] op_sel_hi:[1,1,1]
	v_readlane_b32 s6, v180, 12
	v_readlane_b32 s7, v181, 12
	v_readlane_b32 s8, v182, 12
	v_readlane_b32 s9, v183, 12
	v_readlane_b32 s10, v184, 12
	v_readlane_b32 s11, v185, 12
	v_readlane_b32 s12, v186, 12
	v_readlane_b32 s13, v187, 12
	s_waitcnt vmcnt(52)
	v_pk_fma_f32 v[16:17], v[62:63], s[22:23], v[16:17] op_sel:[1,0,0] op_sel_hi:[1,1,1]
	v_pk_fma_f32 v[14:15], v[62:63], s[24:25], v[14:15] op_sel:[1,0,0] op_sel_hi:[1,1,1]
	v_pk_fma_f32 v[12:13], v[62:63], s[26:27], v[12:13] op_sel:[1,0,0] op_sel_hi:[1,1,1]
	v_pk_fma_f32 v[10:11], v[62:63], s[30:31], v[10:11] op_sel:[1,0,0] op_sel_hi:[1,1,1]
	v_readlane_b32 s22, v180, 13
	v_readlane_b32 s23, v181, 13
	v_readlane_b32 s24, v182, 13
	v_readlane_b32 s25, v183, 13
	v_readlane_b32 s26, v184, 13
	v_readlane_b32 s27, v185, 13
	v_readlane_b32 s30, v186, 13
	v_readlane_b32 s31, v187, 13
	s_waitcnt vmcnt(51)
	v_pk_fma_f32 v[16:17], v[64:65], s[6:7], v[16:17] op_sel:[1,0,0] op_sel_hi:[1,1,1]
	v_pk_fma_f32 v[14:15], v[64:65], s[8:9], v[14:15] op_sel:[1,0,0] op_sel_hi:[1,1,1]
	v_pk_fma_f32 v[12:13], v[64:65], s[10:11], v[12:13] op_sel:[1,0,0] op_sel_hi:[1,1,1]
	v_pk_fma_f32 v[10:11], v[64:65], s[12:13], v[10:11] op_sel:[1,0,0] op_sel_hi:[1,1,1]
	v_readlane_b32 s6, v180, 14
	v_readlane_b32 s7, v181, 14
	v_readlane_b32 s8, v182, 14
	v_readlane_b32 s9, v183, 14
	v_readlane_b32 s10, v184, 14
	v_readlane_b32 s11, v185, 14
	v_readlane_b32 s12, v186, 14
	v_readlane_b32 s13, v187, 14
	s_waitcnt vmcnt(50)
	v_pk_fma_f32 v[16:17], v[66:67], s[22:23], v[16:17] op_sel:[1,0,0] op_sel_hi:[1,1,1]
	v_pk_fma_f32 v[14:15], v[66:67], s[24:25], v[14:15] op_sel:[1,0,0] op_sel_hi:[1,1,1]
	v_pk_fma_f32 v[12:13], v[66:67], s[26:27], v[12:13] op_sel:[1,0,0] op_sel_hi:[1,1,1]
	v_pk_fma_f32 v[10:11], v[66:67], s[30:31], v[10:11] op_sel:[1,0,0] op_sel_hi:[1,1,1]
	v_readlane_b32 s22, v180, 15
	v_readlane_b32 s23, v181, 15
	v_readlane_b32 s24, v182, 15
	v_readlane_b32 s25, v183, 15
	v_readlane_b32 s26, v184, 15
	v_readlane_b32 s27, v185, 15
	v_readlane_b32 s30, v186, 15
	v_readlane_b32 s31, v187, 15
	s_waitcnt vmcnt(49)
	v_pk_fma_f32 v[16:17], v[68:69], s[6:7], v[16:17] op_sel:[1,0,0] op_sel_hi:[1,1,1]
	v_pk_fma_f32 v[14:15], v[68:69], s[8:9], v[14:15] op_sel:[1,0,0] op_sel_hi:[1,1,1]
	v_pk_fma_f32 v[12:13], v[68:69], s[10:11], v[12:13] op_sel:[1,0,0] op_sel_hi:[1,1,1]
	v_pk_fma_f32 v[10:11], v[68:69], s[12:13], v[10:11] op_sel:[1,0,0] op_sel_hi:[1,1,1]
	v_readlane_b32 s6, v180, 16
	v_readlane_b32 s7, v181, 16
	v_readlane_b32 s8, v182, 16
	v_readlane_b32 s9, v183, 16
	v_readlane_b32 s10, v184, 16
	v_readlane_b32 s11, v185, 16
	v_readlane_b32 s12, v186, 16
	v_readlane_b32 s13, v187, 16
	s_waitcnt vmcnt(48)
	v_pk_fma_f32 v[16:17], v[70:71], s[22:23], v[16:17] op_sel:[1,0,0] op_sel_hi:[1,1,1]
	v_pk_fma_f32 v[14:15], v[70:71], s[24:25], v[14:15] op_sel:[1,0,0] op_sel_hi:[1,1,1]
	v_pk_fma_f32 v[12:13], v[70:71], s[26:27], v[12:13] op_sel:[1,0,0] op_sel_hi:[1,1,1]
	v_pk_fma_f32 v[10:11], v[70:71], s[30:31], v[10:11] op_sel:[1,0,0] op_sel_hi:[1,1,1]
	v_readlane_b32 s22, v180, 17
	v_readlane_b32 s23, v181, 17
	v_readlane_b32 s24, v182, 17
	v_readlane_b32 s25, v183, 17
	v_readlane_b32 s26, v184, 17
	v_readlane_b32 s27, v185, 17
	v_readlane_b32 s30, v186, 17
	v_readlane_b32 s31, v187, 17
	s_waitcnt vmcnt(47)
	v_pk_fma_f32 v[16:17], v[72:73], s[6:7], v[16:17] op_sel:[1,0,0] op_sel_hi:[1,1,1]
	v_pk_fma_f32 v[14:15], v[72:73], s[8:9], v[14:15] op_sel:[1,0,0] op_sel_hi:[1,1,1]
	v_pk_fma_f32 v[12:13], v[72:73], s[10:11], v[12:13] op_sel:[1,0,0] op_sel_hi:[1,1,1]
	v_pk_fma_f32 v[10:11], v[72:73], s[12:13], v[10:11] op_sel:[1,0,0] op_sel_hi:[1,1,1]
	v_readlane_b32 s6, v180, 18
	v_readlane_b32 s7, v181, 18
	v_readlane_b32 s8, v182, 18
	v_readlane_b32 s9, v183, 18
	v_readlane_b32 s10, v184, 18
	v_readlane_b32 s11, v185, 18
	v_readlane_b32 s12, v186, 18
	v_readlane_b32 s13, v187, 18
	s_waitcnt vmcnt(46)
	v_pk_fma_f32 v[16:17], v[74:75], s[22:23], v[16:17] op_sel:[1,0,0] op_sel_hi:[1,1,1]
	v_pk_fma_f32 v[14:15], v[74:75], s[24:25], v[14:15] op_sel:[1,0,0] op_sel_hi:[1,1,1]
	v_pk_fma_f32 v[12:13], v[74:75], s[26:27], v[12:13] op_sel:[1,0,0] op_sel_hi:[1,1,1]
	v_pk_fma_f32 v[10:11], v[74:75], s[30:31], v[10:11] op_sel:[1,0,0] op_sel_hi:[1,1,1]
	v_readlane_b32 s22, v180, 19
	v_readlane_b32 s23, v181, 19
	v_readlane_b32 s24, v182, 19
	v_readlane_b32 s25, v183, 19
	v_readlane_b32 s26, v184, 19
	v_readlane_b32 s27, v185, 19
	v_readlane_b32 s30, v186, 19
	v_readlane_b32 s31, v187, 19
	s_waitcnt vmcnt(45)
	v_pk_fma_f32 v[16:17], v[76:77], s[6:7], v[16:17] op_sel:[1,0,0] op_sel_hi:[1,1,1]
	v_pk_fma_f32 v[14:15], v[76:77], s[8:9], v[14:15] op_sel:[1,0,0] op_sel_hi:[1,1,1]
	v_pk_fma_f32 v[12:13], v[76:77], s[10:11], v[12:13] op_sel:[1,0,0] op_sel_hi:[1,1,1]
	v_pk_fma_f32 v[10:11], v[76:77], s[12:13], v[10:11] op_sel:[1,0,0] op_sel_hi:[1,1,1]
	v_readlane_b32 s6, v180, 20
	v_readlane_b32 s7, v181, 20
	v_readlane_b32 s8, v182, 20
	v_readlane_b32 s9, v183, 20
	v_readlane_b32 s10, v184, 20
	v_readlane_b32 s11, v185, 20
	v_readlane_b32 s12, v186, 20
	v_readlane_b32 s13, v187, 20
	s_waitcnt vmcnt(44)
	v_pk_fma_f32 v[16:17], v[78:79], s[22:23], v[16:17] op_sel:[1,0,0] op_sel_hi:[1,1,1]
	v_pk_fma_f32 v[14:15], v[78:79], s[24:25], v[14:15] op_sel:[1,0,0] op_sel_hi:[1,1,1]
	v_pk_fma_f32 v[12:13], v[78:79], s[26:27], v[12:13] op_sel:[1,0,0] op_sel_hi:[1,1,1]
	v_pk_fma_f32 v[10:11], v[78:79], s[30:31], v[10:11] op_sel:[1,0,0] op_sel_hi:[1,1,1]
	v_readlane_b32 s22, v180, 21
	v_readlane_b32 s23, v181, 21
	v_readlane_b32 s24, v182, 21
	v_readlane_b32 s25, v183, 21
	v_readlane_b32 s26, v184, 21
	v_readlane_b32 s27, v185, 21
	v_readlane_b32 s30, v186, 21
	v_readlane_b32 s31, v187, 21
	s_waitcnt vmcnt(43)
	v_pk_fma_f32 v[16:17], v[80:81], s[6:7], v[16:17] op_sel:[1,0,0] op_sel_hi:[1,1,1]
	v_pk_fma_f32 v[14:15], v[80:81], s[8:9], v[14:15] op_sel:[1,0,0] op_sel_hi:[1,1,1]
	v_pk_fma_f32 v[12:13], v[80:81], s[10:11], v[12:13] op_sel:[1,0,0] op_sel_hi:[1,1,1]
	v_pk_fma_f32 v[10:11], v[80:81], s[12:13], v[10:11] op_sel:[1,0,0] op_sel_hi:[1,1,1]
	v_readlane_b32 s6, v180, 22
	v_readlane_b32 s7, v181, 22
	v_readlane_b32 s8, v182, 22
	v_readlane_b32 s9, v183, 22
	v_readlane_b32 s10, v184, 22
	v_readlane_b32 s11, v185, 22
	v_readlane_b32 s12, v186, 22
	v_readlane_b32 s13, v187, 22
	s_waitcnt vmcnt(42)
	v_pk_fma_f32 v[16:17], v[82:83], s[22:23], v[16:17] op_sel:[1,0,0] op_sel_hi:[1,1,1]
	v_pk_fma_f32 v[14:15], v[82:83], s[24:25], v[14:15] op_sel:[1,0,0] op_sel_hi:[1,1,1]
	v_pk_fma_f32 v[12:13], v[82:83], s[26:27], v[12:13] op_sel:[1,0,0] op_sel_hi:[1,1,1]
	v_pk_fma_f32 v[10:11], v[82:83], s[30:31], v[10:11] op_sel:[1,0,0] op_sel_hi:[1,1,1]
	v_readlane_b32 s22, v180, 23
	v_readlane_b32 s23, v181, 23
	v_readlane_b32 s24, v182, 23
	v_readlane_b32 s25, v183, 23
	v_readlane_b32 s26, v184, 23
	v_readlane_b32 s27, v185, 23
	v_readlane_b32 s30, v186, 23
	v_readlane_b32 s31, v187, 23
	s_waitcnt vmcnt(41)
	v_pk_fma_f32 v[16:17], v[84:85], s[6:7], v[16:17] op_sel:[1,0,0] op_sel_hi:[1,1,1]
	v_pk_fma_f32 v[14:15], v[84:85], s[8:9], v[14:15] op_sel:[1,0,0] op_sel_hi:[1,1,1]
	v_pk_fma_f32 v[12:13], v[84:85], s[10:11], v[12:13] op_sel:[1,0,0] op_sel_hi:[1,1,1]
	v_pk_fma_f32 v[10:11], v[84:85], s[12:13], v[10:11] op_sel:[1,0,0] op_sel_hi:[1,1,1]
	v_readlane_b32 s6, v180, 24
	v_readlane_b32 s7, v181, 24
	v_readlane_b32 s8, v182, 24
	v_readlane_b32 s9, v183, 24
	v_readlane_b32 s10, v184, 24
	v_readlane_b32 s11, v185, 24
	v_readlane_b32 s12, v186, 24
	v_readlane_b32 s13, v187, 24
	s_waitcnt vmcnt(40)
	v_pk_fma_f32 v[16:17], v[86:87], s[22:23], v[16:17] op_sel:[1,0,0] op_sel_hi:[1,1,1]
	v_pk_fma_f32 v[14:15], v[86:87], s[24:25], v[14:15] op_sel:[1,0,0] op_sel_hi:[1,1,1]
	v_pk_fma_f32 v[12:13], v[86:87], s[26:27], v[12:13] op_sel:[1,0,0] op_sel_hi:[1,1,1]
	v_pk_fma_f32 v[10:11], v[86:87], s[30:31], v[10:11] op_sel:[1,0,0] op_sel_hi:[1,1,1]
	v_readlane_b32 s22, v180, 25
	v_readlane_b32 s23, v181, 25
	v_readlane_b32 s24, v182, 25
	v_readlane_b32 s25, v183, 25
	v_readlane_b32 s26, v184, 25
	v_readlane_b32 s27, v185, 25
	v_readlane_b32 s30, v186, 25
	v_readlane_b32 s31, v187, 25
	s_waitcnt vmcnt(39)
	v_pk_fma_f32 v[16:17], v[88:89], s[6:7], v[16:17] op_sel:[1,0,0] op_sel_hi:[1,1,1]
	v_pk_fma_f32 v[14:15], v[88:89], s[8:9], v[14:15] op_sel:[1,0,0] op_sel_hi:[1,1,1]
	v_pk_fma_f32 v[12:13], v[88:89], s[10:11], v[12:13] op_sel:[1,0,0] op_sel_hi:[1,1,1]
	v_pk_fma_f32 v[10:11], v[88:89], s[12:13], v[10:11] op_sel:[1,0,0] op_sel_hi:[1,1,1]
	v_readlane_b32 s6, v180, 26
	v_readlane_b32 s7, v181, 26
	v_readlane_b32 s8, v182, 26
	v_readlane_b32 s9, v183, 26
	v_readlane_b32 s10, v184, 26
	v_readlane_b32 s11, v185, 26
	v_readlane_b32 s12, v186, 26
	v_readlane_b32 s13, v187, 26
	s_waitcnt vmcnt(38)
	v_pk_fma_f32 v[16:17], v[90:91], s[22:23], v[16:17] op_sel:[1,0,0] op_sel_hi:[1,1,1]
	v_pk_fma_f32 v[14:15], v[90:91], s[24:25], v[14:15] op_sel:[1,0,0] op_sel_hi:[1,1,1]
	v_pk_fma_f32 v[12:13], v[90:91], s[26:27], v[12:13] op_sel:[1,0,0] op_sel_hi:[1,1,1]
	v_pk_fma_f32 v[10:11], v[90:91], s[30:31], v[10:11] op_sel:[1,0,0] op_sel_hi:[1,1,1]
	v_readlane_b32 s22, v180, 27
	v_readlane_b32 s23, v181, 27
	v_readlane_b32 s24, v182, 27
	v_readlane_b32 s25, v183, 27
	v_readlane_b32 s26, v184, 27
	v_readlane_b32 s27, v185, 27
	v_readlane_b32 s30, v186, 27
	v_readlane_b32 s31, v187, 27
	s_waitcnt vmcnt(37)
	v_pk_fma_f32 v[16:17], v[92:93], s[6:7], v[16:17] op_sel:[1,0,0] op_sel_hi:[1,1,1]
	v_pk_fma_f32 v[14:15], v[92:93], s[8:9], v[14:15] op_sel:[1,0,0] op_sel_hi:[1,1,1]
	v_pk_fma_f32 v[12:13], v[92:93], s[10:11], v[12:13] op_sel:[1,0,0] op_sel_hi:[1,1,1]
	v_pk_fma_f32 v[10:11], v[92:93], s[12:13], v[10:11] op_sel:[1,0,0] op_sel_hi:[1,1,1]
	v_readlane_b32 s6, v180, 28
	v_readlane_b32 s7, v181, 28
	v_readlane_b32 s8, v182, 28
	v_readlane_b32 s9, v183, 28
	v_readlane_b32 s10, v184, 28
	v_readlane_b32 s11, v185, 28
	v_readlane_b32 s12, v186, 28
	v_readlane_b32 s13, v187, 28
	s_waitcnt vmcnt(36)
	v_pk_fma_f32 v[16:17], v[94:95], s[22:23], v[16:17] op_sel:[1,0,0] op_sel_hi:[1,1,1]
	v_pk_fma_f32 v[14:15], v[94:95], s[24:25], v[14:15] op_sel:[1,0,0] op_sel_hi:[1,1,1]
	v_pk_fma_f32 v[12:13], v[94:95], s[26:27], v[12:13] op_sel:[1,0,0] op_sel_hi:[1,1,1]
	v_pk_fma_f32 v[10:11], v[94:95], s[30:31], v[10:11] op_sel:[1,0,0] op_sel_hi:[1,1,1]
	v_readlane_b32 s22, v180, 29
	v_readlane_b32 s23, v181, 29
	v_readlane_b32 s24, v182, 29
	v_readlane_b32 s25, v183, 29
	v_readlane_b32 s26, v184, 29
	v_readlane_b32 s27, v185, 29
	v_readlane_b32 s30, v186, 29
	v_readlane_b32 s31, v187, 29
	s_waitcnt vmcnt(35)
	v_pk_fma_f32 v[16:17], v[96:97], s[6:7], v[16:17] op_sel:[1,0,0] op_sel_hi:[1,1,1]
	v_pk_fma_f32 v[14:15], v[96:97], s[8:9], v[14:15] op_sel:[1,0,0] op_sel_hi:[1,1,1]
	v_pk_fma_f32 v[12:13], v[96:97], s[10:11], v[12:13] op_sel:[1,0,0] op_sel_hi:[1,1,1]
	v_pk_fma_f32 v[10:11], v[96:97], s[12:13], v[10:11] op_sel:[1,0,0] op_sel_hi:[1,1,1]
	v_readlane_b32 s6, v180, 30
	v_readlane_b32 s7, v181, 30
	v_readlane_b32 s8, v182, 30
	v_readlane_b32 s9, v183, 30
	v_readlane_b32 s10, v184, 30
	v_readlane_b32 s11, v185, 30
	v_readlane_b32 s12, v186, 30
	v_readlane_b32 s13, v187, 30
	s_waitcnt vmcnt(34)
	v_pk_fma_f32 v[16:17], v[98:99], s[22:23], v[16:17] op_sel:[1,0,0] op_sel_hi:[1,1,1]
	v_pk_fma_f32 v[14:15], v[98:99], s[24:25], v[14:15] op_sel:[1,0,0] op_sel_hi:[1,1,1]
	v_pk_fma_f32 v[12:13], v[98:99], s[26:27], v[12:13] op_sel:[1,0,0] op_sel_hi:[1,1,1]
	v_pk_fma_f32 v[10:11], v[98:99], s[30:31], v[10:11] op_sel:[1,0,0] op_sel_hi:[1,1,1]
	v_readlane_b32 s22, v180, 31
	v_readlane_b32 s23, v181, 31
	v_readlane_b32 s24, v182, 31
	v_readlane_b32 s25, v183, 31
	v_readlane_b32 s26, v184, 31
	v_readlane_b32 s27, v185, 31
	v_readlane_b32 s30, v186, 31
	v_readlane_b32 s31, v187, 31
	s_waitcnt vmcnt(33)
	v_pk_fma_f32 v[16:17], v[100:101], s[6:7], v[16:17] op_sel:[1,0,0] op_sel_hi:[1,1,1]
	v_pk_fma_f32 v[14:15], v[100:101], s[8:9], v[14:15] op_sel:[1,0,0] op_sel_hi:[1,1,1]
	v_pk_fma_f32 v[12:13], v[100:101], s[10:11], v[12:13] op_sel:[1,0,0] op_sel_hi:[1,1,1]
	v_pk_fma_f32 v[10:11], v[100:101], s[12:13], v[10:11] op_sel:[1,0,0] op_sel_hi:[1,1,1]
	v_readlane_b32 s6, v180, 32
	v_readlane_b32 s7, v181, 32
	v_readlane_b32 s8, v182, 32
	v_readlane_b32 s9, v183, 32
	v_readlane_b32 s10, v184, 32
	v_readlane_b32 s11, v185, 32
	v_readlane_b32 s12, v186, 32
	v_readlane_b32 s13, v187, 32
	s_waitcnt vmcnt(32)
	v_pk_fma_f32 v[16:17], v[102:103], s[22:23], v[16:17] op_sel:[1,0,0] op_sel_hi:[1,1,1]
	v_pk_fma_f32 v[14:15], v[102:103], s[24:25], v[14:15] op_sel:[1,0,0] op_sel_hi:[1,1,1]
	v_pk_fma_f32 v[12:13], v[102:103], s[26:27], v[12:13] op_sel:[1,0,0] op_sel_hi:[1,1,1]
	v_pk_fma_f32 v[10:11], v[102:103], s[30:31], v[10:11] op_sel:[1,0,0] op_sel_hi:[1,1,1]
	v_readlane_b32 s22, v180, 33
	v_readlane_b32 s23, v181, 33
	v_readlane_b32 s24, v182, 33
	v_readlane_b32 s25, v183, 33
	v_readlane_b32 s26, v184, 33
	v_readlane_b32 s27, v185, 33
	v_readlane_b32 s30, v186, 33
	v_readlane_b32 s31, v187, 33
	s_waitcnt vmcnt(31)
	v_pk_fma_f32 v[16:17], v[104:105], s[6:7], v[16:17] op_sel:[1,0,0] op_sel_hi:[1,1,1]
	v_pk_fma_f32 v[14:15], v[104:105], s[8:9], v[14:15] op_sel:[1,0,0] op_sel_hi:[1,1,1]
	v_pk_fma_f32 v[12:13], v[104:105], s[10:11], v[12:13] op_sel:[1,0,0] op_sel_hi:[1,1,1]
	v_pk_fma_f32 v[10:11], v[104:105], s[12:13], v[10:11] op_sel:[1,0,0] op_sel_hi:[1,1,1]
	v_readlane_b32 s6, v180, 34
	v_readlane_b32 s7, v181, 34
	v_readlane_b32 s8, v182, 34
	v_readlane_b32 s9, v183, 34
	v_readlane_b32 s10, v184, 34
	v_readlane_b32 s11, v185, 34
	v_readlane_b32 s12, v186, 34
	v_readlane_b32 s13, v187, 34
	s_waitcnt vmcnt(30)
	v_pk_fma_f32 v[16:17], v[106:107], s[22:23], v[16:17] op_sel:[1,0,0] op_sel_hi:[1,1,1]
	v_pk_fma_f32 v[14:15], v[106:107], s[24:25], v[14:15] op_sel:[1,0,0] op_sel_hi:[1,1,1]
	v_pk_fma_f32 v[12:13], v[106:107], s[26:27], v[12:13] op_sel:[1,0,0] op_sel_hi:[1,1,1]
	v_pk_fma_f32 v[10:11], v[106:107], s[30:31], v[10:11] op_sel:[1,0,0] op_sel_hi:[1,1,1]
	v_readlane_b32 s22, v180, 35
	v_readlane_b32 s23, v181, 35
	v_readlane_b32 s24, v182, 35
	v_readlane_b32 s25, v183, 35
	v_readlane_b32 s26, v184, 35
	v_readlane_b32 s27, v185, 35
	v_readlane_b32 s30, v186, 35
	v_readlane_b32 s31, v187, 35
	s_waitcnt vmcnt(29)
	v_pk_fma_f32 v[16:17], v[108:109], s[6:7], v[16:17] op_sel:[1,0,0] op_sel_hi:[1,1,1]
	v_pk_fma_f32 v[14:15], v[108:109], s[8:9], v[14:15] op_sel:[1,0,0] op_sel_hi:[1,1,1]
	v_pk_fma_f32 v[12:13], v[108:109], s[10:11], v[12:13] op_sel:[1,0,0] op_sel_hi:[1,1,1]
	v_pk_fma_f32 v[10:11], v[108:109], s[12:13], v[10:11] op_sel:[1,0,0] op_sel_hi:[1,1,1]
	v_readlane_b32 s6, v180, 36
	v_readlane_b32 s7, v181, 36
	v_readlane_b32 s8, v182, 36
	v_readlane_b32 s9, v183, 36
	v_readlane_b32 s10, v184, 36
	v_readlane_b32 s11, v185, 36
	v_readlane_b32 s12, v186, 36
	v_readlane_b32 s13, v187, 36
	s_waitcnt vmcnt(28)
	v_pk_fma_f32 v[16:17], v[110:111], s[22:23], v[16:17] op_sel:[1,0,0] op_sel_hi:[1,1,1]
	v_pk_fma_f32 v[14:15], v[110:111], s[24:25], v[14:15] op_sel:[1,0,0] op_sel_hi:[1,1,1]
	v_pk_fma_f32 v[12:13], v[110:111], s[26:27], v[12:13] op_sel:[1,0,0] op_sel_hi:[1,1,1]
	v_pk_fma_f32 v[10:11], v[110:111], s[30:31], v[10:11] op_sel:[1,0,0] op_sel_hi:[1,1,1]
	v_readlane_b32 s22, v180, 37
	v_readlane_b32 s23, v181, 37
	v_readlane_b32 s24, v182, 37
	v_readlane_b32 s25, v183, 37
	v_readlane_b32 s26, v184, 37
	v_readlane_b32 s27, v185, 37
	v_readlane_b32 s30, v186, 37
	v_readlane_b32 s31, v187, 37
	s_waitcnt vmcnt(27)
	v_pk_fma_f32 v[16:17], v[112:113], s[6:7], v[16:17] op_sel:[1,0,0] op_sel_hi:[1,1,1]
	v_pk_fma_f32 v[14:15], v[112:113], s[8:9], v[14:15] op_sel:[1,0,0] op_sel_hi:[1,1,1]
	v_pk_fma_f32 v[12:13], v[112:113], s[10:11], v[12:13] op_sel:[1,0,0] op_sel_hi:[1,1,1]
	v_pk_fma_f32 v[10:11], v[112:113], s[12:13], v[10:11] op_sel:[1,0,0] op_sel_hi:[1,1,1]
	v_readlane_b32 s6, v180, 38
	v_readlane_b32 s7, v181, 38
	v_readlane_b32 s8, v182, 38
	v_readlane_b32 s9, v183, 38
	v_readlane_b32 s10, v184, 38
	v_readlane_b32 s11, v185, 38
	v_readlane_b32 s12, v186, 38
	v_readlane_b32 s13, v187, 38
	s_waitcnt vmcnt(26)
	v_pk_fma_f32 v[16:17], v[114:115], s[22:23], v[16:17] op_sel:[1,0,0] op_sel_hi:[1,1,1]
	v_pk_fma_f32 v[14:15], v[114:115], s[24:25], v[14:15] op_sel:[1,0,0] op_sel_hi:[1,1,1]
	v_pk_fma_f32 v[12:13], v[114:115], s[26:27], v[12:13] op_sel:[1,0,0] op_sel_hi:[1,1,1]
	v_pk_fma_f32 v[10:11], v[114:115], s[30:31], v[10:11] op_sel:[1,0,0] op_sel_hi:[1,1,1]
	v_readlane_b32 s22, v180, 39
	v_readlane_b32 s23, v181, 39
	v_readlane_b32 s24, v182, 39
	v_readlane_b32 s25, v183, 39
	v_readlane_b32 s26, v184, 39
	v_readlane_b32 s27, v185, 39
	v_readlane_b32 s30, v186, 39
	v_readlane_b32 s31, v187, 39
	s_waitcnt vmcnt(25)
	v_pk_fma_f32 v[16:17], v[116:117], s[6:7], v[16:17] op_sel:[1,0,0] op_sel_hi:[1,1,1]
	v_pk_fma_f32 v[14:15], v[116:117], s[8:9], v[14:15] op_sel:[1,0,0] op_sel_hi:[1,1,1]
	v_pk_fma_f32 v[12:13], v[116:117], s[10:11], v[12:13] op_sel:[1,0,0] op_sel_hi:[1,1,1]
	v_pk_fma_f32 v[10:11], v[116:117], s[12:13], v[10:11] op_sel:[1,0,0] op_sel_hi:[1,1,1]
	v_readlane_b32 s6, v180, 40
	v_readlane_b32 s7, v181, 40
	v_readlane_b32 s8, v182, 40
	v_readlane_b32 s9, v183, 40
	v_readlane_b32 s10, v184, 40
	v_readlane_b32 s11, v185, 40
	v_readlane_b32 s12, v186, 40
	v_readlane_b32 s13, v187, 40
	s_waitcnt vmcnt(24)
	v_pk_fma_f32 v[16:17], v[118:119], s[22:23], v[16:17] op_sel:[1,0,0] op_sel_hi:[1,1,1]
	v_pk_fma_f32 v[14:15], v[118:119], s[24:25], v[14:15] op_sel:[1,0,0] op_sel_hi:[1,1,1]
	v_pk_fma_f32 v[12:13], v[118:119], s[26:27], v[12:13] op_sel:[1,0,0] op_sel_hi:[1,1,1]
	v_pk_fma_f32 v[10:11], v[118:119], s[30:31], v[10:11] op_sel:[1,0,0] op_sel_hi:[1,1,1]
	v_readlane_b32 s22, v180, 41
	v_readlane_b32 s23, v181, 41
	v_readlane_b32 s24, v182, 41
	v_readlane_b32 s25, v183, 41
	v_readlane_b32 s26, v184, 41
	v_readlane_b32 s27, v185, 41
	v_readlane_b32 s30, v186, 41
	v_readlane_b32 s31, v187, 41
	s_waitcnt vmcnt(23)
	v_pk_fma_f32 v[16:17], v[120:121], s[6:7], v[16:17] op_sel:[1,0,0] op_sel_hi:[1,1,1]
	v_pk_fma_f32 v[14:15], v[120:121], s[8:9], v[14:15] op_sel:[1,0,0] op_sel_hi:[1,1,1]
	v_pk_fma_f32 v[12:13], v[120:121], s[10:11], v[12:13] op_sel:[1,0,0] op_sel_hi:[1,1,1]
	v_pk_fma_f32 v[10:11], v[120:121], s[12:13], v[10:11] op_sel:[1,0,0] op_sel_hi:[1,1,1]
	v_readlane_b32 s6, v180, 42
	v_readlane_b32 s7, v181, 42
	v_readlane_b32 s8, v182, 42
	v_readlane_b32 s9, v183, 42
	v_readlane_b32 s10, v184, 42
	v_readlane_b32 s11, v185, 42
	v_readlane_b32 s12, v186, 42
	v_readlane_b32 s13, v187, 42
	s_waitcnt vmcnt(22)
	v_pk_fma_f32 v[16:17], v[122:123], s[22:23], v[16:17] op_sel:[1,0,0] op_sel_hi:[1,1,1]
	v_pk_fma_f32 v[14:15], v[122:123], s[24:25], v[14:15] op_sel:[1,0,0] op_sel_hi:[1,1,1]
	v_pk_fma_f32 v[12:13], v[122:123], s[26:27], v[12:13] op_sel:[1,0,0] op_sel_hi:[1,1,1]
	v_pk_fma_f32 v[10:11], v[122:123], s[30:31], v[10:11] op_sel:[1,0,0] op_sel_hi:[1,1,1]
	v_readlane_b32 s22, v180, 43
	v_readlane_b32 s23, v181, 43
	v_readlane_b32 s24, v182, 43
	v_readlane_b32 s25, v183, 43
	v_readlane_b32 s26, v184, 43
	v_readlane_b32 s27, v185, 43
	v_readlane_b32 s30, v186, 43
	v_readlane_b32 s31, v187, 43
	s_waitcnt vmcnt(21)
	v_pk_fma_f32 v[16:17], v[124:125], s[6:7], v[16:17] op_sel:[1,0,0] op_sel_hi:[1,1,1]
	v_pk_fma_f32 v[14:15], v[124:125], s[8:9], v[14:15] op_sel:[1,0,0] op_sel_hi:[1,1,1]
	v_pk_fma_f32 v[12:13], v[124:125], s[10:11], v[12:13] op_sel:[1,0,0] op_sel_hi:[1,1,1]
	v_pk_fma_f32 v[10:11], v[124:125], s[12:13], v[10:11] op_sel:[1,0,0] op_sel_hi:[1,1,1]
	v_readlane_b32 s6, v180, 44
	v_readlane_b32 s7, v181, 44
	v_readlane_b32 s8, v182, 44
	v_readlane_b32 s9, v183, 44
	v_readlane_b32 s10, v184, 44
	v_readlane_b32 s11, v185, 44
	v_readlane_b32 s12, v186, 44
	v_readlane_b32 s13, v187, 44
	s_waitcnt vmcnt(20)
	v_pk_fma_f32 v[16:17], v[126:127], s[22:23], v[16:17] op_sel:[1,0,0] op_sel_hi:[1,1,1]
	v_pk_fma_f32 v[14:15], v[126:127], s[24:25], v[14:15] op_sel:[1,0,0] op_sel_hi:[1,1,1]
	v_pk_fma_f32 v[12:13], v[126:127], s[26:27], v[12:13] op_sel:[1,0,0] op_sel_hi:[1,1,1]
	v_pk_fma_f32 v[10:11], v[126:127], s[30:31], v[10:11] op_sel:[1,0,0] op_sel_hi:[1,1,1]
	v_readlane_b32 s22, v180, 45
	v_readlane_b32 s23, v181, 45
	v_readlane_b32 s24, v182, 45
	v_readlane_b32 s25, v183, 45
	v_readlane_b32 s26, v184, 45
	v_readlane_b32 s27, v185, 45
	v_readlane_b32 s30, v186, 45
	v_readlane_b32 s31, v187, 45
	s_waitcnt vmcnt(19)
	v_pk_fma_f32 v[16:17], v[128:129], s[6:7], v[16:17] op_sel:[1,0,0] op_sel_hi:[1,1,1]
	v_pk_fma_f32 v[14:15], v[128:129], s[8:9], v[14:15] op_sel:[1,0,0] op_sel_hi:[1,1,1]
	v_pk_fma_f32 v[12:13], v[128:129], s[10:11], v[12:13] op_sel:[1,0,0] op_sel_hi:[1,1,1]
	v_pk_fma_f32 v[10:11], v[128:129], s[12:13], v[10:11] op_sel:[1,0,0] op_sel_hi:[1,1,1]
	v_readlane_b32 s6, v180, 46
	v_readlane_b32 s7, v181, 46
	v_readlane_b32 s8, v182, 46
	v_readlane_b32 s9, v183, 46
	v_readlane_b32 s10, v184, 46
	v_readlane_b32 s11, v185, 46
	v_readlane_b32 s12, v186, 46
	v_readlane_b32 s13, v187, 46
	s_waitcnt vmcnt(18)
	v_pk_fma_f32 v[16:17], v[130:131], s[22:23], v[16:17] op_sel:[1,0,0] op_sel_hi:[1,1,1]
	v_pk_fma_f32 v[14:15], v[130:131], s[24:25], v[14:15] op_sel:[1,0,0] op_sel_hi:[1,1,1]
	v_pk_fma_f32 v[12:13], v[130:131], s[26:27], v[12:13] op_sel:[1,0,0] op_sel_hi:[1,1,1]
	v_pk_fma_f32 v[10:11], v[130:131], s[30:31], v[10:11] op_sel:[1,0,0] op_sel_hi:[1,1,1]
	v_readlane_b32 s22, v180, 47
	v_readlane_b32 s23, v181, 47
	v_readlane_b32 s24, v182, 47
	v_readlane_b32 s25, v183, 47
	v_readlane_b32 s26, v184, 47
	v_readlane_b32 s27, v185, 47
	v_readlane_b32 s30, v186, 47
	v_readlane_b32 s31, v187, 47
	s_waitcnt vmcnt(17)
	v_pk_fma_f32 v[16:17], v[132:133], s[6:7], v[16:17] op_sel:[1,0,0] op_sel_hi:[1,1,1]
	v_pk_fma_f32 v[14:15], v[132:133], s[8:9], v[14:15] op_sel:[1,0,0] op_sel_hi:[1,1,1]
	v_pk_fma_f32 v[12:13], v[132:133], s[10:11], v[12:13] op_sel:[1,0,0] op_sel_hi:[1,1,1]
	v_pk_fma_f32 v[10:11], v[132:133], s[12:13], v[10:11] op_sel:[1,0,0] op_sel_hi:[1,1,1]
	v_readlane_b32 s6, v180, 48
	v_readlane_b32 s7, v181, 48
	v_readlane_b32 s8, v182, 48
	v_readlane_b32 s9, v183, 48
	v_readlane_b32 s10, v184, 48
	v_readlane_b32 s11, v185, 48
	v_readlane_b32 s12, v186, 48
	v_readlane_b32 s13, v187, 48
	s_waitcnt vmcnt(16)
	v_pk_fma_f32 v[16:17], v[134:135], s[22:23], v[16:17] op_sel:[1,0,0] op_sel_hi:[1,1,1]
	v_pk_fma_f32 v[14:15], v[134:135], s[24:25], v[14:15] op_sel:[1,0,0] op_sel_hi:[1,1,1]
	v_pk_fma_f32 v[12:13], v[134:135], s[26:27], v[12:13] op_sel:[1,0,0] op_sel_hi:[1,1,1]
	v_pk_fma_f32 v[10:11], v[134:135], s[30:31], v[10:11] op_sel:[1,0,0] op_sel_hi:[1,1,1]
	v_readlane_b32 s22, v180, 49
	v_readlane_b32 s23, v181, 49
	v_readlane_b32 s24, v182, 49
	v_readlane_b32 s25, v183, 49
	v_readlane_b32 s26, v184, 49
	v_readlane_b32 s27, v185, 49
	v_readlane_b32 s30, v186, 49
	v_readlane_b32 s31, v187, 49
	s_waitcnt vmcnt(15)
	v_pk_fma_f32 v[16:17], v[136:137], s[6:7], v[16:17] op_sel:[1,0,0] op_sel_hi:[1,1,1]
	v_pk_fma_f32 v[14:15], v[136:137], s[8:9], v[14:15] op_sel:[1,0,0] op_sel_hi:[1,1,1]
	v_pk_fma_f32 v[12:13], v[136:137], s[10:11], v[12:13] op_sel:[1,0,0] op_sel_hi:[1,1,1]
	v_pk_fma_f32 v[10:11], v[136:137], s[12:13], v[10:11] op_sel:[1,0,0] op_sel_hi:[1,1,1]
	v_readlane_b32 s6, v180, 50
	v_readlane_b32 s7, v181, 50
	v_readlane_b32 s8, v182, 50
	v_readlane_b32 s9, v183, 50
	v_readlane_b32 s10, v184, 50
	v_readlane_b32 s11, v185, 50
	v_readlane_b32 s12, v186, 50
	v_readlane_b32 s13, v187, 50
	s_waitcnt vmcnt(14)
	v_pk_fma_f32 v[16:17], v[138:139], s[22:23], v[16:17] op_sel:[1,0,0] op_sel_hi:[1,1,1]
	v_pk_fma_f32 v[14:15], v[138:139], s[24:25], v[14:15] op_sel:[1,0,0] op_sel_hi:[1,1,1]
	v_pk_fma_f32 v[12:13], v[138:139], s[26:27], v[12:13] op_sel:[1,0,0] op_sel_hi:[1,1,1]
	v_pk_fma_f32 v[10:11], v[138:139], s[30:31], v[10:11] op_sel:[1,0,0] op_sel_hi:[1,1,1]
	v_readlane_b32 s22, v180, 51
	v_readlane_b32 s23, v181, 51
	v_readlane_b32 s24, v182, 51
	v_readlane_b32 s25, v183, 51
	v_readlane_b32 s26, v184, 51
	v_readlane_b32 s27, v185, 51
	v_readlane_b32 s30, v186, 51
	v_readlane_b32 s31, v187, 51
	s_waitcnt vmcnt(13)
	v_pk_fma_f32 v[16:17], v[140:141], s[6:7], v[16:17] op_sel:[1,0,0] op_sel_hi:[1,1,1]
	v_pk_fma_f32 v[14:15], v[140:141], s[8:9], v[14:15] op_sel:[1,0,0] op_sel_hi:[1,1,1]
	v_pk_fma_f32 v[12:13], v[140:141], s[10:11], v[12:13] op_sel:[1,0,0] op_sel_hi:[1,1,1]
	v_pk_fma_f32 v[10:11], v[140:141], s[12:13], v[10:11] op_sel:[1,0,0] op_sel_hi:[1,1,1]
	v_readlane_b32 s6, v180, 52
	v_readlane_b32 s7, v181, 52
	v_readlane_b32 s8, v182, 52
	v_readlane_b32 s9, v183, 52
	v_readlane_b32 s10, v184, 52
	v_readlane_b32 s11, v185, 52
	v_readlane_b32 s12, v186, 52
	v_readlane_b32 s13, v187, 52
	s_waitcnt vmcnt(12)
	v_pk_fma_f32 v[16:17], v[142:143], s[22:23], v[16:17] op_sel:[1,0,0] op_sel_hi:[1,1,1]
	v_pk_fma_f32 v[14:15], v[142:143], s[24:25], v[14:15] op_sel:[1,0,0] op_sel_hi:[1,1,1]
	v_pk_fma_f32 v[12:13], v[142:143], s[26:27], v[12:13] op_sel:[1,0,0] op_sel_hi:[1,1,1]
	v_pk_fma_f32 v[10:11], v[142:143], s[30:31], v[10:11] op_sel:[1,0,0] op_sel_hi:[1,1,1]
	v_readlane_b32 s22, v180, 53
	v_readlane_b32 s23, v181, 53
	v_readlane_b32 s24, v182, 53
	v_readlane_b32 s25, v183, 53
	v_readlane_b32 s26, v184, 53
	v_readlane_b32 s27, v185, 53
	v_readlane_b32 s30, v186, 53
	v_readlane_b32 s31, v187, 53
	s_waitcnt vmcnt(11)
	v_pk_fma_f32 v[16:17], v[144:145], s[6:7], v[16:17] op_sel:[1,0,0] op_sel_hi:[1,1,1]
	v_pk_fma_f32 v[14:15], v[144:145], s[8:9], v[14:15] op_sel:[1,0,0] op_sel_hi:[1,1,1]
	v_pk_fma_f32 v[12:13], v[144:145], s[10:11], v[12:13] op_sel:[1,0,0] op_sel_hi:[1,1,1]
	v_pk_fma_f32 v[10:11], v[144:145], s[12:13], v[10:11] op_sel:[1,0,0] op_sel_hi:[1,1,1]
	v_readlane_b32 s6, v180, 54
	v_readlane_b32 s7, v181, 54
	v_readlane_b32 s8, v182, 54
	v_readlane_b32 s9, v183, 54
	v_readlane_b32 s10, v184, 54
	v_readlane_b32 s11, v185, 54
	v_readlane_b32 s12, v186, 54
	v_readlane_b32 s13, v187, 54
	s_waitcnt vmcnt(10)
	v_pk_fma_f32 v[16:17], v[146:147], s[22:23], v[16:17] op_sel:[1,0,0] op_sel_hi:[1,1,1]
	v_pk_fma_f32 v[14:15], v[146:147], s[24:25], v[14:15] op_sel:[1,0,0] op_sel_hi:[1,1,1]
	v_pk_fma_f32 v[12:13], v[146:147], s[26:27], v[12:13] op_sel:[1,0,0] op_sel_hi:[1,1,1]
	v_pk_fma_f32 v[10:11], v[146:147], s[30:31], v[10:11] op_sel:[1,0,0] op_sel_hi:[1,1,1]
	v_readlane_b32 s22, v180, 55
	v_readlane_b32 s23, v181, 55
	v_readlane_b32 s24, v182, 55
	v_readlane_b32 s25, v183, 55
	v_readlane_b32 s26, v184, 55
	v_readlane_b32 s27, v185, 55
	v_readlane_b32 s30, v186, 55
	v_readlane_b32 s31, v187, 55
	s_waitcnt vmcnt(9)
	v_pk_fma_f32 v[16:17], v[148:149], s[6:7], v[16:17] op_sel:[1,0,0] op_sel_hi:[1,1,1]
	v_pk_fma_f32 v[14:15], v[148:149], s[8:9], v[14:15] op_sel:[1,0,0] op_sel_hi:[1,1,1]
	v_pk_fma_f32 v[12:13], v[148:149], s[10:11], v[12:13] op_sel:[1,0,0] op_sel_hi:[1,1,1]
	v_pk_fma_f32 v[10:11], v[148:149], s[12:13], v[10:11] op_sel:[1,0,0] op_sel_hi:[1,1,1]
	v_readlane_b32 s6, v180, 56
	v_readlane_b32 s7, v181, 56
	v_readlane_b32 s8, v182, 56
	v_readlane_b32 s9, v183, 56
	v_readlane_b32 s10, v184, 56
	v_readlane_b32 s11, v185, 56
	v_readlane_b32 s12, v186, 56
	v_readlane_b32 s13, v187, 56
	s_waitcnt vmcnt(8)
	v_pk_fma_f32 v[16:17], v[150:151], s[22:23], v[16:17] op_sel:[1,0,0] op_sel_hi:[1,1,1]
	v_pk_fma_f32 v[14:15], v[150:151], s[24:25], v[14:15] op_sel:[1,0,0] op_sel_hi:[1,1,1]
	v_pk_fma_f32 v[12:13], v[150:151], s[26:27], v[12:13] op_sel:[1,0,0] op_sel_hi:[1,1,1]
	v_pk_fma_f32 v[10:11], v[150:151], s[30:31], v[10:11] op_sel:[1,0,0] op_sel_hi:[1,1,1]
	v_readlane_b32 s22, v180, 57
	v_readlane_b32 s23, v181, 57
	v_readlane_b32 s24, v182, 57
	v_readlane_b32 s25, v183, 57
	v_readlane_b32 s26, v184, 57
	v_readlane_b32 s27, v185, 57
	v_readlane_b32 s30, v186, 57
	v_readlane_b32 s31, v187, 57
	s_waitcnt vmcnt(7)
	v_pk_fma_f32 v[16:17], v[152:153], s[6:7], v[16:17] op_sel:[1,0,0] op_sel_hi:[1,1,1]
	v_pk_fma_f32 v[14:15], v[152:153], s[8:9], v[14:15] op_sel:[1,0,0] op_sel_hi:[1,1,1]
	v_pk_fma_f32 v[12:13], v[152:153], s[10:11], v[12:13] op_sel:[1,0,0] op_sel_hi:[1,1,1]
	v_pk_fma_f32 v[10:11], v[152:153], s[12:13], v[10:11] op_sel:[1,0,0] op_sel_hi:[1,1,1]
	v_readlane_b32 s6, v180, 58
	v_readlane_b32 s7, v181, 58
	v_readlane_b32 s8, v182, 58
	v_readlane_b32 s9, v183, 58
	v_readlane_b32 s10, v184, 58
	v_readlane_b32 s11, v185, 58
	v_readlane_b32 s12, v186, 58
	v_readlane_b32 s13, v187, 58
	s_waitcnt vmcnt(6)
	v_pk_fma_f32 v[16:17], v[154:155], s[22:23], v[16:17] op_sel:[1,0,0] op_sel_hi:[1,1,1]
	v_pk_fma_f32 v[14:15], v[154:155], s[24:25], v[14:15] op_sel:[1,0,0] op_sel_hi:[1,1,1]
	v_pk_fma_f32 v[12:13], v[154:155], s[26:27], v[12:13] op_sel:[1,0,0] op_sel_hi:[1,1,1]
	v_pk_fma_f32 v[10:11], v[154:155], s[30:31], v[10:11] op_sel:[1,0,0] op_sel_hi:[1,1,1]
	v_readlane_b32 s22, v180, 59
	v_readlane_b32 s23, v181, 59
	v_readlane_b32 s24, v182, 59
	v_readlane_b32 s25, v183, 59
	v_readlane_b32 s26, v184, 59
	v_readlane_b32 s27, v185, 59
	v_readlane_b32 s30, v186, 59
	v_readlane_b32 s31, v187, 59
	s_waitcnt vmcnt(5)
	v_pk_fma_f32 v[16:17], v[156:157], s[6:7], v[16:17] op_sel:[1,0,0] op_sel_hi:[1,1,1]
	v_pk_fma_f32 v[14:15], v[156:157], s[8:9], v[14:15] op_sel:[1,0,0] op_sel_hi:[1,1,1]
	v_pk_fma_f32 v[12:13], v[156:157], s[10:11], v[12:13] op_sel:[1,0,0] op_sel_hi:[1,1,1]
	v_pk_fma_f32 v[10:11], v[156:157], s[12:13], v[10:11] op_sel:[1,0,0] op_sel_hi:[1,1,1]
	v_readlane_b32 s6, v180, 60
	v_readlane_b32 s7, v181, 60
	v_readlane_b32 s8, v182, 60
	v_readlane_b32 s9, v183, 60
	v_readlane_b32 s10, v184, 60
	v_readlane_b32 s11, v185, 60
	v_readlane_b32 s12, v186, 60
	v_readlane_b32 s13, v187, 60
	s_waitcnt vmcnt(4)
	v_pk_fma_f32 v[16:17], v[158:159], s[22:23], v[16:17] op_sel:[1,0,0] op_sel_hi:[1,1,1]
	v_pk_fma_f32 v[14:15], v[158:159], s[24:25], v[14:15] op_sel:[1,0,0] op_sel_hi:[1,1,1]
	v_pk_fma_f32 v[12:13], v[158:159], s[26:27], v[12:13] op_sel:[1,0,0] op_sel_hi:[1,1,1]
	v_pk_fma_f32 v[10:11], v[158:159], s[30:31], v[10:11] op_sel:[1,0,0] op_sel_hi:[1,1,1]
	v_readlane_b32 s22, v180, 61
	v_readlane_b32 s23, v181, 61
	v_readlane_b32 s24, v182, 61
	v_readlane_b32 s25, v183, 61
	v_readlane_b32 s26, v184, 61
	v_readlane_b32 s27, v185, 61
	v_readlane_b32 s30, v186, 61
	v_readlane_b32 s31, v187, 61
	s_waitcnt vmcnt(3)
	v_pk_fma_f32 v[16:17], v[164:165], s[6:7], v[16:17] op_sel:[1,0,0] op_sel_hi:[1,1,1]
	v_pk_fma_f32 v[14:15], v[164:165], s[8:9], v[14:15] op_sel:[1,0,0] op_sel_hi:[1,1,1]
	v_pk_fma_f32 v[12:13], v[164:165], s[10:11], v[12:13] op_sel:[1,0,0] op_sel_hi:[1,1,1]
	v_pk_fma_f32 v[10:11], v[164:165], s[12:13], v[10:11] op_sel:[1,0,0] op_sel_hi:[1,1,1]
	v_readlane_b32 s6, v180, 62
	v_readlane_b32 s7, v181, 62
	v_readlane_b32 s8, v182, 62
	v_readlane_b32 s9, v183, 62
	v_readlane_b32 s10, v184, 62
	v_readlane_b32 s11, v185, 62
	v_readlane_b32 s12, v186, 62
	v_readlane_b32 s13, v187, 62
	s_waitcnt vmcnt(2)
	v_pk_fma_f32 v[16:17], v[166:167], s[22:23], v[16:17] op_sel:[1,0,0] op_sel_hi:[1,1,1]
	v_pk_fma_f32 v[14:15], v[166:167], s[24:25], v[14:15] op_sel:[1,0,0] op_sel_hi:[1,1,1]
	v_pk_fma_f32 v[12:13], v[166:167], s[26:27], v[12:13] op_sel:[1,0,0] op_sel_hi:[1,1,1]
	v_pk_fma_f32 v[10:11], v[166:167], s[30:31], v[10:11] op_sel:[1,0,0] op_sel_hi:[1,1,1]
	v_readlane_b32 s22, v180, 63
	v_readlane_b32 s23, v181, 63
	v_readlane_b32 s24, v182, 63
	v_readlane_b32 s25, v183, 63
	v_readlane_b32 s26, v184, 63
	v_readlane_b32 s27, v185, 63
	v_readlane_b32 s30, v186, 63
	v_readlane_b32 s31, v187, 63
	s_waitcnt vmcnt(1)
	v_pk_fma_f32 v[16:17], v[168:169], s[6:7], v[16:17] op_sel:[1,0,0] op_sel_hi:[1,1,1]
	v_pk_fma_f32 v[14:15], v[168:169], s[8:9], v[14:15] op_sel:[1,0,0] op_sel_hi:[1,1,1]
	v_pk_fma_f32 v[12:13], v[168:169], s[10:11], v[12:13] op_sel:[1,0,0] op_sel_hi:[1,1,1]
	v_pk_fma_f32 v[10:11], v[168:169], s[12:13], v[10:11] op_sel:[1,0,0] op_sel_hi:[1,1,1]
	s_waitcnt vmcnt(0)
	v_pk_fma_f32 v[16:17], v[170:171], s[22:23], v[16:17] op_sel:[1,0,0] op_sel_hi:[1,1,1]
	v_pk_fma_f32 v[14:15], v[170:171], s[24:25], v[14:15] op_sel:[1,0,0] op_sel_hi:[1,1,1]
	v_pk_fma_f32 v[12:13], v[170:171], s[26:27], v[12:13] op_sel:[1,0,0] op_sel_hi:[1,1,1]
	v_pk_fma_f32 v[10:11], v[170:171], s[30:31], v[10:11] op_sel:[1,0,0] op_sel_hi:[1,1,1]
	s_addk_i32 s2, 0x800
	s_lshl_b32 s0, s2, 6
	s_and_b32 s0, s0, 0x7c0
	v_or_b32_e32 v3, s0, v2
	v_readlane_b32 s0, v251, 24
	v_lshlrev_b32_e32 v4, 2, v3
	v_mov_b32_e32 v5, v1
	v_readlane_b32 s1, v251, 25
	s_lshl_b32 s90, s4, 13
	s_nop 0
	v_lshl_add_u64 v[4:5], s[0:1], 0, v[4:5]
	v_lshl_add_u64 v[4:5], v[4:5], 0, s[90:91]
	v_add_co_u32_e32 v6, vcc, 0x2000, v4
	global_atomic_add_f32 v[4:5], v16, off
	s_nop 0
	v_addc_co_u32_e32 v7, vcc, 0, v5, vcc
	global_atomic_add_f32 v[6:7], v17, off
	v_add_co_u32_e32 v6, vcc, 0x4000, v4
	v_readlane_b32 s0, v254, 6
	s_nop 0
	v_addc_co_u32_e32 v7, vcc, 0, v5, vcc
	global_atomic_add_f32 v[6:7], v14, off
	v_add_co_u32_e32 v6, vcc, 0x6000, v4
	v_readlane_b32 s1, v254, 7
	s_nop 0
	v_addc_co_u32_e32 v7, vcc, 0, v5, vcc
	global_atomic_add_f32 v[6:7], v15, off
	v_add_co_u32_e32 v6, vcc, 0x8000, v4
	s_add_i32 s2, s2, s0
	s_nop 0
	v_addc_co_u32_e32 v7, vcc, 0, v5, vcc
	global_atomic_add_f32 v[6:7], v12, off
	v_add_co_u32_e32 v6, vcc, 0xa000, v4
	v_readlane_b32 s0, v254, 2
	s_nop 0
	v_addc_co_u32_e32 v7, vcc, 0, v5, vcc
	global_atomic_add_f32 v[6:7], v13, off
	v_add_co_u32_e32 v6, vcc, 0xc000, v4
	s_add_i32 s3, s3, s0
	s_nop 0
	v_addc_co_u32_e32 v7, vcc, 0, v5, vcc
	v_add_co_u32_e32 v4, vcc, 0xe000, v4
	global_atomic_add_f32 v[6:7], v10, off
	s_nop 0
	v_addc_co_u32_e32 v5, vcc, 0, v5, vcc
	global_atomic_add_f32 v[4:5], v11, off
	s_cmpk_gt_i32 s2, 0xfff
	v_readlane_b32 s1, v254, 3
	s_cbranch_scc0 .LBB0_830
